# stack5 with snake ordering of the accumulator pairs: every consecutive MFMA pair shares one fragment register pair (src0 held for 4 pairs, src1 order reversed on the next src0)
# speedup vs baseline: 1.0116x; 1.0023x over previous
; #define PG8_STAGE(bufoff, gbase, voff) do { _Pragma("unroll") for (int _i = 0; _i < 2; ++_i) \
;         __builtin_amdgcn_global_load_lds((const unsigned*)((const char*)(gbase) + (voff)[_i]), (LAS unsigned*)(lds + (bufoff) + ldsw + _i * 8192), 16, 0, 0); } while (0)
; #define PG8_LDA(dst, b, h) do { _Pragma("unroll") for (int m = 0; m < 4; ++m) _Pragma("unroll") for (int k = 0; k < 2; ++k) dst[m][k] = *(const LAS bf16x8*)(lds + PG8_SA(b, h) + aoff + m * 2048 + k * 1024); } while (0)
; #define PG8_LDB(dst, b, h) do { _Pragma("unroll") for (int n = 0; n < 2; ++n) _Pragma("unroll") for (int k = 0; k < 2; ++k) dst[n][k] = *(const LAS bf16x8*)(lds + PG8_SB(b, h) + boff + n * 2048 + k * 1024); } while (0)
; #define PG8_MMA(ai, bj, At, Bt) do { __builtin_amdgcn_s_setprio(1); _Pragma("unroll") for (int m = 0; m < 4; ++m) _Pragma("unroll") for (int n = 0; n < 2; ++n) _Pragma("unroll") for (int k = 0; k < 2; ++k) \
;         acc[ai][bj][m][n] = __builtin_amdgcn_mfma_f32_16x16x32_bf16(Bt[n][k], At[m][k], acc[ai][bj][m][n], 0, 0, 0); __builtin_amdgcn_s_setprio(0); } while (0)
; #define PG8_WAIT_V(n) asm volatile("s_waitcnt vmcnt(" #n ")" ::: "memory")
; #define PG8_WAIT_L(n) asm volatile("s_waitcnt lgkmcnt(" #n ")" ::: "memory")
; #define PG8_BAR __builtin_amdgcn_s_barrier()
; #define PG8_SCHED __builtin_amdgcn_sched_barrier(0)
; template <class Epi>
; DI void gemm_phase(LAS unsigned char* lds, const Gemm g, const StaticOrder& S, const Epi& E) {
;     ...
;             const bool last = (t == nt - 2);
;             const char* a1 = cA + (size_t)(t + 1) * kstep;
;             const char* a2 = last ? nA : cA + (size_t)(t + 2) * kstep; const char* b2 = last ? nB : cB + (size_t)(t + 2) * kstep;
;             const char* a3 = a2 + kstep; const char* b3 = b2 + kstep;
;             PG8_LDB(B0, 0, 0); PG8_LDB(B1, 0, 1); PG8_SCHED; PG8_LDA(At, 0, 0); PG8_STAGE(PG8_SA(1, 1), a1 + hstepA, voffA);
;             PG8_WAIT_V(8); PG8_WAIT_L(0); PG8_BAR; PG8_MMA(0, 0, At, B0); PG8_MMA(0, 1, At, B1); PG8_BAR; PG8_SCHED;
;             PG8_LDA(At, 0, 1); PG8_STAGE(PG8_SB(0, 0), b2, voffB); PG8_STAGE(PG8_SB(0, 1), b2 + hstepB, voffB); PG8_STAGE(PG8_SA(0, 0), a2, voffA);
;             PG8_WAIT_V(8); PG8_WAIT_L(0); PG8_BAR; PG8_MMA(1, 0, At, B0); PG8_MMA(1, 1, At, B1); PG8_BAR; PG8_SCHED;
.LBB0_161:
	ds_read_b128 v[154:157], v150
	ds_read_b128 v[158:161], v150 offset:1024
	ds_read_b128 v[162:165], v150 offset:2048
	ds_read_b128 v[166:169], v150 offset:3072
	ds_read_b128 v[170:173], v151
	ds_read_b128 v[174:177], v151 offset:1024
	ds_read_b128 v[182:185], v151 offset:2048
	ds_read_b128 v[186:189], v151 offset:3072
	s_add_i32 s64, s34, 2
	s_add_u32 s35, s30, 0xfff00080
	s_addc_u32 s38, s31, -1
	s_cmp_eq_u32 s53, s34
	s_cselect_b32 s34, s29, s62
	s_cselect_b32 s39, s19, s38
	s_cselect_b32 s38, s21, s35
	s_cselect_b32 s35, s27, s63
	v_lshl_add_u64 v[146:147], s[30:31], 0, v[138:139]
	s_add_i32 m0, s41, 0xc000
	ds_read_b128 v[190:193], v152
	ds_read_b128 v[194:197], v152 offset:1024
	ds_read_b128 v[198:201], v152 offset:2048
	ds_read_b128 v[202:205], v152 offset:3072
	ds_read_b128 v[206:209], v152 offset:4096
	ds_read_b128 v[210:213], v152 offset:5120
	ds_read_b128 v[214:217], v152 offset:6144
	ds_read_b128 v[218:221], v152 offset:7168
	global_load_lds_dwordx4 v[146:147], off
	v_lshl_add_u64 v[146:147], s[30:31], 0, v[140:141]
	s_add_i32 m0, s41, 0xe000
	s_nop 0
	global_load_lds_dwordx4 v[146:147], off
	s_waitcnt vmcnt(8)
	s_waitcnt lgkmcnt(0)
	s_setprio 1
	s_barrier
	v_mfma_f32_16x16x32_bf16 v[124:127], v[154:157], v[190:193], v[124:127]
	v_mfma_f32_16x16x32_bf16 v[124:127], v[158:161], v[194:197], v[124:127]
	v_mfma_f32_16x16x32_bf16 v[108:111], v[154:157], v[198:201], v[108:111]
	v_mfma_f32_16x16x32_bf16 v[108:111], v[158:161], v[202:205], v[108:111]
	v_mfma_f32_16x16x32_bf16 v[92:95], v[154:157], v[206:209], v[92:95]
	v_mfma_f32_16x16x32_bf16 v[92:95], v[158:161], v[210:213], v[92:95]
	v_mfma_f32_16x16x32_bf16 v[76:79], v[154:157], v[214:217], v[76:79]
	v_mfma_f32_16x16x32_bf16 v[76:79], v[158:161], v[218:221], v[76:79]
	v_mfma_f32_16x16x32_bf16 v[72:75], v[162:165], v[214:217], v[72:75]
	v_mfma_f32_16x16x32_bf16 v[72:75], v[166:169], v[218:221], v[72:75]
	v_mfma_f32_16x16x32_bf16 v[88:91], v[162:165], v[206:209], v[88:91]
	v_mfma_f32_16x16x32_bf16 v[88:91], v[166:169], v[210:213], v[88:91]
	v_mfma_f32_16x16x32_bf16 v[104:107], v[162:165], v[198:201], v[104:107]
	v_mfma_f32_16x16x32_bf16 v[104:107], v[166:169], v[202:205], v[104:107]
	v_mfma_f32_16x16x32_bf16 v[120:123], v[162:165], v[190:193], v[120:123]
	v_mfma_f32_16x16x32_bf16 v[120:123], v[166:169], v[194:197], v[120:123]
	s_setprio 0
	s_setprio 1
	v_mfma_f32_16x16x32_bf16 v[116:119], v[170:173], v[190:193], v[116:119]
	v_mfma_f32_16x16x32_bf16 v[116:119], v[174:177], v[194:197], v[116:119]
	v_mfma_f32_16x16x32_bf16 v[100:103], v[170:173], v[198:201], v[100:103]
	v_mfma_f32_16x16x32_bf16 v[100:103], v[174:177], v[202:205], v[100:103]
	v_mfma_f32_16x16x32_bf16 v[84:87], v[170:173], v[206:209], v[84:87]
	v_mfma_f32_16x16x32_bf16 v[84:87], v[174:177], v[210:213], v[84:87]
	v_mfma_f32_16x16x32_bf16 v[68:71], v[170:173], v[214:217], v[68:71]
	v_mfma_f32_16x16x32_bf16 v[68:71], v[174:177], v[218:221], v[68:71]
	v_mfma_f32_16x16x32_bf16 v[64:67], v[182:185], v[214:217], v[64:67]
	v_mfma_f32_16x16x32_bf16 v[64:67], v[186:189], v[218:221], v[64:67]
	v_mfma_f32_16x16x32_bf16 v[80:83], v[182:185], v[206:209], v[80:83]
	v_mfma_f32_16x16x32_bf16 v[80:83], v[186:189], v[210:213], v[80:83]
	v_mfma_f32_16x16x32_bf16 v[96:99], v[182:185], v[198:201], v[96:99]
	v_mfma_f32_16x16x32_bf16 v[96:99], v[186:189], v[202:205], v[96:99]
	v_mfma_f32_16x16x32_bf16 v[112:115], v[182:185], v[190:193], v[112:115]
	v_mfma_f32_16x16x32_bf16 v[112:115], v[186:189], v[194:197], v[112:115]
	s_setprio 0
	s_barrier
	s_add_i32 s65, s58, s40
	v_lshl_add_u64 v[146:147], s[34:35], 0, v[130:131]
	s_mov_b32 m0, s65
	ds_read_b128 v[190:193], v152 offset:16384
	ds_read_b128 v[194:197], v152 offset:17408
	ds_read_b128 v[198:201], v152 offset:18432
	ds_read_b128 v[202:205], v152 offset:19456
	ds_read_b128 v[206:209], v152 offset:20480
	ds_read_b128 v[210:213], v152 offset:21504
	ds_read_b128 v[214:217], v152 offset:22528
	ds_read_b128 v[218:221], v152 offset:23552
	global_load_lds_dwordx4 v[146:147], off
	s_add_i32 m0, s65, 0x2000
	s_add_u32 s66, s34, 0x100000
	v_lshl_add_u64 v[178:179], s[34:35], 0, v[134:135]
	s_addc_u32 s67, s35, 0
	s_add_i32 s65, s59, s40
	global_load_lds_dwordx4 v[178:179], off
	v_lshl_add_u64 v[222:223], s[66:67], 0, v[130:131]
	s_mov_b32 m0, s65
	v_lshl_add_u64 v[224:225], s[38:39], 0, v[132:133]
	global_load_lds_dwordx4 v[222:223], off
	v_lshl_add_u64 v[222:223], s[66:67], 0, v[134:135]
	s_add_i32 m0, s65, 0x2000
	s_nop 0
	global_load_lds_dwordx4 v[222:223], off
	v_lshl_add_u64 v[222:223], s[38:39], 0, v[128:129]
	s_mov_b32 m0, s41
	s_nop 0
	global_load_lds_dwordx4 v[222:223], off
	s_mov_b32 m0, s42
	s_nop 0
	global_load_lds_dwordx4 v[224:225], off
	s_waitcnt vmcnt(8)
	s_waitcnt lgkmcnt(0)
	s_setprio 1
	s_barrier
; #define PG8_STAGE(bufoff, gbase, voff) do { _Pragma("unroll") for (int _i = 0; _i < 2; ++_i) \
;         __builtin_amdgcn_global_load_lds((const unsigned*)((const char*)(gbase) + (voff)[_i]), (LAS unsigned*)(lds + (bufoff) + ldsw + _i * 8192), 16, 0, 0); } while (0)
; #define PG8_LDA(dst, b, h) do { _Pragma("unroll") for (int m = 0; m < 4; ++m) _Pragma("unroll") for (int k = 0; k < 2; ++k) dst[m][k] = *(const LAS bf16x8*)(lds + PG8_SA(b, h) + aoff + m * 2048 + k * 1024); } while (0)
; #define PG8_LDB(dst, b, h) do { _Pragma("unroll") for (int n = 0; n < 2; ++n) _Pragma("unroll") for (int k = 0; k < 2; ++k) dst[n][k] = *(const LAS bf16x8*)(lds + PG8_SB(b, h) + boff + n * 2048 + k * 1024); } while (0)
; #define PG8_MMA(ai, bj, At, Bt) do { __builtin_amdgcn_s_setprio(1); _Pragma("unroll") for (int m = 0; m < 4; ++m) _Pragma("unroll") for (int n = 0; n < 2; ++n) _Pragma("unroll") for (int k = 0; k < 2; ++k) \
;         acc[ai][bj][m][n] = __builtin_amdgcn_mfma_f32_16x16x32_bf16(Bt[n][k], At[m][k], acc[ai][bj][m][n], 0, 0, 0); __builtin_amdgcn_s_setprio(0); } while (0)
; #define PG8_WAIT_V(n) asm volatile("s_waitcnt vmcnt(" #n ")" ::: "memory")
; #define PG8_WAIT_L(n) asm volatile("s_waitcnt lgkmcnt(" #n ")" ::: "memory")
; #define PG8_BAR __builtin_amdgcn_s_barrier()
; #define PG8_SCHED __builtin_amdgcn_sched_barrier(0)
; template <class Epi>
; DI void gemm_phase(LAS unsigned char* lds, const Gemm g, const StaticOrder& S, const Epi& E) {
;     ...
;             PG8_WAIT_V(8); PG8_WAIT_L(0); PG8_BAR; PG8_MMA(1, 0, At, B0); PG8_MMA(1, 1, At, B1); PG8_BAR; PG8_SCHED;
;             PG8_LDB(B0, 1, 0); PG8_LDB(B1, 1, 1); PG8_SCHED; PG8_LDA(At, 1, 0); PG8_STAGE(PG8_SA(0, 1), a2 + hstepA, voffA);
;             PG8_WAIT_V(8); PG8_WAIT_L(0); PG8_BAR; PG8_MMA(0, 0, At, B0); PG8_MMA(0, 1, At, B1); PG8_BAR; PG8_SCHED;
	v_mfma_f32_16x16x32_bf16 v[60:63], v[154:157], v[190:193], v[60:63]
	v_mfma_f32_16x16x32_bf16 v[60:63], v[158:161], v[194:197], v[60:63]
	v_mfma_f32_16x16x32_bf16 v[44:47], v[154:157], v[198:201], v[44:47]
	v_mfma_f32_16x16x32_bf16 v[44:47], v[158:161], v[202:205], v[44:47]
	v_mfma_f32_16x16x32_bf16 v[28:31], v[154:157], v[206:209], v[28:31]
	v_mfma_f32_16x16x32_bf16 v[28:31], v[158:161], v[210:213], v[28:31]
	v_mfma_f32_16x16x32_bf16 v[12:15], v[154:157], v[214:217], v[12:15]
	v_mfma_f32_16x16x32_bf16 v[12:15], v[158:161], v[218:221], v[12:15]
	v_mfma_f32_16x16x32_bf16 v[8:11], v[162:165], v[214:217], v[8:11]
	v_mfma_f32_16x16x32_bf16 v[8:11], v[166:169], v[218:221], v[8:11]
	v_mfma_f32_16x16x32_bf16 v[24:27], v[162:165], v[206:209], v[24:27]
	v_mfma_f32_16x16x32_bf16 v[24:27], v[166:169], v[210:213], v[24:27]
	v_mfma_f32_16x16x32_bf16 v[40:43], v[162:165], v[198:201], v[40:43]
	v_mfma_f32_16x16x32_bf16 v[40:43], v[166:169], v[202:205], v[40:43]
	v_mfma_f32_16x16x32_bf16 v[56:59], v[162:165], v[190:193], v[56:59]
	v_mfma_f32_16x16x32_bf16 v[56:59], v[166:169], v[194:197], v[56:59]
	s_setprio 0
	s_setprio 1
	v_mfma_f32_16x16x32_bf16 v[52:55], v[170:173], v[190:193], v[52:55]
	v_mfma_f32_16x16x32_bf16 v[52:55], v[174:177], v[194:197], v[52:55]
	v_mfma_f32_16x16x32_bf16 v[36:39], v[170:173], v[198:201], v[36:39]
	v_mfma_f32_16x16x32_bf16 v[36:39], v[174:177], v[202:205], v[36:39]
	v_mfma_f32_16x16x32_bf16 v[20:23], v[170:173], v[206:209], v[20:23]
	v_mfma_f32_16x16x32_bf16 v[20:23], v[174:177], v[210:213], v[20:23]
	v_mfma_f32_16x16x32_bf16 v[4:7], v[170:173], v[214:217], v[4:7]
	v_mfma_f32_16x16x32_bf16 v[4:7], v[174:177], v[218:221], v[4:7]
	v_mfma_f32_16x16x32_bf16 v[0:3], v[182:185], v[214:217], v[0:3]
	v_mfma_f32_16x16x32_bf16 v[0:3], v[186:189], v[218:221], v[0:3]
	v_mfma_f32_16x16x32_bf16 v[16:19], v[182:185], v[206:209], v[16:19]
	v_mfma_f32_16x16x32_bf16 v[16:19], v[186:189], v[210:213], v[16:19]
	v_mfma_f32_16x16x32_bf16 v[32:35], v[182:185], v[198:201], v[32:35]
	v_mfma_f32_16x16x32_bf16 v[32:35], v[186:189], v[202:205], v[32:35]
	v_mfma_f32_16x16x32_bf16 v[48:51], v[182:185], v[190:193], v[48:51]
	v_mfma_f32_16x16x32_bf16 v[48:51], v[186:189], v[194:197], v[48:51]
	s_setprio 0
	s_barrier
	s_add_i32 s65, 0, 0x18000
	s_add_i32 s66, 0, 0x1c000
	v_add_u32_e32 v166, s65, v149
	v_add_u32_e32 v181, s66, v149
	ds_read_b128 v[154:157], v166
	ds_read_b128 v[158:161], v166 offset:1024
	ds_read_b128 v[162:165], v166 offset:2048
	ds_read_b128 v[166:169], v166 offset:3072
	ds_read_b128 v[170:173], v181
	ds_read_b128 v[174:177], v181 offset:1024
	ds_read_b128 v[182:185], v181 offset:2048
	ds_read_b128 v[186:189], v181 offset:3072
	s_add_u32 s38, s38, 0x100000
	s_addc_u32 s39, s39, 0
	s_mov_b32 m0, s43
	v_lshl_add_u64 v[226:227], s[38:39], 0, v[128:129]
	ds_read_b128 v[190:193], v152 offset:32768
	ds_read_b128 v[194:197], v152 offset:33792
	ds_read_b128 v[198:201], v152 offset:34816
	ds_read_b128 v[202:205], v152 offset:35840
	ds_read_b128 v[206:209], v152 offset:36864
	ds_read_b128 v[210:213], v152 offset:37888
	ds_read_b128 v[214:217], v152 offset:38912
	ds_read_b128 v[218:221], v152 offset:39936
	global_load_lds_dwordx4 v[226:227], off
	v_lshl_add_u64 v[226:227], s[38:39], 0, v[132:133]
	s_mov_b32 m0, s46
	s_nop 0
	global_load_lds_dwordx4 v[226:227], off
	s_waitcnt vmcnt(8)
	s_waitcnt lgkmcnt(0)
	s_setprio 1
	s_barrier
	v_mfma_f32_16x16x32_bf16 v[124:127], v[154:157], v[190:193], v[124:127]
	v_mfma_f32_16x16x32_bf16 v[124:127], v[158:161], v[194:197], v[124:127]
	v_mfma_f32_16x16x32_bf16 v[108:111], v[154:157], v[198:201], v[108:111]
	v_mfma_f32_16x16x32_bf16 v[108:111], v[158:161], v[202:205], v[108:111]
	v_mfma_f32_16x16x32_bf16 v[92:95], v[154:157], v[206:209], v[92:95]
	v_mfma_f32_16x16x32_bf16 v[92:95], v[158:161], v[210:213], v[92:95]
	v_mfma_f32_16x16x32_bf16 v[76:79], v[154:157], v[214:217], v[76:79]
	v_mfma_f32_16x16x32_bf16 v[76:79], v[158:161], v[218:221], v[76:79]
	v_mfma_f32_16x16x32_bf16 v[72:75], v[162:165], v[214:217], v[72:75]
	v_mfma_f32_16x16x32_bf16 v[72:75], v[166:169], v[218:221], v[72:75]
	v_mfma_f32_16x16x32_bf16 v[88:91], v[162:165], v[206:209], v[88:91]
	v_mfma_f32_16x16x32_bf16 v[88:91], v[166:169], v[210:213], v[88:91]
	v_mfma_f32_16x16x32_bf16 v[104:107], v[162:165], v[198:201], v[104:107]
	v_mfma_f32_16x16x32_bf16 v[104:107], v[166:169], v[202:205], v[104:107]
	v_mfma_f32_16x16x32_bf16 v[120:123], v[162:165], v[190:193], v[120:123]
	v_mfma_f32_16x16x32_bf16 v[120:123], v[166:169], v[194:197], v[120:123]
	s_setprio 0
	s_setprio 1
	v_mfma_f32_16x16x32_bf16 v[116:119], v[170:173], v[190:193], v[116:119]
	v_mfma_f32_16x16x32_bf16 v[116:119], v[174:177], v[194:197], v[116:119]
	v_mfma_f32_16x16x32_bf16 v[100:103], v[170:173], v[198:201], v[100:103]
	v_mfma_f32_16x16x32_bf16 v[100:103], v[174:177], v[202:205], v[100:103]
	v_mfma_f32_16x16x32_bf16 v[84:87], v[170:173], v[206:209], v[84:87]
	v_mfma_f32_16x16x32_bf16 v[84:87], v[174:177], v[210:213], v[84:87]
	v_mfma_f32_16x16x32_bf16 v[68:71], v[170:173], v[214:217], v[68:71]
	v_mfma_f32_16x16x32_bf16 v[68:71], v[174:177], v[218:221], v[68:71]
	v_mfma_f32_16x16x32_bf16 v[64:67], v[182:185], v[214:217], v[64:67]
	v_mfma_f32_16x16x32_bf16 v[64:67], v[186:189], v[218:221], v[64:67]
	v_mfma_f32_16x16x32_bf16 v[80:83], v[182:185], v[206:209], v[80:83]
	v_mfma_f32_16x16x32_bf16 v[80:83], v[186:189], v[210:213], v[80:83]
	v_mfma_f32_16x16x32_bf16 v[96:99], v[182:185], v[198:201], v[96:99]
	v_mfma_f32_16x16x32_bf16 v[96:99], v[186:189], v[202:205], v[96:99]
	v_mfma_f32_16x16x32_bf16 v[112:115], v[182:185], v[190:193], v[112:115]
	v_mfma_f32_16x16x32_bf16 v[112:115], v[186:189], v[194:197], v[112:115]
	s_setprio 0
	s_barrier
; #define PG8_STAGE(bufoff, gbase, voff) do { _Pragma("unroll") for (int _i = 0; _i < 2; ++_i) \
;         __builtin_amdgcn_global_load_lds((const unsigned*)((const char*)(gbase) + (voff)[_i]), (LAS unsigned*)(lds + (bufoff) + ldsw + _i * 8192), 16, 0, 0); } while (0)
; #define PG8_LDA(dst, b, h) do { _Pragma("unroll") for (int m = 0; m < 4; ++m) _Pragma("unroll") for (int k = 0; k < 2; ++k) dst[m][k] = *(const LAS bf16x8*)(lds + PG8_SA(b, h) + aoff + m * 2048 + k * 1024); } while (0)
; #define PG8_MMA(ai, bj, At, Bt) do { __builtin_amdgcn_s_setprio(1); _Pragma("unroll") for (int m = 0; m < 4; ++m) _Pragma("unroll") for (int n = 0; n < 2; ++n) _Pragma("unroll") for (int k = 0; k < 2; ++k) \
;         acc[ai][bj][m][n] = __builtin_amdgcn_mfma_f32_16x16x32_bf16(Bt[n][k], At[m][k], acc[ai][bj][m][n], 0, 0, 0); __builtin_amdgcn_s_setprio(0); } while (0)
; #define PG8_WAIT_V(n) asm volatile("s_waitcnt vmcnt(" #n ")" ::: "memory")
; #define PG8_WAIT_L(n) asm volatile("s_waitcnt lgkmcnt(" #n ")" ::: "memory")
; #define PG8_BAR __builtin_amdgcn_s_barrier()
; #define PG8_SCHED __builtin_amdgcn_sched_barrier(0)
; template <class Epi>
; DI void gemm_phase(LAS unsigned char* lds, const Gemm g, const StaticOrder& S, const Epi& E) {
;     ...
;             PG8_LDA(At, 1, 1); PG8_STAGE(PG8_SB(1, 0), b3, voffB); PG8_STAGE(PG8_SB(1, 1), b3 + hstepB, voffB); PG8_STAGE(PG8_SA(1, 0), a3, voffA);
;             PG8_WAIT_V(8); PG8_WAIT_L(0); PG8_BAR; PG8_MMA(1, 0, At, B0); PG8_MMA(1, 1, At, B1); PG8_BAR; PG8_SCHED;
;         }
	s_add_i32 s38, s65, s40
	v_lshl_add_u64 v[146:147], v[146:147], 0, s[14:15]
	s_mov_b32 m0, s38
	ds_read_b128 v[190:193], v152 offset:49152
	ds_read_b128 v[194:197], v152 offset:50176
	ds_read_b128 v[198:201], v152 offset:51200
	ds_read_b128 v[202:205], v152 offset:52224
	ds_read_b128 v[206:209], v152 offset:53248
	ds_read_b128 v[210:213], v152 offset:54272
	ds_read_b128 v[214:217], v152 offset:55296
	ds_read_b128 v[218:221], v152 offset:56320
	global_load_lds_dwordx4 v[146:147], off
	s_add_i32 m0, s38, 0x2000
	s_add_u32 s34, s34, 0x100080
	v_lshl_add_u64 v[146:147], v[178:179], 0, s[14:15]
	s_addc_u32 s35, s35, 0
	s_add_i32 s38, s66, s40
	global_load_lds_dwordx4 v[146:147], off
	v_lshl_add_u64 v[146:147], s[34:35], 0, v[130:131]
	s_mov_b32 m0, s38
	s_nop 0
	global_load_lds_dwordx4 v[146:147], off
	v_lshl_add_u64 v[146:147], s[34:35], 0, v[134:135]
	s_add_i32 m0, s38, 0x2000
	s_nop 0
	global_load_lds_dwordx4 v[146:147], off
	v_lshl_add_u64 v[146:147], v[222:223], 0, s[14:15]
	s_mov_b32 m0, s51
	s_nop 0
	global_load_lds_dwordx4 v[146:147], off
	v_lshl_add_u64 v[146:147], v[224:225], 0, s[14:15]
	s_mov_b32 m0, s52
	s_nop 0
	global_load_lds_dwordx4 v[146:147], off
	s_waitcnt vmcnt(8)
	s_waitcnt lgkmcnt(0)
	s_setprio 1
	s_barrier
	v_mfma_f32_16x16x32_bf16 v[60:63], v[154:157], v[190:193], v[60:63]
	v_mfma_f32_16x16x32_bf16 v[60:63], v[158:161], v[194:197], v[60:63]
	v_mfma_f32_16x16x32_bf16 v[44:47], v[154:157], v[198:201], v[44:47]
	v_mfma_f32_16x16x32_bf16 v[44:47], v[158:161], v[202:205], v[44:47]
	v_mfma_f32_16x16x32_bf16 v[28:31], v[154:157], v[206:209], v[28:31]
	v_mfma_f32_16x16x32_bf16 v[28:31], v[158:161], v[210:213], v[28:31]
	v_mfma_f32_16x16x32_bf16 v[12:15], v[154:157], v[214:217], v[12:15]
	v_mfma_f32_16x16x32_bf16 v[12:15], v[158:161], v[218:221], v[12:15]
	v_mfma_f32_16x16x32_bf16 v[8:11], v[162:165], v[214:217], v[8:11]
	v_mfma_f32_16x16x32_bf16 v[8:11], v[166:169], v[218:221], v[8:11]
	v_mfma_f32_16x16x32_bf16 v[24:27], v[162:165], v[206:209], v[24:27]
	v_mfma_f32_16x16x32_bf16 v[24:27], v[166:169], v[210:213], v[24:27]
	v_mfma_f32_16x16x32_bf16 v[40:43], v[162:165], v[198:201], v[40:43]
	v_mfma_f32_16x16x32_bf16 v[40:43], v[166:169], v[202:205], v[40:43]
	v_mfma_f32_16x16x32_bf16 v[56:59], v[162:165], v[190:193], v[56:59]
	v_mfma_f32_16x16x32_bf16 v[56:59], v[166:169], v[194:197], v[56:59]
	s_setprio 0
	s_setprio 1
	v_mfma_f32_16x16x32_bf16 v[52:55], v[170:173], v[190:193], v[52:55]
	v_mfma_f32_16x16x32_bf16 v[52:55], v[174:177], v[194:197], v[52:55]
	v_mfma_f32_16x16x32_bf16 v[36:39], v[170:173], v[198:201], v[36:39]
	v_mfma_f32_16x16x32_bf16 v[36:39], v[174:177], v[202:205], v[36:39]
	v_mfma_f32_16x16x32_bf16 v[20:23], v[170:173], v[206:209], v[20:23]
	v_mfma_f32_16x16x32_bf16 v[20:23], v[174:177], v[210:213], v[20:23]
	v_mfma_f32_16x16x32_bf16 v[4:7], v[170:173], v[214:217], v[4:7]
	v_mfma_f32_16x16x32_bf16 v[4:7], v[174:177], v[218:221], v[4:7]
	v_mfma_f32_16x16x32_bf16 v[0:3], v[182:185], v[214:217], v[0:3]
	v_mfma_f32_16x16x32_bf16 v[0:3], v[186:189], v[218:221], v[0:3]
	v_mfma_f32_16x16x32_bf16 v[16:19], v[182:185], v[206:209], v[16:19]
	v_mfma_f32_16x16x32_bf16 v[16:19], v[186:189], v[210:213], v[16:19]
	v_mfma_f32_16x16x32_bf16 v[32:35], v[182:185], v[198:201], v[32:35]
	v_mfma_f32_16x16x32_bf16 v[32:35], v[186:189], v[202:205], v[32:35]
	v_mfma_f32_16x16x32_bf16 v[48:51], v[182:185], v[190:193], v[48:51]
	v_mfma_f32_16x16x32_bf16 v[48:51], v[186:189], v[194:197], v[48:51]
	s_setprio 0
	s_barrier
	s_add_u32 s30, s30, 0x100
	s_addc_u32 s31, s31, 0
	s_add_u32 s62, s62, 0x100
	s_addc_u32 s63, s63, 0
	s_cmp_ge_i32 s64, s50
	s_mov_b32 s34, s64
	s_cbranch_scc0 .LBB0_161

; #define PG8_STAGE(bufoff, gbase, voff) do { _Pragma("unroll") for (int _i = 0; _i < 2; ++_i) \
;         __builtin_amdgcn_global_load_lds((const unsigned*)((const char*)(gbase) + (voff)[_i]), (LAS unsigned*)(lds + (bufoff) + ldsw + _i * 8192), 16, 0, 0); } while (0)
; #define PG8_LDA(dst, b, h) do { _Pragma("unroll") for (int m = 0; m < 4; ++m) _Pragma("unroll") for (int k = 0; k < 2; ++k) dst[m][k] = *(const LAS bf16x8*)(lds + PG8_SA(b, h) + aoff + m * 2048 + k * 1024); } while (0)
; #define PG8_LDB(dst, b, h) do { _Pragma("unroll") for (int n = 0; n < 2; ++n) _Pragma("unroll") for (int k = 0; k < 2; ++k) dst[n][k] = *(const LAS bf16x8*)(lds + PG8_SB(b, h) + boff + n * 2048 + k * 1024); } while (0)
; #define PG8_MMA(ai, bj, At, Bt) do { __builtin_amdgcn_s_setprio(1); _Pragma("unroll") for (int m = 0; m < 4; ++m) _Pragma("unroll") for (int n = 0; n < 2; ++n) _Pragma("unroll") for (int k = 0; k < 2; ++k) \
;         acc[ai][bj][m][n] = __builtin_amdgcn_mfma_f32_16x16x32_bf16(Bt[n][k], At[m][k], acc[ai][bj][m][n], 0, 0, 0); __builtin_amdgcn_s_setprio(0); } while (0)
; #define PG8_WAIT_V(n) asm volatile("s_waitcnt vmcnt(" #n ")" ::: "memory")
; #define PG8_WAIT_L(n) asm volatile("s_waitcnt lgkmcnt(" #n ")" ::: "memory")
; #define PG8_BAR __builtin_amdgcn_s_barrier()
; #define PG8_SCHED __builtin_amdgcn_sched_barrier(0)
; template <class Epi>
; DI void gemm_phase(LAS unsigned char* lds, const Gemm g, const StaticOrder& S, const Epi& E) {
;     ...
;             const bool last = (t == nt - 2);
;             const char* a1 = cA + (size_t)(t + 1) * kstep;
;             const char* a2 = last ? nA : cA + (size_t)(t + 2) * kstep; const char* b2 = last ? nB : cB + (size_t)(t + 2) * kstep;
;             const char* a3 = a2 + kstep; const char* b3 = b2 + kstep;
;             PG8_LDB(B0, 0, 0); PG8_LDB(B1, 0, 1); PG8_SCHED; PG8_LDA(At, 0, 0); PG8_STAGE(PG8_SA(1, 1), a1 + hstepA, voffA);
;             PG8_WAIT_V(8); PG8_WAIT_L(0); PG8_BAR; PG8_MMA(0, 0, At, B0); PG8_MMA(0, 1, At, B1); PG8_BAR; PG8_SCHED;
;             PG8_LDA(At, 0, 1); PG8_STAGE(PG8_SB(0, 0), b2, voffB); PG8_STAGE(PG8_SB(0, 1), b2 + hstepB, voffB); PG8_STAGE(PG8_SA(0, 0), a2, voffA);
;             PG8_WAIT_V(8); PG8_WAIT_L(0); PG8_BAR; PG8_MMA(1, 0, At, B0); PG8_MMA(1, 1, At, B1); PG8_BAR; PG8_SCHED;
.LBB0_201:
	ds_read_b128 v[148:151], v145
	ds_read_b128 v[152:155], v145 offset:1024
	ds_read_b128 v[156:159], v145 offset:2048
	ds_read_b128 v[160:163], v145 offset:3072
	ds_read_b128 v[164:167], v146
	ds_read_b128 v[168:171], v146 offset:1024
	ds_read_b128 v[172:175], v146 offset:2048
	ds_read_b128 v[176:179], v146 offset:3072
	s_add_i32 s65, s28, 2
	s_add_u32 s29, s26, 0xfff00080
	s_addc_u32 s30, s27, -1
	s_cmp_eq_u32 s50, s28
	s_cselect_b32 s28, s62, s63
	s_cselect_b32 s31, s19, s30
	s_cselect_b32 s30, s21, s29
	s_cselect_b32 s29, s61, s64
	v_lshl_add_u64 v[214:215], s[26:27], 0, v[138:139]
	s_add_i32 m0, s38, 0xc000
	ds_read_b128 v[182:185], v147
	ds_read_b128 v[186:189], v147 offset:1024
	ds_read_b128 v[190:193], v147 offset:2048
	ds_read_b128 v[194:197], v147 offset:3072
	ds_read_b128 v[198:201], v147 offset:4096
	ds_read_b128 v[202:205], v147 offset:5120
	ds_read_b128 v[206:209], v147 offset:6144
	ds_read_b128 v[210:213], v147 offset:7168
	global_load_lds_dwordx4 v[214:215], off
	v_lshl_add_u64 v[214:215], s[26:27], 0, v[140:141]
	s_add_i32 m0, s38, 0xe000
	s_nop 0
	global_load_lds_dwordx4 v[214:215], off
	s_waitcnt vmcnt(8)
	s_waitcnt lgkmcnt(0)
	s_setprio 1
	s_barrier
	v_mfma_f32_16x16x32_bf16 v[120:123], v[148:151], v[182:185], v[120:123]
	v_mfma_f32_16x16x32_bf16 v[120:123], v[152:155], v[186:189], v[120:123]
	v_mfma_f32_16x16x32_bf16 v[108:111], v[148:151], v[190:193], v[108:111]
	v_mfma_f32_16x16x32_bf16 v[108:111], v[152:155], v[194:197], v[108:111]
	v_mfma_f32_16x16x32_bf16 v[92:95], v[148:151], v[198:201], v[92:95]
	v_mfma_f32_16x16x32_bf16 v[92:95], v[152:155], v[202:205], v[92:95]
	v_mfma_f32_16x16x32_bf16 v[76:79], v[148:151], v[206:209], v[76:79]
	v_mfma_f32_16x16x32_bf16 v[76:79], v[152:155], v[210:213], v[76:79]
	v_mfma_f32_16x16x32_bf16 v[72:75], v[156:159], v[206:209], v[72:75]
	v_mfma_f32_16x16x32_bf16 v[72:75], v[160:163], v[210:213], v[72:75]
	v_mfma_f32_16x16x32_bf16 v[88:91], v[156:159], v[198:201], v[88:91]
	v_mfma_f32_16x16x32_bf16 v[88:91], v[160:163], v[202:205], v[88:91]
	v_mfma_f32_16x16x32_bf16 v[104:107], v[156:159], v[190:193], v[104:107]
	v_mfma_f32_16x16x32_bf16 v[104:107], v[160:163], v[194:197], v[104:107]
	v_mfma_f32_16x16x32_bf16 v[124:127], v[156:159], v[182:185], v[124:127]
	v_mfma_f32_16x16x32_bf16 v[124:127], v[160:163], v[186:189], v[124:127]
	s_setprio 0
	s_setprio 1
	v_mfma_f32_16x16x32_bf16 v[116:119], v[164:167], v[182:185], v[116:119]
	v_mfma_f32_16x16x32_bf16 v[116:119], v[168:171], v[186:189], v[116:119]
	v_mfma_f32_16x16x32_bf16 v[100:103], v[164:167], v[190:193], v[100:103]
	v_mfma_f32_16x16x32_bf16 v[100:103], v[168:171], v[194:197], v[100:103]
	v_mfma_f32_16x16x32_bf16 v[84:87], v[164:167], v[198:201], v[84:87]
	v_mfma_f32_16x16x32_bf16 v[84:87], v[168:171], v[202:205], v[84:87]
	v_mfma_f32_16x16x32_bf16 v[68:71], v[164:167], v[206:209], v[68:71]
	v_mfma_f32_16x16x32_bf16 v[68:71], v[168:171], v[210:213], v[68:71]
	v_mfma_f32_16x16x32_bf16 v[64:67], v[172:175], v[206:209], v[64:67]
	v_mfma_f32_16x16x32_bf16 v[64:67], v[176:179], v[210:213], v[64:67]
	v_mfma_f32_16x16x32_bf16 v[80:83], v[172:175], v[198:201], v[80:83]
	v_mfma_f32_16x16x32_bf16 v[80:83], v[176:179], v[202:205], v[80:83]
	v_mfma_f32_16x16x32_bf16 v[96:99], v[172:175], v[190:193], v[96:99]
	v_mfma_f32_16x16x32_bf16 v[96:99], v[176:179], v[194:197], v[96:99]
	v_mfma_f32_16x16x32_bf16 v[112:115], v[172:175], v[182:185], v[112:115]
	v_mfma_f32_16x16x32_bf16 v[112:115], v[176:179], v[186:189], v[112:115]
	s_setprio 0
	s_barrier
	s_add_i32 s66, s52, s35
	v_lshl_add_u64 v[214:215], s[28:29], 0, v[132:133]
	s_mov_b32 m0, s66
	ds_read_b128 v[182:185], v147 offset:16384
	ds_read_b128 v[186:189], v147 offset:17408
	ds_read_b128 v[190:193], v147 offset:18432
	ds_read_b128 v[194:197], v147 offset:19456
	ds_read_b128 v[198:201], v147 offset:20480
	ds_read_b128 v[202:205], v147 offset:21504
	ds_read_b128 v[206:209], v147 offset:22528
	ds_read_b128 v[210:213], v147 offset:23552
	global_load_lds_dwordx4 v[214:215], off
	s_add_i32 m0, s66, 0x2000
	s_add_u32 s66, s28, 0x100000
	v_lshl_add_u64 v[216:217], s[28:29], 0, v[128:129]
	s_addc_u32 s67, s29, 0
	s_add_i32 s68, s53, s35
	global_load_lds_dwordx4 v[216:217], off
	v_lshl_add_u64 v[218:219], s[66:67], 0, v[132:133]
	s_mov_b32 m0, s68
	v_lshl_add_u64 v[220:221], s[30:31], 0, v[130:131]
	global_load_lds_dwordx4 v[218:219], off
	v_lshl_add_u64 v[218:219], s[66:67], 0, v[128:129]
	s_add_i32 m0, s68, 0x2000
	s_nop 0
	global_load_lds_dwordx4 v[218:219], off
	v_lshl_add_u64 v[218:219], s[30:31], 0, v[134:135]
	s_mov_b32 m0, s38
	s_nop 0
	global_load_lds_dwordx4 v[218:219], off
	s_mov_b32 m0, s39
	s_nop 0
	global_load_lds_dwordx4 v[220:221], off
	s_waitcnt vmcnt(8)
	s_waitcnt lgkmcnt(0)
	s_setprio 1
	s_barrier
; #define PG8_STAGE(bufoff, gbase, voff) do { _Pragma("unroll") for (int _i = 0; _i < 2; ++_i) \
;         __builtin_amdgcn_global_load_lds((const unsigned*)((const char*)(gbase) + (voff)[_i]), (LAS unsigned*)(lds + (bufoff) + ldsw + _i * 8192), 16, 0, 0); } while (0)
; #define PG8_LDA(dst, b, h) do { _Pragma("unroll") for (int m = 0; m < 4; ++m) _Pragma("unroll") for (int k = 0; k < 2; ++k) dst[m][k] = *(const LAS bf16x8*)(lds + PG8_SA(b, h) + aoff + m * 2048 + k * 1024); } while (0)
; #define PG8_LDB(dst, b, h) do { _Pragma("unroll") for (int n = 0; n < 2; ++n) _Pragma("unroll") for (int k = 0; k < 2; ++k) dst[n][k] = *(const LAS bf16x8*)(lds + PG8_SB(b, h) + boff + n * 2048 + k * 1024); } while (0)
; #define PG8_MMA(ai, bj, At, Bt) do { __builtin_amdgcn_s_setprio(1); _Pragma("unroll") for (int m = 0; m < 4; ++m) _Pragma("unroll") for (int n = 0; n < 2; ++n) _Pragma("unroll") for (int k = 0; k < 2; ++k) \
;         acc[ai][bj][m][n] = __builtin_amdgcn_mfma_f32_16x16x32_bf16(Bt[n][k], At[m][k], acc[ai][bj][m][n], 0, 0, 0); __builtin_amdgcn_s_setprio(0); } while (0)
; #define PG8_WAIT_V(n) asm volatile("s_waitcnt vmcnt(" #n ")" ::: "memory")
; #define PG8_WAIT_L(n) asm volatile("s_waitcnt lgkmcnt(" #n ")" ::: "memory")
; #define PG8_BAR __builtin_amdgcn_s_barrier()
; #define PG8_SCHED __builtin_amdgcn_sched_barrier(0)
; template <class Epi>
; DI void gemm_phase(LAS unsigned char* lds, const Gemm g, const StaticOrder& S, const Epi& E) {
;     ...
;             PG8_WAIT_V(8); PG8_WAIT_L(0); PG8_BAR; PG8_MMA(1, 0, At, B0); PG8_MMA(1, 1, At, B1); PG8_BAR; PG8_SCHED;
;             PG8_LDB(B0, 1, 0); PG8_LDB(B1, 1, 1); PG8_SCHED; PG8_LDA(At, 1, 0); PG8_STAGE(PG8_SA(0, 1), a2 + hstepA, voffA);
;             PG8_WAIT_V(8); PG8_WAIT_L(0); PG8_BAR; PG8_MMA(0, 0, At, B0); PG8_MMA(0, 1, At, B1); PG8_BAR; PG8_SCHED;
	v_mfma_f32_16x16x32_bf16 v[60:63], v[148:151], v[182:185], v[60:63]
	v_mfma_f32_16x16x32_bf16 v[60:63], v[152:155], v[186:189], v[60:63]
	v_mfma_f32_16x16x32_bf16 v[44:47], v[148:151], v[190:193], v[44:47]
	v_mfma_f32_16x16x32_bf16 v[44:47], v[152:155], v[194:197], v[44:47]
	v_mfma_f32_16x16x32_bf16 v[28:31], v[148:151], v[198:201], v[28:31]
	v_mfma_f32_16x16x32_bf16 v[28:31], v[152:155], v[202:205], v[28:31]
	v_mfma_f32_16x16x32_bf16 v[12:15], v[148:151], v[206:209], v[12:15]
	v_mfma_f32_16x16x32_bf16 v[12:15], v[152:155], v[210:213], v[12:15]
	v_mfma_f32_16x16x32_bf16 v[8:11], v[156:159], v[206:209], v[8:11]
	v_mfma_f32_16x16x32_bf16 v[8:11], v[160:163], v[210:213], v[8:11]
	v_mfma_f32_16x16x32_bf16 v[24:27], v[156:159], v[198:201], v[24:27]
	v_mfma_f32_16x16x32_bf16 v[24:27], v[160:163], v[202:205], v[24:27]
	v_mfma_f32_16x16x32_bf16 v[40:43], v[156:159], v[190:193], v[40:43]
	v_mfma_f32_16x16x32_bf16 v[40:43], v[160:163], v[194:197], v[40:43]
	v_mfma_f32_16x16x32_bf16 v[56:59], v[156:159], v[182:185], v[56:59]
	v_mfma_f32_16x16x32_bf16 v[56:59], v[160:163], v[186:189], v[56:59]
	s_setprio 0
	s_setprio 1
	v_mfma_f32_16x16x32_bf16 v[52:55], v[164:167], v[182:185], v[52:55]
	v_mfma_f32_16x16x32_bf16 v[52:55], v[168:171], v[186:189], v[52:55]
	v_mfma_f32_16x16x32_bf16 v[36:39], v[164:167], v[190:193], v[36:39]
	v_mfma_f32_16x16x32_bf16 v[36:39], v[168:171], v[194:197], v[36:39]
	v_mfma_f32_16x16x32_bf16 v[20:23], v[164:167], v[198:201], v[20:23]
	v_mfma_f32_16x16x32_bf16 v[20:23], v[168:171], v[202:205], v[20:23]
	v_mfma_f32_16x16x32_bf16 v[4:7], v[164:167], v[206:209], v[4:7]
	v_mfma_f32_16x16x32_bf16 v[4:7], v[168:171], v[210:213], v[4:7]
	v_mfma_f32_16x16x32_bf16 v[0:3], v[172:175], v[206:209], v[0:3]
	v_mfma_f32_16x16x32_bf16 v[0:3], v[176:179], v[210:213], v[0:3]
	v_mfma_f32_16x16x32_bf16 v[16:19], v[172:175], v[198:201], v[16:19]
	v_mfma_f32_16x16x32_bf16 v[16:19], v[176:179], v[202:205], v[16:19]
	v_mfma_f32_16x16x32_bf16 v[32:35], v[172:175], v[190:193], v[32:35]
	v_mfma_f32_16x16x32_bf16 v[32:35], v[176:179], v[194:197], v[32:35]
	v_mfma_f32_16x16x32_bf16 v[48:51], v[172:175], v[182:185], v[48:51]
	v_mfma_f32_16x16x32_bf16 v[48:51], v[176:179], v[186:189], v[48:51]
	s_setprio 0
	s_barrier
	s_add_i32 s66, 0, 0x18000
	v_add_u32_e32 v136, s66, v143
	s_add_i32 s67, 0, 0x1c000
	ds_read_b128 v[148:151], v136
	ds_read_b128 v[152:155], v136 offset:1024
	ds_read_b128 v[156:159], v136 offset:2048
	ds_read_b128 v[160:163], v136 offset:3072
	v_add_u32_e32 v136, s67, v143
	ds_read_b128 v[164:167], v136
	ds_read_b128 v[168:171], v136 offset:1024
	ds_read_b128 v[172:175], v136 offset:2048
	ds_read_b128 v[176:179], v136 offset:3072
	s_add_u32 s30, s30, 0x100000
	s_addc_u32 s31, s31, 0
	s_mov_b32 m0, s40
	v_lshl_add_u64 v[222:223], s[30:31], 0, v[134:135]
	ds_read_b128 v[182:185], v147 offset:32768
	ds_read_b128 v[186:189], v147 offset:33792
	ds_read_b128 v[190:193], v147 offset:34816
	ds_read_b128 v[194:197], v147 offset:35840
	ds_read_b128 v[198:201], v147 offset:36864
	ds_read_b128 v[202:205], v147 offset:37888
	ds_read_b128 v[206:209], v147 offset:38912
	ds_read_b128 v[210:213], v147 offset:39936
	global_load_lds_dwordx4 v[222:223], off
	v_lshl_add_u64 v[222:223], s[30:31], 0, v[130:131]
	s_mov_b32 m0, s41
	s_nop 0
	global_load_lds_dwordx4 v[222:223], off
	s_waitcnt vmcnt(8)
	s_waitcnt lgkmcnt(0)
	s_setprio 1
	s_barrier
	v_mfma_f32_16x16x32_bf16 v[120:123], v[148:151], v[182:185], v[120:123]
	v_mfma_f32_16x16x32_bf16 v[120:123], v[152:155], v[186:189], v[120:123]
	v_mfma_f32_16x16x32_bf16 v[108:111], v[148:151], v[190:193], v[108:111]
	v_mfma_f32_16x16x32_bf16 v[108:111], v[152:155], v[194:197], v[108:111]
	v_mfma_f32_16x16x32_bf16 v[92:95], v[148:151], v[198:201], v[92:95]
	v_mfma_f32_16x16x32_bf16 v[92:95], v[152:155], v[202:205], v[92:95]
	v_mfma_f32_16x16x32_bf16 v[76:79], v[148:151], v[206:209], v[76:79]
	v_mfma_f32_16x16x32_bf16 v[76:79], v[152:155], v[210:213], v[76:79]
	v_mfma_f32_16x16x32_bf16 v[72:75], v[156:159], v[206:209], v[72:75]
	v_mfma_f32_16x16x32_bf16 v[72:75], v[160:163], v[210:213], v[72:75]
	v_mfma_f32_16x16x32_bf16 v[88:91], v[156:159], v[198:201], v[88:91]
	v_mfma_f32_16x16x32_bf16 v[88:91], v[160:163], v[202:205], v[88:91]
	v_mfma_f32_16x16x32_bf16 v[104:107], v[156:159], v[190:193], v[104:107]
	v_mfma_f32_16x16x32_bf16 v[104:107], v[160:163], v[194:197], v[104:107]
	v_mfma_f32_16x16x32_bf16 v[124:127], v[156:159], v[182:185], v[124:127]
	v_mfma_f32_16x16x32_bf16 v[124:127], v[160:163], v[186:189], v[124:127]
	s_setprio 0
	s_setprio 1
	v_mfma_f32_16x16x32_bf16 v[116:119], v[164:167], v[182:185], v[116:119]
	v_mfma_f32_16x16x32_bf16 v[116:119], v[168:171], v[186:189], v[116:119]
	v_mfma_f32_16x16x32_bf16 v[100:103], v[164:167], v[190:193], v[100:103]
	v_mfma_f32_16x16x32_bf16 v[100:103], v[168:171], v[194:197], v[100:103]
	v_mfma_f32_16x16x32_bf16 v[84:87], v[164:167], v[198:201], v[84:87]
	v_mfma_f32_16x16x32_bf16 v[84:87], v[168:171], v[202:205], v[84:87]
	v_mfma_f32_16x16x32_bf16 v[68:71], v[164:167], v[206:209], v[68:71]
	v_mfma_f32_16x16x32_bf16 v[68:71], v[168:171], v[210:213], v[68:71]
	v_mfma_f32_16x16x32_bf16 v[64:67], v[172:175], v[206:209], v[64:67]
	v_mfma_f32_16x16x32_bf16 v[64:67], v[176:179], v[210:213], v[64:67]
	v_mfma_f32_16x16x32_bf16 v[80:83], v[172:175], v[198:201], v[80:83]
	v_mfma_f32_16x16x32_bf16 v[80:83], v[176:179], v[202:205], v[80:83]
	v_mfma_f32_16x16x32_bf16 v[96:99], v[172:175], v[190:193], v[96:99]
	v_mfma_f32_16x16x32_bf16 v[96:99], v[176:179], v[194:197], v[96:99]
	v_mfma_f32_16x16x32_bf16 v[112:115], v[172:175], v[182:185], v[112:115]
	v_mfma_f32_16x16x32_bf16 v[112:115], v[176:179], v[186:189], v[112:115]
	s_setprio 0
	s_barrier
; #define PG8_STAGE(bufoff, gbase, voff) do { _Pragma("unroll") for (int _i = 0; _i < 2; ++_i) \
;         __builtin_amdgcn_global_load_lds((const unsigned*)((const char*)(gbase) + (voff)[_i]), (LAS unsigned*)(lds + (bufoff) + ldsw + _i * 8192), 16, 0, 0); } while (0)
; #define PG8_LDA(dst, b, h) do { _Pragma("unroll") for (int m = 0; m < 4; ++m) _Pragma("unroll") for (int k = 0; k < 2; ++k) dst[m][k] = *(const LAS bf16x8*)(lds + PG8_SA(b, h) + aoff + m * 2048 + k * 1024); } while (0)
; #define PG8_MMA(ai, bj, At, Bt) do { __builtin_amdgcn_s_setprio(1); _Pragma("unroll") for (int m = 0; m < 4; ++m) _Pragma("unroll") for (int n = 0; n < 2; ++n) _Pragma("unroll") for (int k = 0; k < 2; ++k) \
;         acc[ai][bj][m][n] = __builtin_amdgcn_mfma_f32_16x16x32_bf16(Bt[n][k], At[m][k], acc[ai][bj][m][n], 0, 0, 0); __builtin_amdgcn_s_setprio(0); } while (0)
; #define PG8_WAIT_V(n) asm volatile("s_waitcnt vmcnt(" #n ")" ::: "memory")
; #define PG8_WAIT_L(n) asm volatile("s_waitcnt lgkmcnt(" #n ")" ::: "memory")
; #define PG8_BAR __builtin_amdgcn_s_barrier()
; #define PG8_SCHED __builtin_amdgcn_sched_barrier(0)
; template <class Epi>
; DI void gemm_phase(LAS unsigned char* lds, const Gemm g, const StaticOrder& S, const Epi& E) {
;     ...
;             PG8_LDA(At, 1, 1); PG8_STAGE(PG8_SB(1, 0), b3, voffB); PG8_STAGE(PG8_SB(1, 1), b3 + hstepB, voffB); PG8_STAGE(PG8_SA(1, 0), a3, voffA);
;             PG8_WAIT_V(8); PG8_WAIT_L(0); PG8_BAR; PG8_MMA(1, 0, At, B0); PG8_MMA(1, 1, At, B1); PG8_BAR; PG8_SCHED;
;         }
	s_add_i32 s30, s66, s35
	v_lshl_add_u64 v[214:215], v[214:215], 0, s[10:11]
	s_mov_b32 m0, s30
	ds_read_b128 v[182:185], v147 offset:49152
	ds_read_b128 v[186:189], v147 offset:50176
	ds_read_b128 v[190:193], v147 offset:51200
	ds_read_b128 v[194:197], v147 offset:52224
	ds_read_b128 v[198:201], v147 offset:53248
	ds_read_b128 v[202:205], v147 offset:54272
	ds_read_b128 v[206:209], v147 offset:55296
	ds_read_b128 v[210:213], v147 offset:56320
	global_load_lds_dwordx4 v[214:215], off
	s_add_i32 m0, s30, 0x2000
	s_add_u32 s28, s28, 0x100080
	v_lshl_add_u64 v[214:215], v[216:217], 0, s[10:11]
	s_addc_u32 s29, s29, 0
	s_add_i32 s30, s67, s35
	global_load_lds_dwordx4 v[214:215], off
	v_lshl_add_u64 v[214:215], s[28:29], 0, v[132:133]
	s_mov_b32 m0, s30
	s_nop 0
	global_load_lds_dwordx4 v[214:215], off
	v_lshl_add_u64 v[214:215], s[28:29], 0, v[128:129]
	s_add_i32 m0, s30, 0x2000
	s_nop 0
	global_load_lds_dwordx4 v[214:215], off
	v_lshl_add_u64 v[214:215], v[218:219], 0, s[10:11]
	s_mov_b32 m0, s46
	s_nop 0
	global_load_lds_dwordx4 v[214:215], off
	v_lshl_add_u64 v[214:215], v[220:221], 0, s[10:11]
	s_mov_b32 m0, s47
	s_nop 0
	global_load_lds_dwordx4 v[214:215], off
	s_waitcnt vmcnt(8)
	s_waitcnt lgkmcnt(0)
	s_setprio 1
	s_barrier
	v_mfma_f32_16x16x32_bf16 v[60:63], v[148:151], v[182:185], v[60:63]
	v_mfma_f32_16x16x32_bf16 v[60:63], v[152:155], v[186:189], v[60:63]
	v_mfma_f32_16x16x32_bf16 v[44:47], v[148:151], v[190:193], v[44:47]
	v_mfma_f32_16x16x32_bf16 v[44:47], v[152:155], v[194:197], v[44:47]
	v_mfma_f32_16x16x32_bf16 v[28:31], v[148:151], v[198:201], v[28:31]
	v_mfma_f32_16x16x32_bf16 v[28:31], v[152:155], v[202:205], v[28:31]
	v_mfma_f32_16x16x32_bf16 v[12:15], v[148:151], v[206:209], v[12:15]
	v_mfma_f32_16x16x32_bf16 v[12:15], v[152:155], v[210:213], v[12:15]
	v_mfma_f32_16x16x32_bf16 v[8:11], v[156:159], v[206:209], v[8:11]
	v_mfma_f32_16x16x32_bf16 v[8:11], v[160:163], v[210:213], v[8:11]
	v_mfma_f32_16x16x32_bf16 v[24:27], v[156:159], v[198:201], v[24:27]
	v_mfma_f32_16x16x32_bf16 v[24:27], v[160:163], v[202:205], v[24:27]
	v_mfma_f32_16x16x32_bf16 v[40:43], v[156:159], v[190:193], v[40:43]
	v_mfma_f32_16x16x32_bf16 v[40:43], v[160:163], v[194:197], v[40:43]
	v_mfma_f32_16x16x32_bf16 v[56:59], v[156:159], v[182:185], v[56:59]
	v_mfma_f32_16x16x32_bf16 v[56:59], v[160:163], v[186:189], v[56:59]
	s_setprio 0
	s_setprio 1
	v_mfma_f32_16x16x32_bf16 v[52:55], v[164:167], v[182:185], v[52:55]
	v_mfma_f32_16x16x32_bf16 v[52:55], v[168:171], v[186:189], v[52:55]
	v_mfma_f32_16x16x32_bf16 v[36:39], v[164:167], v[190:193], v[36:39]
	v_mfma_f32_16x16x32_bf16 v[36:39], v[168:171], v[194:197], v[36:39]
	v_mfma_f32_16x16x32_bf16 v[20:23], v[164:167], v[198:201], v[20:23]
	v_mfma_f32_16x16x32_bf16 v[20:23], v[168:171], v[202:205], v[20:23]
	v_mfma_f32_16x16x32_bf16 v[4:7], v[164:167], v[206:209], v[4:7]
	v_mfma_f32_16x16x32_bf16 v[4:7], v[168:171], v[210:213], v[4:7]
	v_mfma_f32_16x16x32_bf16 v[0:3], v[172:175], v[206:209], v[0:3]
	v_mfma_f32_16x16x32_bf16 v[0:3], v[176:179], v[210:213], v[0:3]
	v_mfma_f32_16x16x32_bf16 v[16:19], v[172:175], v[198:201], v[16:19]
	v_mfma_f32_16x16x32_bf16 v[16:19], v[176:179], v[202:205], v[16:19]
	v_mfma_f32_16x16x32_bf16 v[32:35], v[172:175], v[190:193], v[32:35]
	v_mfma_f32_16x16x32_bf16 v[32:35], v[176:179], v[194:197], v[32:35]
	v_mfma_f32_16x16x32_bf16 v[48:51], v[172:175], v[182:185], v[48:51]
	v_mfma_f32_16x16x32_bf16 v[48:51], v[176:179], v[186:189], v[48:51]
	s_setprio 0
	s_barrier
	s_add_u32 s26, s26, 0x100
	s_addc_u32 s27, s27, 0
	s_add_u32 s63, s63, 0x100
	s_addc_u32 s64, s64, 0
	s_cmp_ge_i32 s65, s43
	s_mov_b32 s28, s65
	s_cbranch_scc0 .LBB0_201

; #define PG8_STAGE(bufoff, gbase, voff) do { _Pragma("unroll") for (int _i = 0; _i < 2; ++_i) \
;         __builtin_amdgcn_global_load_lds((const unsigned*)((const char*)(gbase) + (voff)[_i]), (LAS unsigned*)(lds + (bufoff) + ldsw + _i * 8192), 16, 0, 0); } while (0)
; #define PG8_LDA(dst, b, h) do { _Pragma("unroll") for (int m = 0; m < 4; ++m) _Pragma("unroll") for (int k = 0; k < 2; ++k) dst[m][k] = *(const LAS bf16x8*)(lds + PG8_SA(b, h) + aoff + m * 2048 + k * 1024); } while (0)
; #define PG8_LDB(dst, b, h) do { _Pragma("unroll") for (int n = 0; n < 2; ++n) _Pragma("unroll") for (int k = 0; k < 2; ++k) dst[n][k] = *(const LAS bf16x8*)(lds + PG8_SB(b, h) + boff + n * 2048 + k * 1024); } while (0)
; #define PG8_MMA(ai, bj, At, Bt) do { __builtin_amdgcn_s_setprio(1); _Pragma("unroll") for (int m = 0; m < 4; ++m) _Pragma("unroll") for (int n = 0; n < 2; ++n) _Pragma("unroll") for (int k = 0; k < 2; ++k) \
;         acc[ai][bj][m][n] = __builtin_amdgcn_mfma_f32_16x16x32_bf16(Bt[n][k], At[m][k], acc[ai][bj][m][n], 0, 0, 0); __builtin_amdgcn_s_setprio(0); } while (0)
; #define PG8_WAIT_V(n) asm volatile("s_waitcnt vmcnt(" #n ")" ::: "memory")
; #define PG8_WAIT_L(n) asm volatile("s_waitcnt lgkmcnt(" #n ")" ::: "memory")
; #define PG8_BAR __builtin_amdgcn_s_barrier()
; #define PG8_SCHED __builtin_amdgcn_sched_barrier(0)
; template <class Epi>
; DI void gemm_phase(LAS unsigned char* lds, const Gemm g, const StaticOrder& S, const Epi& E) {
;     ...
;             const bool last = (t == nt - 2);
;             const char* a1 = cA + (size_t)(t + 1) * kstep;
;             const char* a2 = last ? nA : cA + (size_t)(t + 2) * kstep; const char* b2 = last ? nB : cB + (size_t)(t + 2) * kstep;
;             const char* a3 = a2 + kstep; const char* b3 = b2 + kstep;
;             PG8_LDB(B0, 0, 0); PG8_LDB(B1, 0, 1); PG8_SCHED; PG8_LDA(At, 0, 0); PG8_STAGE(PG8_SA(1, 1), a1 + hstepA, voffA);
;             PG8_WAIT_V(8); PG8_WAIT_L(0); PG8_BAR; PG8_MMA(0, 0, At, B0); PG8_MMA(0, 1, At, B1); PG8_BAR; PG8_SCHED;
;             PG8_LDA(At, 0, 1); PG8_STAGE(PG8_SB(0, 0), b2, voffB); PG8_STAGE(PG8_SB(0, 1), b2 + hstepB, voffB); PG8_STAGE(PG8_SA(0, 0), a2, voffA);
;             PG8_WAIT_V(8); PG8_WAIT_L(0); PG8_BAR; PG8_MMA(1, 0, At, B0); PG8_MMA(1, 1, At, B1); PG8_BAR; PG8_SCHED;
.LBB0_302:
	ds_read_b128 v[128:131], v174
	ds_read_b128 v[132:135], v174 offset:1024
	ds_read_b128 v[156:159], v174 offset:2048
	ds_read_b128 v[160:163], v174 offset:3072
	ds_read_b128 v[164:167], v175
	ds_read_b128 v[168:171], v175 offset:1024
	ds_read_b128 v[182:185], v175 offset:2048
	ds_read_b128 v[186:189], v175 offset:3072
	s_add_i32 s30, s10, 2
	s_add_u32 s6, s8, 0x100
	s_addc_u32 s7, s9, 0
	s_cmp_eq_u32 s68, s10
	s_cselect_b32 s10, s17, s18
	s_cselect_b32 s13, s43, s7
	s_cselect_b32 s12, s42, s6
	s_cselect_b32 s11, s16, s19
	v_lshl_add_u64 v[178:179], s[8:9], 0, v[148:149]
	s_add_i32 m0, s61, 0xc000
	ds_read_b128 v[190:193], v176
	ds_read_b128 v[194:197], v176 offset:1024
	ds_read_b128 v[198:201], v176 offset:2048
	ds_read_b128 v[202:205], v176 offset:3072
	ds_read_b128 v[206:209], v176 offset:4096
	ds_read_b128 v[210:213], v176 offset:5120
	ds_read_b128 v[214:217], v176 offset:6144
	ds_read_b128 v[218:221], v176 offset:7168
	global_load_lds_dwordx4 v[178:179], off
	v_lshl_add_u64 v[178:179], s[8:9], 0, v[150:151]
	s_add_i32 m0, s61, 0xe000
	s_nop 0
	global_load_lds_dwordx4 v[178:179], off
	s_waitcnt vmcnt(8)
	s_waitcnt lgkmcnt(0)
	s_setprio 1
	s_barrier
	v_mfma_f32_16x16x32_bf16 v[120:123], v[128:131], v[190:193], v[120:123]
	v_mfma_f32_16x16x32_bf16 v[120:123], v[132:135], v[194:197], v[120:123]
	v_mfma_f32_16x16x32_bf16 v[108:111], v[128:131], v[198:201], v[108:111]
	v_mfma_f32_16x16x32_bf16 v[108:111], v[132:135], v[202:205], v[108:111]
	v_mfma_f32_16x16x32_bf16 v[92:95], v[128:131], v[206:209], v[92:95]
	v_mfma_f32_16x16x32_bf16 v[92:95], v[132:135], v[210:213], v[92:95]
	v_mfma_f32_16x16x32_bf16 v[76:79], v[128:131], v[214:217], v[76:79]
	v_mfma_f32_16x16x32_bf16 v[76:79], v[132:135], v[218:221], v[76:79]
	v_mfma_f32_16x16x32_bf16 v[72:75], v[156:159], v[214:217], v[72:75]
	v_mfma_f32_16x16x32_bf16 v[72:75], v[160:163], v[218:221], v[72:75]
	v_mfma_f32_16x16x32_bf16 v[88:91], v[156:159], v[206:209], v[88:91]
	v_mfma_f32_16x16x32_bf16 v[88:91], v[160:163], v[210:213], v[88:91]
	v_mfma_f32_16x16x32_bf16 v[104:107], v[156:159], v[198:201], v[104:107]
	v_mfma_f32_16x16x32_bf16 v[104:107], v[160:163], v[202:205], v[104:107]
	v_mfma_f32_16x16x32_bf16 v[124:127], v[156:159], v[190:193], v[124:127]
	v_mfma_f32_16x16x32_bf16 v[124:127], v[160:163], v[194:197], v[124:127]
	s_setprio 0
	s_setprio 1
	v_mfma_f32_16x16x32_bf16 v[116:119], v[164:167], v[190:193], v[116:119]
	v_mfma_f32_16x16x32_bf16 v[116:119], v[168:171], v[194:197], v[116:119]
	v_mfma_f32_16x16x32_bf16 v[100:103], v[164:167], v[198:201], v[100:103]
	v_mfma_f32_16x16x32_bf16 v[100:103], v[168:171], v[202:205], v[100:103]
	v_mfma_f32_16x16x32_bf16 v[84:87], v[164:167], v[206:209], v[84:87]
	v_mfma_f32_16x16x32_bf16 v[84:87], v[168:171], v[210:213], v[84:87]
	v_mfma_f32_16x16x32_bf16 v[68:71], v[164:167], v[214:217], v[68:71]
	v_mfma_f32_16x16x32_bf16 v[68:71], v[168:171], v[218:221], v[68:71]
	v_mfma_f32_16x16x32_bf16 v[64:67], v[182:185], v[214:217], v[64:67]
	v_mfma_f32_16x16x32_bf16 v[64:67], v[186:189], v[218:221], v[64:67]
	v_mfma_f32_16x16x32_bf16 v[80:83], v[182:185], v[206:209], v[80:83]
	v_mfma_f32_16x16x32_bf16 v[80:83], v[186:189], v[210:213], v[80:83]
	v_mfma_f32_16x16x32_bf16 v[96:99], v[182:185], v[198:201], v[96:99]
	v_mfma_f32_16x16x32_bf16 v[96:99], v[186:189], v[202:205], v[96:99]
	v_mfma_f32_16x16x32_bf16 v[112:115], v[182:185], v[190:193], v[112:115]
	v_mfma_f32_16x16x32_bf16 v[112:115], v[186:189], v[194:197], v[112:115]
	s_setprio 0
	s_barrier
	s_add_i32 s8, s69, s59
	v_lshl_add_u64 v[178:179], s[10:11], 0, v[140:141]
	s_mov_b32 m0, s8
	ds_read_b128 v[190:193], v176 offset:16384
	ds_read_b128 v[194:197], v176 offset:17408
	ds_read_b128 v[198:201], v176 offset:18432
	ds_read_b128 v[202:205], v176 offset:19456
	ds_read_b128 v[206:209], v176 offset:20480
	ds_read_b128 v[210:213], v176 offset:21504
	ds_read_b128 v[214:217], v176 offset:22528
	ds_read_b128 v[218:221], v176 offset:23552
	global_load_lds_dwordx4 v[178:179], off
	s_add_i32 m0, s8, 0x2000
	s_add_u32 s8, s10, 0x40000
	v_lshl_add_u64 v[222:223], s[10:11], 0, v[136:137]
	s_addc_u32 s9, s11, 0
	s_add_i32 s41, s70, s59
	global_load_lds_dwordx4 v[222:223], off
	v_lshl_add_u64 v[224:225], s[8:9], 0, v[140:141]
	s_mov_b32 m0, s41
	v_lshl_add_u64 v[226:227], s[12:13], 0, v[138:139]
	global_load_lds_dwordx4 v[224:225], off
	v_lshl_add_u64 v[224:225], s[8:9], 0, v[136:137]
	s_add_i32 m0, s41, 0x2000
	s_nop 0
	global_load_lds_dwordx4 v[224:225], off
	v_lshl_add_u64 v[224:225], s[12:13], 0, v[142:143]
	s_mov_b32 m0, s61
	s_nop 0
	global_load_lds_dwordx4 v[224:225], off
	s_mov_b32 m0, s62
	s_nop 0
	global_load_lds_dwordx4 v[226:227], off
	s_waitcnt vmcnt(8)
	s_waitcnt lgkmcnt(0)
	s_setprio 1
	s_barrier
; #define PG8_STAGE(bufoff, gbase, voff) do { _Pragma("unroll") for (int _i = 0; _i < 2; ++_i) \
;         __builtin_amdgcn_global_load_lds((const unsigned*)((const char*)(gbase) + (voff)[_i]), (LAS unsigned*)(lds + (bufoff) + ldsw + _i * 8192), 16, 0, 0); } while (0)
; #define PG8_LDA(dst, b, h) do { _Pragma("unroll") for (int m = 0; m < 4; ++m) _Pragma("unroll") for (int k = 0; k < 2; ++k) dst[m][k] = *(const LAS bf16x8*)(lds + PG8_SA(b, h) + aoff + m * 2048 + k * 1024); } while (0)
; #define PG8_LDB(dst, b, h) do { _Pragma("unroll") for (int n = 0; n < 2; ++n) _Pragma("unroll") for (int k = 0; k < 2; ++k) dst[n][k] = *(const LAS bf16x8*)(lds + PG8_SB(b, h) + boff + n * 2048 + k * 1024); } while (0)
; #define PG8_MMA(ai, bj, At, Bt) do { __builtin_amdgcn_s_setprio(1); _Pragma("unroll") for (int m = 0; m < 4; ++m) _Pragma("unroll") for (int n = 0; n < 2; ++n) _Pragma("unroll") for (int k = 0; k < 2; ++k) \
;         acc[ai][bj][m][n] = __builtin_amdgcn_mfma_f32_16x16x32_bf16(Bt[n][k], At[m][k], acc[ai][bj][m][n], 0, 0, 0); __builtin_amdgcn_s_setprio(0); } while (0)
; #define PG8_WAIT_V(n) asm volatile("s_waitcnt vmcnt(" #n ")" ::: "memory")
; #define PG8_WAIT_L(n) asm volatile("s_waitcnt lgkmcnt(" #n ")" ::: "memory")
; #define PG8_BAR __builtin_amdgcn_s_barrier()
; #define PG8_SCHED __builtin_amdgcn_sched_barrier(0)
; template <class Epi>
; DI void gemm_phase(LAS unsigned char* lds, const Gemm g, const StaticOrder& S, const Epi& E) {
;     ...
;             PG8_WAIT_V(8); PG8_WAIT_L(0); PG8_BAR; PG8_MMA(1, 0, At, B0); PG8_MMA(1, 1, At, B1); PG8_BAR; PG8_SCHED;
;             PG8_LDB(B0, 1, 0); PG8_LDB(B1, 1, 1); PG8_SCHED; PG8_LDA(At, 1, 0); PG8_STAGE(PG8_SA(0, 1), a2 + hstepA, voffA);
;             PG8_WAIT_V(8); PG8_WAIT_L(0); PG8_BAR; PG8_MMA(0, 0, At, B0); PG8_MMA(0, 1, At, B1); PG8_BAR; PG8_SCHED;
	v_mfma_f32_16x16x32_bf16 v[60:63], v[128:131], v[190:193], v[60:63]
	v_mfma_f32_16x16x32_bf16 v[60:63], v[132:135], v[194:197], v[60:63]
	v_mfma_f32_16x16x32_bf16 v[44:47], v[128:131], v[198:201], v[44:47]
	v_mfma_f32_16x16x32_bf16 v[44:47], v[132:135], v[202:205], v[44:47]
	v_mfma_f32_16x16x32_bf16 v[28:31], v[128:131], v[206:209], v[28:31]
	v_mfma_f32_16x16x32_bf16 v[28:31], v[132:135], v[210:213], v[28:31]
	v_mfma_f32_16x16x32_bf16 v[12:15], v[128:131], v[214:217], v[12:15]
	v_mfma_f32_16x16x32_bf16 v[12:15], v[132:135], v[218:221], v[12:15]
	v_mfma_f32_16x16x32_bf16 v[8:11], v[156:159], v[214:217], v[8:11]
	v_mfma_f32_16x16x32_bf16 v[8:11], v[160:163], v[218:221], v[8:11]
	v_mfma_f32_16x16x32_bf16 v[24:27], v[156:159], v[206:209], v[24:27]
	v_mfma_f32_16x16x32_bf16 v[24:27], v[160:163], v[210:213], v[24:27]
	v_mfma_f32_16x16x32_bf16 v[40:43], v[156:159], v[198:201], v[40:43]
	v_mfma_f32_16x16x32_bf16 v[40:43], v[160:163], v[202:205], v[40:43]
	v_mfma_f32_16x16x32_bf16 v[56:59], v[156:159], v[190:193], v[56:59]
	v_mfma_f32_16x16x32_bf16 v[56:59], v[160:163], v[194:197], v[56:59]
	s_setprio 0
	s_setprio 1
	v_mfma_f32_16x16x32_bf16 v[52:55], v[164:167], v[190:193], v[52:55]
	v_mfma_f32_16x16x32_bf16 v[52:55], v[168:171], v[194:197], v[52:55]
	v_mfma_f32_16x16x32_bf16 v[36:39], v[164:167], v[198:201], v[36:39]
	v_mfma_f32_16x16x32_bf16 v[36:39], v[168:171], v[202:205], v[36:39]
	v_mfma_f32_16x16x32_bf16 v[20:23], v[164:167], v[206:209], v[20:23]
	v_mfma_f32_16x16x32_bf16 v[20:23], v[168:171], v[210:213], v[20:23]
	v_mfma_f32_16x16x32_bf16 v[4:7], v[164:167], v[214:217], v[4:7]
	v_mfma_f32_16x16x32_bf16 v[4:7], v[168:171], v[218:221], v[4:7]
	v_mfma_f32_16x16x32_bf16 v[0:3], v[182:185], v[214:217], v[0:3]
	v_mfma_f32_16x16x32_bf16 v[0:3], v[186:189], v[218:221], v[0:3]
	v_mfma_f32_16x16x32_bf16 v[16:19], v[182:185], v[206:209], v[16:19]
	v_mfma_f32_16x16x32_bf16 v[16:19], v[186:189], v[210:213], v[16:19]
	v_mfma_f32_16x16x32_bf16 v[32:35], v[182:185], v[198:201], v[32:35]
	v_mfma_f32_16x16x32_bf16 v[32:35], v[186:189], v[202:205], v[32:35]
	v_mfma_f32_16x16x32_bf16 v[48:51], v[182:185], v[190:193], v[48:51]
	v_mfma_f32_16x16x32_bf16 v[48:51], v[186:189], v[194:197], v[48:51]
	s_setprio 0
	s_barrier
	s_add_i32 s41, 0, 0x18000
	s_add_i32 s50, 0, 0x1c000
	v_add_u32_e32 v160, s41, v173
	v_add_u32_e32 v181, s50, v173
	ds_read_b128 v[128:131], v160
	ds_read_b128 v[132:135], v160 offset:1024
	ds_read_b128 v[156:159], v160 offset:2048
	ds_read_b128 v[160:163], v160 offset:3072
	ds_read_b128 v[164:167], v181
	ds_read_b128 v[168:171], v181 offset:1024
	ds_read_b128 v[182:185], v181 offset:2048
	ds_read_b128 v[186:189], v181 offset:3072
	s_add_u32 s8, s12, 0x110000
	s_addc_u32 s9, s13, 0
	s_mov_b32 m0, s63
	v_lshl_add_u64 v[228:229], s[8:9], 0, v[142:143]
	ds_read_b128 v[190:193], v176 offset:32768
	ds_read_b128 v[194:197], v176 offset:33792
	ds_read_b128 v[198:201], v176 offset:34816
	ds_read_b128 v[202:205], v176 offset:35840
	ds_read_b128 v[206:209], v176 offset:36864
	ds_read_b128 v[210:213], v176 offset:37888
	ds_read_b128 v[214:217], v176 offset:38912
	ds_read_b128 v[218:221], v176 offset:39936
	global_load_lds_dwordx4 v[228:229], off
	v_lshl_add_u64 v[228:229], s[8:9], 0, v[138:139]
	s_mov_b32 m0, s64
	s_nop 0
	global_load_lds_dwordx4 v[228:229], off
	s_waitcnt vmcnt(8)
	s_waitcnt lgkmcnt(0)
	s_setprio 1
	s_barrier
	v_mfma_f32_16x16x32_bf16 v[120:123], v[128:131], v[190:193], v[120:123]
	v_mfma_f32_16x16x32_bf16 v[120:123], v[132:135], v[194:197], v[120:123]
	v_mfma_f32_16x16x32_bf16 v[108:111], v[128:131], v[198:201], v[108:111]
	v_mfma_f32_16x16x32_bf16 v[108:111], v[132:135], v[202:205], v[108:111]
	v_mfma_f32_16x16x32_bf16 v[92:95], v[128:131], v[206:209], v[92:95]
	v_mfma_f32_16x16x32_bf16 v[92:95], v[132:135], v[210:213], v[92:95]
	v_mfma_f32_16x16x32_bf16 v[76:79], v[128:131], v[214:217], v[76:79]
	v_mfma_f32_16x16x32_bf16 v[76:79], v[132:135], v[218:221], v[76:79]
	v_mfma_f32_16x16x32_bf16 v[72:75], v[156:159], v[214:217], v[72:75]
	v_mfma_f32_16x16x32_bf16 v[72:75], v[160:163], v[218:221], v[72:75]
	v_mfma_f32_16x16x32_bf16 v[88:91], v[156:159], v[206:209], v[88:91]
	v_mfma_f32_16x16x32_bf16 v[88:91], v[160:163], v[210:213], v[88:91]
	v_mfma_f32_16x16x32_bf16 v[104:107], v[156:159], v[198:201], v[104:107]
	v_mfma_f32_16x16x32_bf16 v[104:107], v[160:163], v[202:205], v[104:107]
	v_mfma_f32_16x16x32_bf16 v[124:127], v[156:159], v[190:193], v[124:127]
	v_mfma_f32_16x16x32_bf16 v[124:127], v[160:163], v[194:197], v[124:127]
	s_setprio 0
	s_setprio 1
	v_mfma_f32_16x16x32_bf16 v[116:119], v[164:167], v[190:193], v[116:119]
	v_mfma_f32_16x16x32_bf16 v[116:119], v[168:171], v[194:197], v[116:119]
	v_mfma_f32_16x16x32_bf16 v[100:103], v[164:167], v[198:201], v[100:103]
	v_mfma_f32_16x16x32_bf16 v[100:103], v[168:171], v[202:205], v[100:103]
	v_mfma_f32_16x16x32_bf16 v[84:87], v[164:167], v[206:209], v[84:87]
	v_mfma_f32_16x16x32_bf16 v[84:87], v[168:171], v[210:213], v[84:87]
	v_mfma_f32_16x16x32_bf16 v[68:71], v[164:167], v[214:217], v[68:71]
	v_mfma_f32_16x16x32_bf16 v[68:71], v[168:171], v[218:221], v[68:71]
	v_mfma_f32_16x16x32_bf16 v[64:67], v[182:185], v[214:217], v[64:67]
	v_mfma_f32_16x16x32_bf16 v[64:67], v[186:189], v[218:221], v[64:67]
	v_mfma_f32_16x16x32_bf16 v[80:83], v[182:185], v[206:209], v[80:83]
	v_mfma_f32_16x16x32_bf16 v[80:83], v[186:189], v[210:213], v[80:83]
	v_mfma_f32_16x16x32_bf16 v[96:99], v[182:185], v[198:201], v[96:99]
	v_mfma_f32_16x16x32_bf16 v[96:99], v[186:189], v[202:205], v[96:99]
	v_mfma_f32_16x16x32_bf16 v[112:115], v[182:185], v[190:193], v[112:115]
	v_mfma_f32_16x16x32_bf16 v[112:115], v[186:189], v[194:197], v[112:115]
	s_setprio 0
	s_barrier
; #define PG8_STAGE(bufoff, gbase, voff) do { _Pragma("unroll") for (int _i = 0; _i < 2; ++_i) \
;         __builtin_amdgcn_global_load_lds((const unsigned*)((const char*)(gbase) + (voff)[_i]), (LAS unsigned*)(lds + (bufoff) + ldsw + _i * 8192), 16, 0, 0); } while (0)
; #define PG8_LDA(dst, b, h) do { _Pragma("unroll") for (int m = 0; m < 4; ++m) _Pragma("unroll") for (int k = 0; k < 2; ++k) dst[m][k] = *(const LAS bf16x8*)(lds + PG8_SA(b, h) + aoff + m * 2048 + k * 1024); } while (0)
; #define PG8_MMA(ai, bj, At, Bt) do { __builtin_amdgcn_s_setprio(1); _Pragma("unroll") for (int m = 0; m < 4; ++m) _Pragma("unroll") for (int n = 0; n < 2; ++n) _Pragma("unroll") for (int k = 0; k < 2; ++k) \
;         acc[ai][bj][m][n] = __builtin_amdgcn_mfma_f32_16x16x32_bf16(Bt[n][k], At[m][k], acc[ai][bj][m][n], 0, 0, 0); __builtin_amdgcn_s_setprio(0); } while (0)
; #define PG8_WAIT_V(n) asm volatile("s_waitcnt vmcnt(" #n ")" ::: "memory")
; #define PG8_WAIT_L(n) asm volatile("s_waitcnt lgkmcnt(" #n ")" ::: "memory")
; #define PG8_BAR __builtin_amdgcn_s_barrier()
; #define PG8_SCHED __builtin_amdgcn_sched_barrier(0)
; template <class Epi>
; DI void gemm_phase(LAS unsigned char* lds, const Gemm g, const StaticOrder& S, const Epi& E) {
;     ...
;             PG8_LDA(At, 1, 1); PG8_STAGE(PG8_SB(1, 0), b3, voffB); PG8_STAGE(PG8_SB(1, 1), b3 + hstepB, voffB); PG8_STAGE(PG8_SA(1, 0), a3, voffA);
;             PG8_WAIT_V(8); PG8_WAIT_L(0); PG8_BAR; PG8_MMA(1, 0, At, B0); PG8_MMA(1, 1, At, B1); PG8_BAR; PG8_SCHED;
;         }
	s_add_i32 s8, s41, s59
	v_lshl_add_u64 v[178:179], v[178:179], 0, s[28:29]
	s_mov_b32 m0, s8
	ds_read_b128 v[190:193], v176 offset:49152
	ds_read_b128 v[194:197], v176 offset:50176
	ds_read_b128 v[198:201], v176 offset:51200
	ds_read_b128 v[202:205], v176 offset:52224
	ds_read_b128 v[206:209], v176 offset:53248
	ds_read_b128 v[210:213], v176 offset:54272
	ds_read_b128 v[214:217], v176 offset:55296
	ds_read_b128 v[218:221], v176 offset:56320
	global_load_lds_dwordx4 v[178:179], off
	s_add_i32 m0, s8, 0x2000
	s_add_u32 s8, s10, 0x40080
	v_lshl_add_u64 v[178:179], v[222:223], 0, s[28:29]
	s_addc_u32 s9, s11, 0
	s_add_i32 s10, s50, s59
	global_load_lds_dwordx4 v[178:179], off
	v_lshl_add_u64 v[178:179], s[8:9], 0, v[140:141]
	s_mov_b32 m0, s10
	s_nop 0
	global_load_lds_dwordx4 v[178:179], off
	v_lshl_add_u64 v[178:179], s[8:9], 0, v[136:137]
	s_add_i32 m0, s10, 0x2000
	s_nop 0
	global_load_lds_dwordx4 v[178:179], off
	v_lshl_add_u64 v[178:179], v[224:225], 0, s[28:29]
	s_mov_b32 m0, s66
	s_nop 0
	global_load_lds_dwordx4 v[178:179], off
	v_lshl_add_u64 v[178:179], v[226:227], 0, s[28:29]
	s_mov_b32 m0, s67
	s_nop 0
	global_load_lds_dwordx4 v[178:179], off
	s_waitcnt vmcnt(8)
	s_waitcnt lgkmcnt(0)
	s_setprio 1
	s_barrier
	v_mfma_f32_16x16x32_bf16 v[60:63], v[128:131], v[190:193], v[60:63]
	v_mfma_f32_16x16x32_bf16 v[60:63], v[132:135], v[194:197], v[60:63]
	v_mfma_f32_16x16x32_bf16 v[44:47], v[128:131], v[198:201], v[44:47]
	v_mfma_f32_16x16x32_bf16 v[44:47], v[132:135], v[202:205], v[44:47]
	v_mfma_f32_16x16x32_bf16 v[28:31], v[128:131], v[206:209], v[28:31]
	v_mfma_f32_16x16x32_bf16 v[28:31], v[132:135], v[210:213], v[28:31]
	v_mfma_f32_16x16x32_bf16 v[12:15], v[128:131], v[214:217], v[12:15]
	v_mfma_f32_16x16x32_bf16 v[12:15], v[132:135], v[218:221], v[12:15]
	v_mfma_f32_16x16x32_bf16 v[8:11], v[156:159], v[214:217], v[8:11]
	v_mfma_f32_16x16x32_bf16 v[8:11], v[160:163], v[218:221], v[8:11]
	v_mfma_f32_16x16x32_bf16 v[24:27], v[156:159], v[206:209], v[24:27]
	v_mfma_f32_16x16x32_bf16 v[24:27], v[160:163], v[210:213], v[24:27]
	v_mfma_f32_16x16x32_bf16 v[40:43], v[156:159], v[198:201], v[40:43]
	v_mfma_f32_16x16x32_bf16 v[40:43], v[160:163], v[202:205], v[40:43]
	v_mfma_f32_16x16x32_bf16 v[56:59], v[156:159], v[190:193], v[56:59]
	v_mfma_f32_16x16x32_bf16 v[56:59], v[160:163], v[194:197], v[56:59]
	s_setprio 0
	s_setprio 1
	v_mfma_f32_16x16x32_bf16 v[52:55], v[164:167], v[190:193], v[52:55]
	v_mfma_f32_16x16x32_bf16 v[52:55], v[168:171], v[194:197], v[52:55]
	v_mfma_f32_16x16x32_bf16 v[36:39], v[164:167], v[198:201], v[36:39]
	v_mfma_f32_16x16x32_bf16 v[36:39], v[168:171], v[202:205], v[36:39]
	v_mfma_f32_16x16x32_bf16 v[20:23], v[164:167], v[206:209], v[20:23]
	v_mfma_f32_16x16x32_bf16 v[20:23], v[168:171], v[210:213], v[20:23]
	v_mfma_f32_16x16x32_bf16 v[4:7], v[164:167], v[214:217], v[4:7]
	v_mfma_f32_16x16x32_bf16 v[4:7], v[168:171], v[218:221], v[4:7]
	v_mfma_f32_16x16x32_bf16 v[0:3], v[182:185], v[214:217], v[0:3]
	v_mfma_f32_16x16x32_bf16 v[0:3], v[186:189], v[218:221], v[0:3]
	v_mfma_f32_16x16x32_bf16 v[16:19], v[182:185], v[206:209], v[16:19]
	v_mfma_f32_16x16x32_bf16 v[16:19], v[186:189], v[210:213], v[16:19]
	v_mfma_f32_16x16x32_bf16 v[32:35], v[182:185], v[198:201], v[32:35]
	v_mfma_f32_16x16x32_bf16 v[32:35], v[186:189], v[202:205], v[32:35]
	v_mfma_f32_16x16x32_bf16 v[48:51], v[182:185], v[190:193], v[48:51]
	v_mfma_f32_16x16x32_bf16 v[48:51], v[186:189], v[194:197], v[48:51]
	s_setprio 0
	s_barrier
	s_add_u32 s18, s18, 0x100
	s_addc_u32 s19, s19, 0
	s_cmp_ge_i32 s30, s65
	s_mov_b64 s[8:9], s[6:7]
	s_mov_b32 s10, s30
	s_cbranch_scc0 .LBB0_302

; #define PG8_STAGE(bufoff, gbase, voff) do { _Pragma("unroll") for (int _i = 0; _i < 2; ++_i) \
;         __builtin_amdgcn_global_load_lds((const unsigned*)((const char*)(gbase) + (voff)[_i]), (LAS unsigned*)(lds + (bufoff) + ldsw + _i * 8192), 16, 0, 0); } while (0)
; #define PG8_LDA(dst, b, h) do { _Pragma("unroll") for (int m = 0; m < 4; ++m) _Pragma("unroll") for (int k = 0; k < 2; ++k) dst[m][k] = *(const LAS bf16x8*)(lds + PG8_SA(b, h) + aoff + m * 2048 + k * 1024); } while (0)
; #define PG8_LDB(dst, b, h) do { _Pragma("unroll") for (int n = 0; n < 2; ++n) _Pragma("unroll") for (int k = 0; k < 2; ++k) dst[n][k] = *(const LAS bf16x8*)(lds + PG8_SB(b, h) + boff + n * 2048 + k * 1024); } while (0)
; #define PG8_MMA(ai, bj, At, Bt) do { __builtin_amdgcn_s_setprio(1); _Pragma("unroll") for (int m = 0; m < 4; ++m) _Pragma("unroll") for (int n = 0; n < 2; ++n) _Pragma("unroll") for (int k = 0; k < 2; ++k) \
;         acc[ai][bj][m][n] = __builtin_amdgcn_mfma_f32_16x16x32_bf16(Bt[n][k], At[m][k], acc[ai][bj][m][n], 0, 0, 0); __builtin_amdgcn_s_setprio(0); } while (0)
; #define PG8_WAIT_V(n) asm volatile("s_waitcnt vmcnt(" #n ")" ::: "memory")
; #define PG8_WAIT_L(n) asm volatile("s_waitcnt lgkmcnt(" #n ")" ::: "memory")
; #define PG8_BAR __builtin_amdgcn_s_barrier()
; #define PG8_SCHED __builtin_amdgcn_sched_barrier(0)
; template <class Epi>
; DI void gemm_phase(LAS unsigned char* lds, const Gemm g, const StaticOrder& S, const Epi& E) {
;     ...
;             const bool last = (t == nt - 2);
;             const char* a1 = cA + (size_t)(t + 1) * kstep;
;             const char* a2 = last ? nA : cA + (size_t)(t + 2) * kstep; const char* b2 = last ? nB : cB + (size_t)(t + 2) * kstep;
;             const char* a3 = a2 + kstep; const char* b3 = b2 + kstep;
;             PG8_LDB(B0, 0, 0); PG8_LDB(B1, 0, 1); PG8_SCHED; PG8_LDA(At, 0, 0); PG8_STAGE(PG8_SA(1, 1), a1 + hstepA, voffA);
;             PG8_WAIT_V(8); PG8_WAIT_L(0); PG8_BAR; PG8_MMA(0, 0, At, B0); PG8_MMA(0, 1, At, B1); PG8_BAR; PG8_SCHED;
;             PG8_LDA(At, 0, 1); PG8_STAGE(PG8_SB(0, 0), b2, voffB); PG8_STAGE(PG8_SB(0, 1), b2 + hstepB, voffB); PG8_STAGE(PG8_SA(0, 0), a2, voffA);
;             PG8_WAIT_V(8); PG8_WAIT_L(0); PG8_BAR; PG8_MMA(1, 0, At, B0); PG8_MMA(1, 1, At, B1); PG8_BAR; PG8_SCHED;
.LBB0_329:
	ds_read_b128 v[154:157], v150
	ds_read_b128 v[158:161], v150 offset:1024
	ds_read_b128 v[162:165], v150 offset:2048
	ds_read_b128 v[166:169], v150 offset:3072
	ds_read_b128 v[170:173], v151
	ds_read_b128 v[174:177], v151 offset:1024
	ds_read_b128 v[182:185], v151 offset:2048
	ds_read_b128 v[186:189], v151 offset:3072
	s_add_i32 s73, s30, 2
	s_add_u32 s6, s8, 0x100
	s_addc_u32 s7, s9, 0
	s_cmp_eq_u32 s62, s30
	s_cselect_b32 s30, s70, s71
	s_cselect_b32 s39, s27, s7
	s_cselect_b32 s38, s26, s6
	s_cselect_b32 s31, s25, s72
	v_lshl_add_u64 v[146:147], s[8:9], 0, v[138:139]
	s_add_i32 m0, s47, 0xc000
	ds_read_b128 v[190:193], v152
	ds_read_b128 v[194:197], v152 offset:1024
	ds_read_b128 v[198:201], v152 offset:2048
	ds_read_b128 v[202:205], v152 offset:3072
	ds_read_b128 v[206:209], v152 offset:4096
	ds_read_b128 v[210:213], v152 offset:5120
	ds_read_b128 v[214:217], v152 offset:6144
	ds_read_b128 v[218:221], v152 offset:7168
	global_load_lds_dwordx4 v[146:147], off
	v_lshl_add_u64 v[146:147], s[8:9], 0, v[140:141]
	s_add_i32 m0, s47, 0xe000
	s_nop 0
	global_load_lds_dwordx4 v[146:147], off
	s_waitcnt vmcnt(8)
	s_waitcnt lgkmcnt(0)
	s_setprio 1
	s_barrier
	v_mfma_f32_16x16x32_bf16 v[120:123], v[154:157], v[190:193], v[120:123]
	v_mfma_f32_16x16x32_bf16 v[120:123], v[158:161], v[194:197], v[120:123]
	v_mfma_f32_16x16x32_bf16 v[108:111], v[154:157], v[198:201], v[108:111]
	v_mfma_f32_16x16x32_bf16 v[108:111], v[158:161], v[202:205], v[108:111]
	v_mfma_f32_16x16x32_bf16 v[92:95], v[154:157], v[206:209], v[92:95]
	v_mfma_f32_16x16x32_bf16 v[92:95], v[158:161], v[210:213], v[92:95]
	v_mfma_f32_16x16x32_bf16 v[76:79], v[154:157], v[214:217], v[76:79]
	v_mfma_f32_16x16x32_bf16 v[76:79], v[158:161], v[218:221], v[76:79]
	v_mfma_f32_16x16x32_bf16 v[72:75], v[162:165], v[214:217], v[72:75]
	v_mfma_f32_16x16x32_bf16 v[72:75], v[166:169], v[218:221], v[72:75]
	v_mfma_f32_16x16x32_bf16 v[88:91], v[162:165], v[206:209], v[88:91]
	v_mfma_f32_16x16x32_bf16 v[88:91], v[166:169], v[210:213], v[88:91]
	v_mfma_f32_16x16x32_bf16 v[104:107], v[162:165], v[198:201], v[104:107]
	v_mfma_f32_16x16x32_bf16 v[104:107], v[166:169], v[202:205], v[104:107]
	v_mfma_f32_16x16x32_bf16 v[124:127], v[162:165], v[190:193], v[124:127]
	v_mfma_f32_16x16x32_bf16 v[124:127], v[166:169], v[194:197], v[124:127]
	s_setprio 0
	s_setprio 1
	v_mfma_f32_16x16x32_bf16 v[116:119], v[170:173], v[190:193], v[116:119]
	v_mfma_f32_16x16x32_bf16 v[116:119], v[174:177], v[194:197], v[116:119]
	v_mfma_f32_16x16x32_bf16 v[100:103], v[170:173], v[198:201], v[100:103]
	v_mfma_f32_16x16x32_bf16 v[100:103], v[174:177], v[202:205], v[100:103]
	v_mfma_f32_16x16x32_bf16 v[84:87], v[170:173], v[206:209], v[84:87]
	v_mfma_f32_16x16x32_bf16 v[84:87], v[174:177], v[210:213], v[84:87]
	v_mfma_f32_16x16x32_bf16 v[68:71], v[170:173], v[214:217], v[68:71]
	v_mfma_f32_16x16x32_bf16 v[68:71], v[174:177], v[218:221], v[68:71]
	v_mfma_f32_16x16x32_bf16 v[64:67], v[182:185], v[214:217], v[64:67]
	v_mfma_f32_16x16x32_bf16 v[64:67], v[186:189], v[218:221], v[64:67]
	v_mfma_f32_16x16x32_bf16 v[80:83], v[182:185], v[206:209], v[80:83]
	v_mfma_f32_16x16x32_bf16 v[80:83], v[186:189], v[210:213], v[80:83]
	v_mfma_f32_16x16x32_bf16 v[96:99], v[182:185], v[198:201], v[96:99]
	v_mfma_f32_16x16x32_bf16 v[96:99], v[186:189], v[202:205], v[96:99]
	v_mfma_f32_16x16x32_bf16 v[112:115], v[182:185], v[190:193], v[112:115]
	v_mfma_f32_16x16x32_bf16 v[112:115], v[186:189], v[194:197], v[112:115]
	s_setprio 0
	s_barrier
	s_add_i32 s8, s63, s41
	v_lshl_add_u64 v[146:147], s[30:31], 0, v[132:133]
	s_mov_b32 m0, s8
	ds_read_b128 v[190:193], v152 offset:16384
	ds_read_b128 v[194:197], v152 offset:17408
	ds_read_b128 v[198:201], v152 offset:18432
	ds_read_b128 v[202:205], v152 offset:19456
	ds_read_b128 v[206:209], v152 offset:20480
	ds_read_b128 v[210:213], v152 offset:21504
	ds_read_b128 v[214:217], v152 offset:22528
	ds_read_b128 v[218:221], v152 offset:23552
	global_load_lds_dwordx4 v[146:147], off
	s_add_i32 m0, s8, 0x2000
	s_add_u32 s8, s30, 0x20000
	v_lshl_add_u64 v[178:179], s[30:31], 0, v[128:129]
	s_addc_u32 s9, s31, 0
	s_add_i32 s74, s64, s41
	global_load_lds_dwordx4 v[178:179], off
	v_lshl_add_u64 v[222:223], s[8:9], 0, v[132:133]
	s_mov_b32 m0, s74
	v_lshl_add_u64 v[224:225], s[38:39], 0, v[130:131]
	global_load_lds_dwordx4 v[222:223], off
	v_lshl_add_u64 v[222:223], s[8:9], 0, v[128:129]
	s_add_i32 m0, s74, 0x2000
	s_nop 0
	global_load_lds_dwordx4 v[222:223], off
	v_lshl_add_u64 v[222:223], s[38:39], 0, v[134:135]
	s_mov_b32 m0, s47
	s_nop 0
	global_load_lds_dwordx4 v[222:223], off
	s_mov_b32 m0, s50
	s_nop 0
	global_load_lds_dwordx4 v[224:225], off
	s_waitcnt vmcnt(8)
	s_waitcnt lgkmcnt(0)
	s_setprio 1
	s_barrier
; #define PG8_STAGE(bufoff, gbase, voff) do { _Pragma("unroll") for (int _i = 0; _i < 2; ++_i) \
;         __builtin_amdgcn_global_load_lds((const unsigned*)((const char*)(gbase) + (voff)[_i]), (LAS unsigned*)(lds + (bufoff) + ldsw + _i * 8192), 16, 0, 0); } while (0)
; #define PG8_LDA(dst, b, h) do { _Pragma("unroll") for (int m = 0; m < 4; ++m) _Pragma("unroll") for (int k = 0; k < 2; ++k) dst[m][k] = *(const LAS bf16x8*)(lds + PG8_SA(b, h) + aoff + m * 2048 + k * 1024); } while (0)
; #define PG8_LDB(dst, b, h) do { _Pragma("unroll") for (int n = 0; n < 2; ++n) _Pragma("unroll") for (int k = 0; k < 2; ++k) dst[n][k] = *(const LAS bf16x8*)(lds + PG8_SB(b, h) + boff + n * 2048 + k * 1024); } while (0)
; #define PG8_MMA(ai, bj, At, Bt) do { __builtin_amdgcn_s_setprio(1); _Pragma("unroll") for (int m = 0; m < 4; ++m) _Pragma("unroll") for (int n = 0; n < 2; ++n) _Pragma("unroll") for (int k = 0; k < 2; ++k) \
;         acc[ai][bj][m][n] = __builtin_amdgcn_mfma_f32_16x16x32_bf16(Bt[n][k], At[m][k], acc[ai][bj][m][n], 0, 0, 0); __builtin_amdgcn_s_setprio(0); } while (0)
; #define PG8_WAIT_V(n) asm volatile("s_waitcnt vmcnt(" #n ")" ::: "memory")
; #define PG8_WAIT_L(n) asm volatile("s_waitcnt lgkmcnt(" #n ")" ::: "memory")
; #define PG8_BAR __builtin_amdgcn_s_barrier()
; #define PG8_SCHED __builtin_amdgcn_sched_barrier(0)
; template <class Epi>
; DI void gemm_phase(LAS unsigned char* lds, const Gemm g, const StaticOrder& S, const Epi& E) {
;     ...
;             PG8_WAIT_V(8); PG8_WAIT_L(0); PG8_BAR; PG8_MMA(1, 0, At, B0); PG8_MMA(1, 1, At, B1); PG8_BAR; PG8_SCHED;
;             PG8_LDB(B0, 1, 0); PG8_LDB(B1, 1, 1); PG8_SCHED; PG8_LDA(At, 1, 0); PG8_STAGE(PG8_SA(0, 1), a2 + hstepA, voffA);
;             PG8_WAIT_V(8); PG8_WAIT_L(0); PG8_BAR; PG8_MMA(0, 0, At, B0); PG8_MMA(0, 1, At, B1); PG8_BAR; PG8_SCHED;
	v_mfma_f32_16x16x32_bf16 v[60:63], v[154:157], v[190:193], v[60:63]
	v_mfma_f32_16x16x32_bf16 v[60:63], v[158:161], v[194:197], v[60:63]
	v_mfma_f32_16x16x32_bf16 v[44:47], v[154:157], v[198:201], v[44:47]
	v_mfma_f32_16x16x32_bf16 v[44:47], v[158:161], v[202:205], v[44:47]
	v_mfma_f32_16x16x32_bf16 v[28:31], v[154:157], v[206:209], v[28:31]
	v_mfma_f32_16x16x32_bf16 v[28:31], v[158:161], v[210:213], v[28:31]
	v_mfma_f32_16x16x32_bf16 v[12:15], v[154:157], v[214:217], v[12:15]
	v_mfma_f32_16x16x32_bf16 v[12:15], v[158:161], v[218:221], v[12:15]
	v_mfma_f32_16x16x32_bf16 v[8:11], v[162:165], v[214:217], v[8:11]
	v_mfma_f32_16x16x32_bf16 v[8:11], v[166:169], v[218:221], v[8:11]
	v_mfma_f32_16x16x32_bf16 v[24:27], v[162:165], v[206:209], v[24:27]
	v_mfma_f32_16x16x32_bf16 v[24:27], v[166:169], v[210:213], v[24:27]
	v_mfma_f32_16x16x32_bf16 v[40:43], v[162:165], v[198:201], v[40:43]
	v_mfma_f32_16x16x32_bf16 v[40:43], v[166:169], v[202:205], v[40:43]
	v_mfma_f32_16x16x32_bf16 v[56:59], v[162:165], v[190:193], v[56:59]
	v_mfma_f32_16x16x32_bf16 v[56:59], v[166:169], v[194:197], v[56:59]
	s_setprio 0
	s_setprio 1
	v_mfma_f32_16x16x32_bf16 v[52:55], v[170:173], v[190:193], v[52:55]
	v_mfma_f32_16x16x32_bf16 v[52:55], v[174:177], v[194:197], v[52:55]
	v_mfma_f32_16x16x32_bf16 v[36:39], v[170:173], v[198:201], v[36:39]
	v_mfma_f32_16x16x32_bf16 v[36:39], v[174:177], v[202:205], v[36:39]
	v_mfma_f32_16x16x32_bf16 v[20:23], v[170:173], v[206:209], v[20:23]
	v_mfma_f32_16x16x32_bf16 v[20:23], v[174:177], v[210:213], v[20:23]
	v_mfma_f32_16x16x32_bf16 v[4:7], v[170:173], v[214:217], v[4:7]
	v_mfma_f32_16x16x32_bf16 v[4:7], v[174:177], v[218:221], v[4:7]
	v_mfma_f32_16x16x32_bf16 v[0:3], v[182:185], v[214:217], v[0:3]
	v_mfma_f32_16x16x32_bf16 v[0:3], v[186:189], v[218:221], v[0:3]
	v_mfma_f32_16x16x32_bf16 v[16:19], v[182:185], v[206:209], v[16:19]
	v_mfma_f32_16x16x32_bf16 v[16:19], v[186:189], v[210:213], v[16:19]
	v_mfma_f32_16x16x32_bf16 v[32:35], v[182:185], v[198:201], v[32:35]
	v_mfma_f32_16x16x32_bf16 v[32:35], v[186:189], v[202:205], v[32:35]
	v_mfma_f32_16x16x32_bf16 v[48:51], v[182:185], v[190:193], v[48:51]
	v_mfma_f32_16x16x32_bf16 v[48:51], v[186:189], v[194:197], v[48:51]
	s_setprio 0
	s_barrier
	s_add_i32 s74, 0, 0x18000
	s_add_i32 s75, 0, 0x1c000
	v_add_u32_e32 v166, s74, v149
	v_add_u32_e32 v181, s75, v149
	ds_read_b128 v[154:157], v166
	ds_read_b128 v[158:161], v166 offset:1024
	ds_read_b128 v[162:165], v166 offset:2048
	ds_read_b128 v[166:169], v166 offset:3072
	ds_read_b128 v[170:173], v181
	ds_read_b128 v[174:177], v181 offset:1024
	ds_read_b128 v[182:185], v181 offset:2048
	ds_read_b128 v[186:189], v181 offset:3072
	s_add_u32 s8, s38, 0x110000
	s_addc_u32 s9, s39, 0
	s_mov_b32 m0, s51
	v_lshl_add_u64 v[226:227], s[8:9], 0, v[134:135]
	ds_read_b128 v[190:193], v152 offset:32768
	ds_read_b128 v[194:197], v152 offset:33792
	ds_read_b128 v[198:201], v152 offset:34816
	ds_read_b128 v[202:205], v152 offset:35840
	ds_read_b128 v[206:209], v152 offset:36864
	ds_read_b128 v[210:213], v152 offset:37888
	ds_read_b128 v[214:217], v152 offset:38912
	ds_read_b128 v[218:221], v152 offset:39936
	global_load_lds_dwordx4 v[226:227], off
	v_lshl_add_u64 v[226:227], s[8:9], 0, v[130:131]
	s_mov_b32 m0, s56
	s_nop 0
	global_load_lds_dwordx4 v[226:227], off
	s_waitcnt vmcnt(8)
	s_waitcnt lgkmcnt(0)
	s_setprio 1
	s_barrier
	v_mfma_f32_16x16x32_bf16 v[120:123], v[154:157], v[190:193], v[120:123]
	v_mfma_f32_16x16x32_bf16 v[120:123], v[158:161], v[194:197], v[120:123]
	v_mfma_f32_16x16x32_bf16 v[108:111], v[154:157], v[198:201], v[108:111]
	v_mfma_f32_16x16x32_bf16 v[108:111], v[158:161], v[202:205], v[108:111]
	v_mfma_f32_16x16x32_bf16 v[92:95], v[154:157], v[206:209], v[92:95]
	v_mfma_f32_16x16x32_bf16 v[92:95], v[158:161], v[210:213], v[92:95]
	v_mfma_f32_16x16x32_bf16 v[76:79], v[154:157], v[214:217], v[76:79]
	v_mfma_f32_16x16x32_bf16 v[76:79], v[158:161], v[218:221], v[76:79]
	v_mfma_f32_16x16x32_bf16 v[72:75], v[162:165], v[214:217], v[72:75]
	v_mfma_f32_16x16x32_bf16 v[72:75], v[166:169], v[218:221], v[72:75]
	v_mfma_f32_16x16x32_bf16 v[88:91], v[162:165], v[206:209], v[88:91]
	v_mfma_f32_16x16x32_bf16 v[88:91], v[166:169], v[210:213], v[88:91]
	v_mfma_f32_16x16x32_bf16 v[104:107], v[162:165], v[198:201], v[104:107]
	v_mfma_f32_16x16x32_bf16 v[104:107], v[166:169], v[202:205], v[104:107]
	v_mfma_f32_16x16x32_bf16 v[124:127], v[162:165], v[190:193], v[124:127]
	v_mfma_f32_16x16x32_bf16 v[124:127], v[166:169], v[194:197], v[124:127]
	s_setprio 0
	s_setprio 1
	v_mfma_f32_16x16x32_bf16 v[116:119], v[170:173], v[190:193], v[116:119]
	v_mfma_f32_16x16x32_bf16 v[116:119], v[174:177], v[194:197], v[116:119]
	v_mfma_f32_16x16x32_bf16 v[100:103], v[170:173], v[198:201], v[100:103]
	v_mfma_f32_16x16x32_bf16 v[100:103], v[174:177], v[202:205], v[100:103]
	v_mfma_f32_16x16x32_bf16 v[84:87], v[170:173], v[206:209], v[84:87]
	v_mfma_f32_16x16x32_bf16 v[84:87], v[174:177], v[210:213], v[84:87]
	v_mfma_f32_16x16x32_bf16 v[68:71], v[170:173], v[214:217], v[68:71]
	v_mfma_f32_16x16x32_bf16 v[68:71], v[174:177], v[218:221], v[68:71]
	v_mfma_f32_16x16x32_bf16 v[64:67], v[182:185], v[214:217], v[64:67]
	v_mfma_f32_16x16x32_bf16 v[64:67], v[186:189], v[218:221], v[64:67]
	v_mfma_f32_16x16x32_bf16 v[80:83], v[182:185], v[206:209], v[80:83]
	v_mfma_f32_16x16x32_bf16 v[80:83], v[186:189], v[210:213], v[80:83]
	v_mfma_f32_16x16x32_bf16 v[96:99], v[182:185], v[198:201], v[96:99]
	v_mfma_f32_16x16x32_bf16 v[96:99], v[186:189], v[202:205], v[96:99]
	v_mfma_f32_16x16x32_bf16 v[112:115], v[182:185], v[190:193], v[112:115]
	v_mfma_f32_16x16x32_bf16 v[112:115], v[186:189], v[194:197], v[112:115]
	s_setprio 0
	s_barrier
; #define PG8_STAGE(bufoff, gbase, voff) do { _Pragma("unroll") for (int _i = 0; _i < 2; ++_i) \
;         __builtin_amdgcn_global_load_lds((const unsigned*)((const char*)(gbase) + (voff)[_i]), (LAS unsigned*)(lds + (bufoff) + ldsw + _i * 8192), 16, 0, 0); } while (0)
; #define PG8_LDA(dst, b, h) do { _Pragma("unroll") for (int m = 0; m < 4; ++m) _Pragma("unroll") for (int k = 0; k < 2; ++k) dst[m][k] = *(const LAS bf16x8*)(lds + PG8_SA(b, h) + aoff + m * 2048 + k * 1024); } while (0)
; #define PG8_MMA(ai, bj, At, Bt) do { __builtin_amdgcn_s_setprio(1); _Pragma("unroll") for (int m = 0; m < 4; ++m) _Pragma("unroll") for (int n = 0; n < 2; ++n) _Pragma("unroll") for (int k = 0; k < 2; ++k) \
;         acc[ai][bj][m][n] = __builtin_amdgcn_mfma_f32_16x16x32_bf16(Bt[n][k], At[m][k], acc[ai][bj][m][n], 0, 0, 0); __builtin_amdgcn_s_setprio(0); } while (0)
; #define PG8_WAIT_V(n) asm volatile("s_waitcnt vmcnt(" #n ")" ::: "memory")
; #define PG8_WAIT_L(n) asm volatile("s_waitcnt lgkmcnt(" #n ")" ::: "memory")
; #define PG8_BAR __builtin_amdgcn_s_barrier()
; #define PG8_SCHED __builtin_amdgcn_sched_barrier(0)
; template <class Epi>
; DI void gemm_phase(LAS unsigned char* lds, const Gemm g, const StaticOrder& S, const Epi& E) {
;     ...
;             PG8_LDA(At, 1, 1); PG8_STAGE(PG8_SB(1, 0), b3, voffB); PG8_STAGE(PG8_SB(1, 1), b3 + hstepB, voffB); PG8_STAGE(PG8_SA(1, 0), a3, voffA);
;             PG8_WAIT_V(8); PG8_WAIT_L(0); PG8_BAR; PG8_MMA(1, 0, At, B0); PG8_MMA(1, 1, At, B1); PG8_BAR; PG8_SCHED;
;         }
	s_add_i32 s8, s74, s41
	v_lshl_add_u64 v[146:147], v[146:147], 0, s[16:17]
	s_mov_b32 m0, s8
	ds_read_b128 v[190:193], v152 offset:49152
	ds_read_b128 v[194:197], v152 offset:50176
	ds_read_b128 v[198:201], v152 offset:51200
	ds_read_b128 v[202:205], v152 offset:52224
	ds_read_b128 v[206:209], v152 offset:53248
	ds_read_b128 v[210:213], v152 offset:54272
	ds_read_b128 v[214:217], v152 offset:55296
	ds_read_b128 v[218:221], v152 offset:56320
	global_load_lds_dwordx4 v[146:147], off
	s_add_i32 m0, s8, 0x2000
	s_add_u32 s8, s30, 0x20080
	v_lshl_add_u64 v[146:147], v[178:179], 0, s[16:17]
	s_addc_u32 s9, s31, 0
	s_add_i32 s30, s75, s41
	global_load_lds_dwordx4 v[146:147], off
	v_lshl_add_u64 v[146:147], s[8:9], 0, v[132:133]
	s_mov_b32 m0, s30
	s_nop 0
	global_load_lds_dwordx4 v[146:147], off
	v_lshl_add_u64 v[146:147], s[8:9], 0, v[128:129]
	s_add_i32 m0, s30, 0x2000
	s_nop 0
	global_load_lds_dwordx4 v[146:147], off
	v_lshl_add_u64 v[146:147], v[222:223], 0, s[16:17]
	s_mov_b32 m0, s60
	s_nop 0
	global_load_lds_dwordx4 v[146:147], off
	v_lshl_add_u64 v[146:147], v[224:225], 0, s[16:17]
	s_mov_b32 m0, s61
	s_nop 0
	global_load_lds_dwordx4 v[146:147], off
	s_waitcnt vmcnt(8)
	s_waitcnt lgkmcnt(0)
	s_setprio 1
	s_barrier
	v_mfma_f32_16x16x32_bf16 v[60:63], v[154:157], v[190:193], v[60:63]
	v_mfma_f32_16x16x32_bf16 v[60:63], v[158:161], v[194:197], v[60:63]
	v_mfma_f32_16x16x32_bf16 v[44:47], v[154:157], v[198:201], v[44:47]
	v_mfma_f32_16x16x32_bf16 v[44:47], v[158:161], v[202:205], v[44:47]
	v_mfma_f32_16x16x32_bf16 v[28:31], v[154:157], v[206:209], v[28:31]
	v_mfma_f32_16x16x32_bf16 v[28:31], v[158:161], v[210:213], v[28:31]
	v_mfma_f32_16x16x32_bf16 v[12:15], v[154:157], v[214:217], v[12:15]
	v_mfma_f32_16x16x32_bf16 v[12:15], v[158:161], v[218:221], v[12:15]
	v_mfma_f32_16x16x32_bf16 v[8:11], v[162:165], v[214:217], v[8:11]
	v_mfma_f32_16x16x32_bf16 v[8:11], v[166:169], v[218:221], v[8:11]
	v_mfma_f32_16x16x32_bf16 v[24:27], v[162:165], v[206:209], v[24:27]
	v_mfma_f32_16x16x32_bf16 v[24:27], v[166:169], v[210:213], v[24:27]
	v_mfma_f32_16x16x32_bf16 v[40:43], v[162:165], v[198:201], v[40:43]
	v_mfma_f32_16x16x32_bf16 v[40:43], v[166:169], v[202:205], v[40:43]
	v_mfma_f32_16x16x32_bf16 v[56:59], v[162:165], v[190:193], v[56:59]
	v_mfma_f32_16x16x32_bf16 v[56:59], v[166:169], v[194:197], v[56:59]
	s_setprio 0
	s_setprio 1
	v_mfma_f32_16x16x32_bf16 v[52:55], v[170:173], v[190:193], v[52:55]
	v_mfma_f32_16x16x32_bf16 v[52:55], v[174:177], v[194:197], v[52:55]
	v_mfma_f32_16x16x32_bf16 v[36:39], v[170:173], v[198:201], v[36:39]
	v_mfma_f32_16x16x32_bf16 v[36:39], v[174:177], v[202:205], v[36:39]
	v_mfma_f32_16x16x32_bf16 v[20:23], v[170:173], v[206:209], v[20:23]
	v_mfma_f32_16x16x32_bf16 v[20:23], v[174:177], v[210:213], v[20:23]
	v_mfma_f32_16x16x32_bf16 v[4:7], v[170:173], v[214:217], v[4:7]
	v_mfma_f32_16x16x32_bf16 v[4:7], v[174:177], v[218:221], v[4:7]
	v_mfma_f32_16x16x32_bf16 v[0:3], v[182:185], v[214:217], v[0:3]
	v_mfma_f32_16x16x32_bf16 v[0:3], v[186:189], v[218:221], v[0:3]
	v_mfma_f32_16x16x32_bf16 v[16:19], v[182:185], v[206:209], v[16:19]
	v_mfma_f32_16x16x32_bf16 v[16:19], v[186:189], v[210:213], v[16:19]
	v_mfma_f32_16x16x32_bf16 v[32:35], v[182:185], v[198:201], v[32:35]
	v_mfma_f32_16x16x32_bf16 v[32:35], v[186:189], v[202:205], v[32:35]
	v_mfma_f32_16x16x32_bf16 v[48:51], v[182:185], v[190:193], v[48:51]
	v_mfma_f32_16x16x32_bf16 v[48:51], v[186:189], v[194:197], v[48:51]
	s_setprio 0
	s_barrier
	s_add_u32 s71, s71, 0x100
	s_addc_u32 s72, s72, 0
	s_cmp_ge_i32 s73, s59
	s_mov_b64 s[8:9], s[6:7]
	s_mov_b32 s30, s73
	s_cbranch_scc0 .LBB0_329

; #define PG8_STAGE(bufoff, gbase, voff) do { _Pragma("unroll") for (int _i = 0; _i < 2; ++_i) \
;         __builtin_amdgcn_global_load_lds((const unsigned*)((const char*)(gbase) + (voff)[_i]), (LAS unsigned*)(lds + (bufoff) + ldsw + _i * 8192), 16, 0, 0); } while (0)
; #define PG8_LDA(dst, b, h) do { _Pragma("unroll") for (int m = 0; m < 4; ++m) _Pragma("unroll") for (int k = 0; k < 2; ++k) dst[m][k] = *(const LAS bf16x8*)(lds + PG8_SA(b, h) + aoff + m * 2048 + k * 1024); } while (0)
; #define PG8_LDB(dst, b, h) do { _Pragma("unroll") for (int n = 0; n < 2; ++n) _Pragma("unroll") for (int k = 0; k < 2; ++k) dst[n][k] = *(const LAS bf16x8*)(lds + PG8_SB(b, h) + boff + n * 2048 + k * 1024); } while (0)
; #define PG8_MMA(ai, bj, At, Bt) do { __builtin_amdgcn_s_setprio(1); _Pragma("unroll") for (int m = 0; m < 4; ++m) _Pragma("unroll") for (int n = 0; n < 2; ++n) _Pragma("unroll") for (int k = 0; k < 2; ++k) \
;         acc[ai][bj][m][n] = __builtin_amdgcn_mfma_f32_16x16x32_bf16(Bt[n][k], At[m][k], acc[ai][bj][m][n], 0, 0, 0); __builtin_amdgcn_s_setprio(0); } while (0)
; #define PG8_WAIT_V(n) asm volatile("s_waitcnt vmcnt(" #n ")" ::: "memory")
; #define PG8_WAIT_L(n) asm volatile("s_waitcnt lgkmcnt(" #n ")" ::: "memory")
; #define PG8_BAR __builtin_amdgcn_s_barrier()
; #define PG8_SCHED __builtin_amdgcn_sched_barrier(0)
; template <class Epi>
; DI void gemm_phase(LAS unsigned char* lds, const Gemm g, const StaticOrder& S, const Epi& E) {
;     ...
;             PG8_LDB(B0, 0, 0); PG8_LDB(B1, 0, 1); PG8_SCHED; PG8_LDA(At, 0, 0); PG8_STAGE(PG8_SA(1, 1), a1 + hstepA, voffA);
;             PG8_WAIT_V(8); PG8_WAIT_L(0); PG8_BAR; PG8_MMA(0, 0, At, B0); PG8_MMA(0, 1, At, B1); PG8_BAR; PG8_SCHED;
;             PG8_LDA(At, 0, 1); PG8_STAGE(PG8_SB(0, 0), b2, voffB); PG8_STAGE(PG8_SB(0, 1), b2 + hstepB, voffB); PG8_STAGE(PG8_SA(0, 0), a2, voffA);
;             PG8_WAIT_V(8); PG8_WAIT_L(0); PG8_BAR; PG8_MMA(1, 0, At, B0); PG8_MMA(1, 1, At, B1); PG8_BAR; PG8_SCHED;
.LBB0_352:
	ds_read_b128 v[146:149], v167
	ds_read_b128 v[150:153], v167 offset:1024
	ds_read_b128 v[154:157], v167 offset:2048
	ds_read_b128 v[158:161], v167 offset:3072
	ds_read_b128 v[172:175], v168
	ds_read_b128 v[176:179], v168 offset:1024
	ds_read_b128 v[182:185], v168 offset:2048
	ds_read_b128 v[186:189], v168 offset:3072
	s_add_i32 s16, s8, 2
	s_add_u32 s9, s6, 0xfffe0080
	s_addc_u32 s10, s7, -1
	s_cmp_eq_u32 s76, s8
	s_cselect_b32 s8, s60, s14
	s_cselect_b32 s11, s12, s10
	s_cselect_b32 s10, s13, s9
	s_cselect_b32 s9, s61, s15
	v_lshl_add_u64 v[162:163], s[6:7], 0, v[138:139]
	s_add_i32 m0, s65, 0xc000
	ds_read_b128 v[190:193], v169
	ds_read_b128 v[194:197], v169 offset:1024
	ds_read_b128 v[198:201], v169 offset:2048
	ds_read_b128 v[202:205], v169 offset:3072
	ds_read_b128 v[206:209], v169 offset:4096
	ds_read_b128 v[210:213], v169 offset:5120
	ds_read_b128 v[214:217], v169 offset:6144
	ds_read_b128 v[218:221], v169 offset:7168
	global_load_lds_dwordx4 v[162:163], off
	v_lshl_add_u64 v[162:163], s[6:7], 0, v[140:141]
	s_add_i32 m0, s65, 0xe000
	s_nop 0
	global_load_lds_dwordx4 v[162:163], off
	s_waitcnt vmcnt(8)
	s_waitcnt lgkmcnt(0)
	s_setprio 1
	s_barrier
	v_mfma_f32_16x16x32_bf16 v[124:127], v[146:149], v[190:193], v[124:127]
	v_mfma_f32_16x16x32_bf16 v[124:127], v[150:153], v[194:197], v[124:127]
	v_mfma_f32_16x16x32_bf16 v[108:111], v[146:149], v[198:201], v[108:111]
	v_mfma_f32_16x16x32_bf16 v[108:111], v[150:153], v[202:205], v[108:111]
	v_mfma_f32_16x16x32_bf16 v[92:95], v[146:149], v[206:209], v[92:95]
	v_mfma_f32_16x16x32_bf16 v[92:95], v[150:153], v[210:213], v[92:95]
	v_mfma_f32_16x16x32_bf16 v[76:79], v[146:149], v[214:217], v[76:79]
	v_mfma_f32_16x16x32_bf16 v[76:79], v[150:153], v[218:221], v[76:79]
	v_mfma_f32_16x16x32_bf16 v[72:75], v[154:157], v[214:217], v[72:75]
	v_mfma_f32_16x16x32_bf16 v[72:75], v[158:161], v[218:221], v[72:75]
	v_mfma_f32_16x16x32_bf16 v[88:91], v[154:157], v[206:209], v[88:91]
	v_mfma_f32_16x16x32_bf16 v[88:91], v[158:161], v[210:213], v[88:91]
	v_mfma_f32_16x16x32_bf16 v[104:107], v[154:157], v[198:201], v[104:107]
	v_mfma_f32_16x16x32_bf16 v[104:107], v[158:161], v[202:205], v[104:107]
	v_mfma_f32_16x16x32_bf16 v[120:123], v[154:157], v[190:193], v[120:123]
	v_mfma_f32_16x16x32_bf16 v[120:123], v[158:161], v[194:197], v[120:123]
	s_setprio 0
	s_setprio 1
	v_mfma_f32_16x16x32_bf16 v[116:119], v[172:175], v[190:193], v[116:119]
	v_mfma_f32_16x16x32_bf16 v[116:119], v[176:179], v[194:197], v[116:119]
	v_mfma_f32_16x16x32_bf16 v[100:103], v[172:175], v[198:201], v[100:103]
	v_mfma_f32_16x16x32_bf16 v[100:103], v[176:179], v[202:205], v[100:103]
	v_mfma_f32_16x16x32_bf16 v[84:87], v[172:175], v[206:209], v[84:87]
	v_mfma_f32_16x16x32_bf16 v[84:87], v[176:179], v[210:213], v[84:87]
	v_mfma_f32_16x16x32_bf16 v[68:71], v[172:175], v[214:217], v[68:71]
	v_mfma_f32_16x16x32_bf16 v[68:71], v[176:179], v[218:221], v[68:71]
	v_mfma_f32_16x16x32_bf16 v[64:67], v[182:185], v[214:217], v[64:67]
	v_mfma_f32_16x16x32_bf16 v[64:67], v[186:189], v[218:221], v[64:67]
	v_mfma_f32_16x16x32_bf16 v[80:83], v[182:185], v[206:209], v[80:83]
	v_mfma_f32_16x16x32_bf16 v[80:83], v[186:189], v[210:213], v[80:83]
	v_mfma_f32_16x16x32_bf16 v[96:99], v[182:185], v[198:201], v[96:99]
	v_mfma_f32_16x16x32_bf16 v[96:99], v[186:189], v[202:205], v[96:99]
	v_mfma_f32_16x16x32_bf16 v[112:115], v[182:185], v[190:193], v[112:115]
	v_mfma_f32_16x16x32_bf16 v[112:115], v[186:189], v[194:197], v[112:115]
	s_setprio 0
	s_barrier
	s_add_i32 s17, s77, s66
	v_lshl_add_u64 v[162:163], s[8:9], 0, v[132:133]
	s_mov_b32 m0, s17
	ds_read_b128 v[190:193], v169 offset:16384
	ds_read_b128 v[194:197], v169 offset:17408
	ds_read_b128 v[198:201], v169 offset:18432
	ds_read_b128 v[202:205], v169 offset:19456
	ds_read_b128 v[206:209], v169 offset:20480
	ds_read_b128 v[210:213], v169 offset:21504
	ds_read_b128 v[214:217], v169 offset:22528
	ds_read_b128 v[218:221], v169 offset:23552
	global_load_lds_dwordx4 v[162:163], off
	s_add_i32 m0, s17, 0x2000
	s_add_u32 s18, s8, 0x110000
	v_lshl_add_u64 v[222:223], s[8:9], 0, v[128:129]
	s_addc_u32 s19, s9, 0
	s_add_i32 s17, s78, s66
	global_load_lds_dwordx4 v[222:223], off
	v_lshl_add_u64 v[224:225], s[18:19], 0, v[132:133]
	s_mov_b32 m0, s17
	v_lshl_add_u64 v[226:227], s[10:11], 0, v[130:131]
	global_load_lds_dwordx4 v[224:225], off
	v_lshl_add_u64 v[224:225], s[18:19], 0, v[128:129]
	s_add_i32 m0, s17, 0x2000
	s_nop 0
	global_load_lds_dwordx4 v[224:225], off
	v_lshl_add_u64 v[224:225], s[10:11], 0, v[134:135]
	s_mov_b32 m0, s65
	s_nop 0
	global_load_lds_dwordx4 v[224:225], off
	s_mov_b32 m0, s69
	s_nop 0
	global_load_lds_dwordx4 v[226:227], off
	s_waitcnt vmcnt(8)
	s_waitcnt lgkmcnt(0)
	s_setprio 1
	s_barrier
; #define PG8_STAGE(bufoff, gbase, voff) do { _Pragma("unroll") for (int _i = 0; _i < 2; ++_i) \
;         __builtin_amdgcn_global_load_lds((const unsigned*)((const char*)(gbase) + (voff)[_i]), (LAS unsigned*)(lds + (bufoff) + ldsw + _i * 8192), 16, 0, 0); } while (0)
; #define PG8_LDA(dst, b, h) do { _Pragma("unroll") for (int m = 0; m < 4; ++m) _Pragma("unroll") for (int k = 0; k < 2; ++k) dst[m][k] = *(const LAS bf16x8*)(lds + PG8_SA(b, h) + aoff + m * 2048 + k * 1024); } while (0)
; #define PG8_LDB(dst, b, h) do { _Pragma("unroll") for (int n = 0; n < 2; ++n) _Pragma("unroll") for (int k = 0; k < 2; ++k) dst[n][k] = *(const LAS bf16x8*)(lds + PG8_SB(b, h) + boff + n * 2048 + k * 1024); } while (0)
; #define PG8_MMA(ai, bj, At, Bt) do { __builtin_amdgcn_s_setprio(1); _Pragma("unroll") for (int m = 0; m < 4; ++m) _Pragma("unroll") for (int n = 0; n < 2; ++n) _Pragma("unroll") for (int k = 0; k < 2; ++k) \
;         acc[ai][bj][m][n] = __builtin_amdgcn_mfma_f32_16x16x32_bf16(Bt[n][k], At[m][k], acc[ai][bj][m][n], 0, 0, 0); __builtin_amdgcn_s_setprio(0); } while (0)
; #define PG8_WAIT_V(n) asm volatile("s_waitcnt vmcnt(" #n ")" ::: "memory")
; #define PG8_WAIT_L(n) asm volatile("s_waitcnt lgkmcnt(" #n ")" ::: "memory")
; #define PG8_BAR __builtin_amdgcn_s_barrier()
; #define PG8_SCHED __builtin_amdgcn_sched_barrier(0)
; template <class Epi>
; DI void gemm_phase(LAS unsigned char* lds, const Gemm g, const StaticOrder& S, const Epi& E) {
;     ...
;             PG8_WAIT_V(8); PG8_WAIT_L(0); PG8_BAR; PG8_MMA(1, 0, At, B0); PG8_MMA(1, 1, At, B1); PG8_BAR; PG8_SCHED;
;             PG8_LDB(B0, 1, 0); PG8_LDB(B1, 1, 1); PG8_SCHED; PG8_LDA(At, 1, 0); PG8_STAGE(PG8_SA(0, 1), a2 + hstepA, voffA);
;             PG8_WAIT_V(8); PG8_WAIT_L(0); PG8_BAR; PG8_MMA(0, 0, At, B0); PG8_MMA(0, 1, At, B1); PG8_BAR; PG8_SCHED;
	v_mfma_f32_16x16x32_bf16 v[60:63], v[146:149], v[190:193], v[60:63]
	v_mfma_f32_16x16x32_bf16 v[60:63], v[150:153], v[194:197], v[60:63]
	v_mfma_f32_16x16x32_bf16 v[44:47], v[146:149], v[198:201], v[44:47]
	v_mfma_f32_16x16x32_bf16 v[44:47], v[150:153], v[202:205], v[44:47]
	v_mfma_f32_16x16x32_bf16 v[28:31], v[146:149], v[206:209], v[28:31]
	v_mfma_f32_16x16x32_bf16 v[28:31], v[150:153], v[210:213], v[28:31]
	v_mfma_f32_16x16x32_bf16 v[12:15], v[146:149], v[214:217], v[12:15]
	v_mfma_f32_16x16x32_bf16 v[12:15], v[150:153], v[218:221], v[12:15]
	v_mfma_f32_16x16x32_bf16 v[8:11], v[154:157], v[214:217], v[8:11]
	v_mfma_f32_16x16x32_bf16 v[8:11], v[158:161], v[218:221], v[8:11]
	v_mfma_f32_16x16x32_bf16 v[24:27], v[154:157], v[206:209], v[24:27]
	v_mfma_f32_16x16x32_bf16 v[24:27], v[158:161], v[210:213], v[24:27]
	v_mfma_f32_16x16x32_bf16 v[40:43], v[154:157], v[198:201], v[40:43]
	v_mfma_f32_16x16x32_bf16 v[40:43], v[158:161], v[202:205], v[40:43]
	v_mfma_f32_16x16x32_bf16 v[56:59], v[154:157], v[190:193], v[56:59]
	v_mfma_f32_16x16x32_bf16 v[56:59], v[158:161], v[194:197], v[56:59]
	s_setprio 0
	s_setprio 1
	v_mfma_f32_16x16x32_bf16 v[52:55], v[172:175], v[190:193], v[52:55]
	v_mfma_f32_16x16x32_bf16 v[52:55], v[176:179], v[194:197], v[52:55]
	v_mfma_f32_16x16x32_bf16 v[36:39], v[172:175], v[198:201], v[36:39]
	v_mfma_f32_16x16x32_bf16 v[36:39], v[176:179], v[202:205], v[36:39]
	v_mfma_f32_16x16x32_bf16 v[20:23], v[172:175], v[206:209], v[20:23]
	v_mfma_f32_16x16x32_bf16 v[20:23], v[176:179], v[210:213], v[20:23]
	v_mfma_f32_16x16x32_bf16 v[4:7], v[172:175], v[214:217], v[4:7]
	v_mfma_f32_16x16x32_bf16 v[4:7], v[176:179], v[218:221], v[4:7]
	v_mfma_f32_16x16x32_bf16 v[0:3], v[182:185], v[214:217], v[0:3]
	v_mfma_f32_16x16x32_bf16 v[0:3], v[186:189], v[218:221], v[0:3]
	v_mfma_f32_16x16x32_bf16 v[16:19], v[182:185], v[206:209], v[16:19]
	v_mfma_f32_16x16x32_bf16 v[16:19], v[186:189], v[210:213], v[16:19]
	v_mfma_f32_16x16x32_bf16 v[32:35], v[182:185], v[198:201], v[32:35]
	v_mfma_f32_16x16x32_bf16 v[32:35], v[186:189], v[202:205], v[32:35]
	v_mfma_f32_16x16x32_bf16 v[48:51], v[182:185], v[190:193], v[48:51]
	v_mfma_f32_16x16x32_bf16 v[48:51], v[186:189], v[194:197], v[48:51]
	s_setprio 0
	s_barrier
	s_add_i32 s17, 0, 0x18000
	v_add_u32_e32 v136, s17, v165
	s_add_i32 s18, 0, 0x1c000
	ds_read_b128 v[146:149], v136
	ds_read_b128 v[150:153], v136 offset:1024
	ds_read_b128 v[154:157], v136 offset:2048
	ds_read_b128 v[158:161], v136 offset:3072
	v_add_u32_e32 v136, s18, v165
	ds_read_b128 v[172:175], v136
	ds_read_b128 v[176:179], v136 offset:1024
	ds_read_b128 v[182:185], v136 offset:2048
	ds_read_b128 v[186:189], v136 offset:3072
	s_add_u32 s10, s10, 0x20000
	s_addc_u32 s11, s11, 0
	s_mov_b32 m0, s70
	v_lshl_add_u64 v[228:229], s[10:11], 0, v[134:135]
	ds_read_b128 v[190:193], v169 offset:32768
	ds_read_b128 v[194:197], v169 offset:33792
	ds_read_b128 v[198:201], v169 offset:34816
	ds_read_b128 v[202:205], v169 offset:35840
	ds_read_b128 v[206:209], v169 offset:36864
	ds_read_b128 v[210:213], v169 offset:37888
	ds_read_b128 v[214:217], v169 offset:38912
	ds_read_b128 v[218:221], v169 offset:39936
	global_load_lds_dwordx4 v[228:229], off
	v_lshl_add_u64 v[228:229], s[10:11], 0, v[130:131]
	s_mov_b32 m0, s71
	s_nop 0
	global_load_lds_dwordx4 v[228:229], off
	s_waitcnt vmcnt(8)
	s_waitcnt lgkmcnt(0)
	s_setprio 1
	s_barrier
	v_mfma_f32_16x16x32_bf16 v[124:127], v[146:149], v[190:193], v[124:127]
	v_mfma_f32_16x16x32_bf16 v[124:127], v[150:153], v[194:197], v[124:127]
	v_mfma_f32_16x16x32_bf16 v[108:111], v[146:149], v[198:201], v[108:111]
	v_mfma_f32_16x16x32_bf16 v[108:111], v[150:153], v[202:205], v[108:111]
	v_mfma_f32_16x16x32_bf16 v[92:95], v[146:149], v[206:209], v[92:95]
	v_mfma_f32_16x16x32_bf16 v[92:95], v[150:153], v[210:213], v[92:95]
	v_mfma_f32_16x16x32_bf16 v[76:79], v[146:149], v[214:217], v[76:79]
	v_mfma_f32_16x16x32_bf16 v[76:79], v[150:153], v[218:221], v[76:79]
	v_mfma_f32_16x16x32_bf16 v[72:75], v[154:157], v[214:217], v[72:75]
	v_mfma_f32_16x16x32_bf16 v[72:75], v[158:161], v[218:221], v[72:75]
	v_mfma_f32_16x16x32_bf16 v[88:91], v[154:157], v[206:209], v[88:91]
	v_mfma_f32_16x16x32_bf16 v[88:91], v[158:161], v[210:213], v[88:91]
	v_mfma_f32_16x16x32_bf16 v[104:107], v[154:157], v[198:201], v[104:107]
	v_mfma_f32_16x16x32_bf16 v[104:107], v[158:161], v[202:205], v[104:107]
	v_mfma_f32_16x16x32_bf16 v[120:123], v[154:157], v[190:193], v[120:123]
	v_mfma_f32_16x16x32_bf16 v[120:123], v[158:161], v[194:197], v[120:123]
	s_setprio 0
	s_setprio 1
	v_mfma_f32_16x16x32_bf16 v[116:119], v[172:175], v[190:193], v[116:119]
	v_mfma_f32_16x16x32_bf16 v[116:119], v[176:179], v[194:197], v[116:119]
	v_mfma_f32_16x16x32_bf16 v[100:103], v[172:175], v[198:201], v[100:103]
	v_mfma_f32_16x16x32_bf16 v[100:103], v[176:179], v[202:205], v[100:103]
	v_mfma_f32_16x16x32_bf16 v[84:87], v[172:175], v[206:209], v[84:87]
	v_mfma_f32_16x16x32_bf16 v[84:87], v[176:179], v[210:213], v[84:87]
	v_mfma_f32_16x16x32_bf16 v[68:71], v[172:175], v[214:217], v[68:71]
	v_mfma_f32_16x16x32_bf16 v[68:71], v[176:179], v[218:221], v[68:71]
	v_mfma_f32_16x16x32_bf16 v[64:67], v[182:185], v[214:217], v[64:67]
	v_mfma_f32_16x16x32_bf16 v[64:67], v[186:189], v[218:221], v[64:67]
	v_mfma_f32_16x16x32_bf16 v[80:83], v[182:185], v[206:209], v[80:83]
	v_mfma_f32_16x16x32_bf16 v[80:83], v[186:189], v[210:213], v[80:83]
	v_mfma_f32_16x16x32_bf16 v[96:99], v[182:185], v[198:201], v[96:99]
	v_mfma_f32_16x16x32_bf16 v[96:99], v[186:189], v[202:205], v[96:99]
	v_mfma_f32_16x16x32_bf16 v[112:115], v[182:185], v[190:193], v[112:115]
	v_mfma_f32_16x16x32_bf16 v[112:115], v[186:189], v[194:197], v[112:115]
	s_setprio 0
	s_barrier
; #define PG8_STAGE(bufoff, gbase, voff) do { _Pragma("unroll") for (int _i = 0; _i < 2; ++_i) \
;         __builtin_amdgcn_global_load_lds((const unsigned*)((const char*)(gbase) + (voff)[_i]), (LAS unsigned*)(lds + (bufoff) + ldsw + _i * 8192), 16, 0, 0); } while (0)
; #define PG8_LDA(dst, b, h) do { _Pragma("unroll") for (int m = 0; m < 4; ++m) _Pragma("unroll") for (int k = 0; k < 2; ++k) dst[m][k] = *(const LAS bf16x8*)(lds + PG8_SA(b, h) + aoff + m * 2048 + k * 1024); } while (0)
; #define PG8_MMA(ai, bj, At, Bt) do { __builtin_amdgcn_s_setprio(1); _Pragma("unroll") for (int m = 0; m < 4; ++m) _Pragma("unroll") for (int n = 0; n < 2; ++n) _Pragma("unroll") for (int k = 0; k < 2; ++k) \
;         acc[ai][bj][m][n] = __builtin_amdgcn_mfma_f32_16x16x32_bf16(Bt[n][k], At[m][k], acc[ai][bj][m][n], 0, 0, 0); __builtin_amdgcn_s_setprio(0); } while (0)
; #define PG8_WAIT_V(n) asm volatile("s_waitcnt vmcnt(" #n ")" ::: "memory")
; #define PG8_WAIT_L(n) asm volatile("s_waitcnt lgkmcnt(" #n ")" ::: "memory")
; #define PG8_BAR __builtin_amdgcn_s_barrier()
; #define PG8_SCHED __builtin_amdgcn_sched_barrier(0)
; template <class Epi>
; DI void gemm_phase(LAS unsigned char* lds, const Gemm g, const StaticOrder& S, const Epi& E) {
;     ...
;             PG8_LDA(At, 1, 1); PG8_STAGE(PG8_SB(1, 0), b3, voffB); PG8_STAGE(PG8_SB(1, 1), b3 + hstepB, voffB); PG8_STAGE(PG8_SA(1, 0), a3, voffA);
;             PG8_WAIT_V(8); PG8_WAIT_L(0); PG8_BAR; PG8_MMA(1, 0, At, B0); PG8_MMA(1, 1, At, B1); PG8_BAR; PG8_SCHED;
;         }
	s_add_i32 s10, s17, s66
	v_lshl_add_u64 v[162:163], v[162:163], 0, s[42:43]
	s_mov_b32 m0, s10
	ds_read_b128 v[190:193], v169 offset:49152
	ds_read_b128 v[194:197], v169 offset:50176
	ds_read_b128 v[198:201], v169 offset:51200
	ds_read_b128 v[202:205], v169 offset:52224
	ds_read_b128 v[206:209], v169 offset:53248
	ds_read_b128 v[210:213], v169 offset:54272
	ds_read_b128 v[214:217], v169 offset:55296
	ds_read_b128 v[218:221], v169 offset:56320
	global_load_lds_dwordx4 v[162:163], off
	s_add_i32 m0, s10, 0x2000
	s_add_u32 s8, s8, 0x110080
	v_lshl_add_u64 v[162:163], v[222:223], 0, s[42:43]
	s_addc_u32 s9, s9, 0
	s_add_i32 s10, s18, s66
	global_load_lds_dwordx4 v[162:163], off
	v_lshl_add_u64 v[162:163], s[8:9], 0, v[132:133]
	s_mov_b32 m0, s10
	s_nop 0
	global_load_lds_dwordx4 v[162:163], off
	v_lshl_add_u64 v[162:163], s[8:9], 0, v[128:129]
	s_add_i32 m0, s10, 0x2000
	s_nop 0
	global_load_lds_dwordx4 v[162:163], off
	v_lshl_add_u64 v[162:163], v[224:225], 0, s[42:43]
	s_mov_b32 m0, s74
	s_nop 0
	global_load_lds_dwordx4 v[162:163], off
	v_lshl_add_u64 v[162:163], v[226:227], 0, s[42:43]
	s_mov_b32 m0, s75
	s_nop 0
	global_load_lds_dwordx4 v[162:163], off
	s_waitcnt vmcnt(8)
	s_waitcnt lgkmcnt(0)
	s_setprio 1
	s_barrier
	v_mfma_f32_16x16x32_bf16 v[60:63], v[146:149], v[190:193], v[60:63]
	v_mfma_f32_16x16x32_bf16 v[60:63], v[150:153], v[194:197], v[60:63]
	v_mfma_f32_16x16x32_bf16 v[44:47], v[146:149], v[198:201], v[44:47]
	v_mfma_f32_16x16x32_bf16 v[44:47], v[150:153], v[202:205], v[44:47]
	v_mfma_f32_16x16x32_bf16 v[28:31], v[146:149], v[206:209], v[28:31]
	v_mfma_f32_16x16x32_bf16 v[28:31], v[150:153], v[210:213], v[28:31]
	v_mfma_f32_16x16x32_bf16 v[12:15], v[146:149], v[214:217], v[12:15]
	v_mfma_f32_16x16x32_bf16 v[12:15], v[150:153], v[218:221], v[12:15]
	v_mfma_f32_16x16x32_bf16 v[8:11], v[154:157], v[214:217], v[8:11]
	v_mfma_f32_16x16x32_bf16 v[8:11], v[158:161], v[218:221], v[8:11]
	v_mfma_f32_16x16x32_bf16 v[24:27], v[154:157], v[206:209], v[24:27]
	v_mfma_f32_16x16x32_bf16 v[24:27], v[158:161], v[210:213], v[24:27]
	v_mfma_f32_16x16x32_bf16 v[40:43], v[154:157], v[198:201], v[40:43]
	v_mfma_f32_16x16x32_bf16 v[40:43], v[158:161], v[202:205], v[40:43]
	v_mfma_f32_16x16x32_bf16 v[56:59], v[154:157], v[190:193], v[56:59]
	v_mfma_f32_16x16x32_bf16 v[56:59], v[158:161], v[194:197], v[56:59]
	s_setprio 0
	s_setprio 1
	v_mfma_f32_16x16x32_bf16 v[52:55], v[172:175], v[190:193], v[52:55]
	v_mfma_f32_16x16x32_bf16 v[52:55], v[176:179], v[194:197], v[52:55]
	v_mfma_f32_16x16x32_bf16 v[36:39], v[172:175], v[198:201], v[36:39]
	v_mfma_f32_16x16x32_bf16 v[36:39], v[176:179], v[202:205], v[36:39]
	v_mfma_f32_16x16x32_bf16 v[20:23], v[172:175], v[206:209], v[20:23]
	v_mfma_f32_16x16x32_bf16 v[20:23], v[176:179], v[210:213], v[20:23]
	v_mfma_f32_16x16x32_bf16 v[4:7], v[172:175], v[214:217], v[4:7]
	v_mfma_f32_16x16x32_bf16 v[4:7], v[176:179], v[218:221], v[4:7]
	v_mfma_f32_16x16x32_bf16 v[0:3], v[182:185], v[214:217], v[0:3]
	v_mfma_f32_16x16x32_bf16 v[0:3], v[186:189], v[218:221], v[0:3]
	v_mfma_f32_16x16x32_bf16 v[16:19], v[182:185], v[206:209], v[16:19]
	v_mfma_f32_16x16x32_bf16 v[16:19], v[186:189], v[210:213], v[16:19]
	v_mfma_f32_16x16x32_bf16 v[32:35], v[182:185], v[198:201], v[32:35]
	v_mfma_f32_16x16x32_bf16 v[32:35], v[186:189], v[202:205], v[32:35]
	v_mfma_f32_16x16x32_bf16 v[48:51], v[182:185], v[190:193], v[48:51]
	v_mfma_f32_16x16x32_bf16 v[48:51], v[186:189], v[194:197], v[48:51]
	s_setprio 0
	s_barrier
	s_add_u32 s6, s6, 0x100
	s_addc_u32 s7, s7, 0
	s_add_u32 s14, s14, 0x100
	s_addc_u32 s15, s15, 0
	s_cmp_ge_i32 s16, s73
	s_mov_b32 s8, s16
	s_cbranch_scc0 .LBB0_352

; #define PG8_STAGE(bufoff, gbase, voff) do { _Pragma("unroll") for (int _i = 0; _i < 2; ++_i) \
;         __builtin_amdgcn_global_load_lds((const unsigned*)((const char*)(gbase) + (voff)[_i]), (LAS unsigned*)(lds + (bufoff) + ldsw + _i * 8192), 16, 0, 0); } while (0)
; #define PG8_LDA(dst, b, h) do { _Pragma("unroll") for (int m = 0; m < 4; ++m) _Pragma("unroll") for (int k = 0; k < 2; ++k) dst[m][k] = *(const LAS bf16x8*)(lds + PG8_SA(b, h) + aoff + m * 2048 + k * 1024); } while (0)
; #define PG8_LDB(dst, b, h) do { _Pragma("unroll") for (int n = 0; n < 2; ++n) _Pragma("unroll") for (int k = 0; k < 2; ++k) dst[n][k] = *(const LAS bf16x8*)(lds + PG8_SB(b, h) + boff + n * 2048 + k * 1024); } while (0)
; #define PG8_MMA(ai, bj, At, Bt) do { __builtin_amdgcn_s_setprio(1); _Pragma("unroll") for (int m = 0; m < 4; ++m) _Pragma("unroll") for (int n = 0; n < 2; ++n) _Pragma("unroll") for (int k = 0; k < 2; ++k) \
;         acc[ai][bj][m][n] = __builtin_amdgcn_mfma_f32_16x16x32_bf16(Bt[n][k], At[m][k], acc[ai][bj][m][n], 0, 0, 0); __builtin_amdgcn_s_setprio(0); } while (0)
; #define PG8_WAIT_V(n) asm volatile("s_waitcnt vmcnt(" #n ")" ::: "memory")
; #define PG8_WAIT_L(n) asm volatile("s_waitcnt lgkmcnt(" #n ")" ::: "memory")
; #define PG8_BAR __builtin_amdgcn_s_barrier()
; #define PG8_SCHED __builtin_amdgcn_sched_barrier(0)
; template <class Epi>
; DI void gemm_phase(LAS unsigned char* lds, const Gemm g, const StaticOrder& S, const Epi& E) {
;     ...
;             PG8_LDB(B0, 0, 0); PG8_LDB(B1, 0, 1); PG8_SCHED; PG8_LDA(At, 0, 0); PG8_STAGE(PG8_SA(1, 1), a1 + hstepA, voffA);
;             PG8_WAIT_V(8); PG8_WAIT_L(0); PG8_BAR; PG8_MMA(0, 0, At, B0); PG8_MMA(0, 1, At, B1); PG8_BAR; PG8_SCHED;
;             PG8_LDA(At, 0, 1); PG8_STAGE(PG8_SB(0, 0), b2, voffB); PG8_STAGE(PG8_SB(0, 1), b2 + hstepB, voffB); PG8_STAGE(PG8_SA(0, 0), a2, voffA);
;             PG8_WAIT_V(8); PG8_WAIT_L(0); PG8_BAR; PG8_MMA(1, 0, At, B0); PG8_MMA(1, 1, At, B1); PG8_BAR; PG8_SCHED;
.LBB0_548:
	v_add_u32_e32 v1, s65, v160
	ds_read_b128 v[148:151], v1
	ds_read_b128 v[152:155], v1 offset:1024
	ds_read_b128 v[166:169], v1 offset:2048
	ds_read_b128 v[170:173], v1 offset:3072
	v_add_u32_e32 v1, s66, v160
	ds_read_b128 v[174:177], v1
	ds_read_b128 v[182:185], v1 offset:1024
	ds_read_b128 v[186:189], v1 offset:2048
	ds_read_b128 v[190:193], v1 offset:3072
	s_add_i32 s39, s46, 2
	s_add_u32 s47, s8, 0xfff00080
	s_addc_u32 s50, s9, -1
	s_cmp_eq_u32 s64, s46
	s_cselect_b32 s46, s42, s13
	s_cselect_b32 s51, s41, s50
	s_cselect_b32 s50, s40, s47
	s_cselect_b32 s47, s43, s35
	s_waitcnt lgkmcnt(0)
	v_lshl_add_u64 v[2:3], s[8:9], 0, v[140:141]
	s_add_i32 m0, s56, 0xc000
	ds_read_b128 v[194:197], v162
	ds_read_b128 v[198:201], v162 offset:1024
	ds_read_b128 v[202:205], v162 offset:2048
	ds_read_b128 v[206:209], v162 offset:3072
	ds_read_b128 v[210:213], v162 offset:4096
	ds_read_b128 v[214:217], v162 offset:5120
	ds_read_b128 v[218:221], v162 offset:6144
	ds_read_b128 v[222:225], v162 offset:7168
	global_load_lds_dwordx4 v[2:3], off
	v_lshl_add_u64 v[2:3], s[8:9], 0, v[142:143]
	s_add_i32 m0, s56, 0xe000
	s_nop 0
	global_load_lds_dwordx4 v[2:3], off
	s_waitcnt vmcnt(8)
	s_waitcnt lgkmcnt(0)
	s_setprio 1
	s_barrier
	v_mfma_f32_16x16x32_bf16 v[128:131], v[148:151], v[194:197], v[128:131]
	v_mfma_f32_16x16x32_bf16 v[128:131], v[152:155], v[198:201], v[128:131]
	v_mfma_f32_16x16x32_bf16 v[120:123], v[148:151], v[202:205], v[120:123]
	v_mfma_f32_16x16x32_bf16 v[120:123], v[152:155], v[206:209], v[120:123]
	v_mfma_f32_16x16x32_bf16 v[112:115], v[148:151], v[210:213], v[112:115]
	v_mfma_f32_16x16x32_bf16 v[112:115], v[152:155], v[214:217], v[112:115]
	v_mfma_f32_16x16x32_bf16 v[104:107], v[148:151], v[218:221], v[104:107]
	v_mfma_f32_16x16x32_bf16 v[104:107], v[152:155], v[222:225], v[104:107]
	v_mfma_f32_16x16x32_bf16 v[100:103], v[166:169], v[218:221], v[100:103]
	v_mfma_f32_16x16x32_bf16 v[100:103], v[170:173], v[222:225], v[100:103]
	v_mfma_f32_16x16x32_bf16 v[108:111], v[166:169], v[210:213], v[108:111]
	v_mfma_f32_16x16x32_bf16 v[108:111], v[170:173], v[214:217], v[108:111]
	v_mfma_f32_16x16x32_bf16 v[116:119], v[166:169], v[202:205], v[116:119]
	v_mfma_f32_16x16x32_bf16 v[116:119], v[170:173], v[206:209], v[116:119]
	v_mfma_f32_16x16x32_bf16 v[124:127], v[166:169], v[194:197], v[124:127]
	v_mfma_f32_16x16x32_bf16 v[124:127], v[170:173], v[198:201], v[124:127]
	s_setprio 0
	s_setprio 1
	v_mfma_f32_16x16x32_bf16 v[96:99], v[174:177], v[194:197], v[96:99]
	v_mfma_f32_16x16x32_bf16 v[96:99], v[182:185], v[198:201], v[96:99]
	v_mfma_f32_16x16x32_bf16 v[88:91], v[174:177], v[202:205], v[88:91]
	v_mfma_f32_16x16x32_bf16 v[88:91], v[182:185], v[206:209], v[88:91]
	v_mfma_f32_16x16x32_bf16 v[80:83], v[174:177], v[210:213], v[80:83]
	v_mfma_f32_16x16x32_bf16 v[80:83], v[182:185], v[214:217], v[80:83]
	v_mfma_f32_16x16x32_bf16 v[72:75], v[174:177], v[218:221], v[72:75]
	v_mfma_f32_16x16x32_bf16 v[72:75], v[182:185], v[222:225], v[72:75]
	v_mfma_f32_16x16x32_bf16 v[68:71], v[186:189], v[218:221], v[68:71]
	v_mfma_f32_16x16x32_bf16 v[68:71], v[190:193], v[222:225], v[68:71]
	v_mfma_f32_16x16x32_bf16 v[76:79], v[186:189], v[210:213], v[76:79]
	v_mfma_f32_16x16x32_bf16 v[76:79], v[190:193], v[214:217], v[76:79]
	v_mfma_f32_16x16x32_bf16 v[84:87], v[186:189], v[202:205], v[84:87]
	v_mfma_f32_16x16x32_bf16 v[84:87], v[190:193], v[206:209], v[84:87]
	v_mfma_f32_16x16x32_bf16 v[92:95], v[186:189], v[194:197], v[92:95]
	v_mfma_f32_16x16x32_bf16 v[92:95], v[190:193], v[198:201], v[92:95]
	s_setprio 0
	s_barrier
	s_add_i32 s71, s65, s55
	v_lshl_add_u64 v[156:157], s[46:47], 0, v[134:135]
	s_mov_b32 m0, s71
	ds_read_b128 v[194:197], v162 offset:16384
	ds_read_b128 v[198:201], v162 offset:17408
	ds_read_b128 v[202:205], v162 offset:18432
	ds_read_b128 v[206:209], v162 offset:19456
	ds_read_b128 v[210:213], v162 offset:20480
	ds_read_b128 v[214:217], v162 offset:21504
	ds_read_b128 v[218:221], v162 offset:22528
	ds_read_b128 v[222:225], v162 offset:23552
	global_load_lds_dwordx4 v[156:157], off
	s_add_i32 m0, s71, 0x2000
	s_add_u32 s72, s46, 0x100000
	v_lshl_add_u64 v[178:179], s[46:47], 0, v[138:139]
	s_addc_u32 s73, s47, 0
	s_add_i32 s71, s66, s55
	global_load_lds_dwordx4 v[178:179], off
	v_lshl_add_u64 v[2:3], s[72:73], 0, v[134:135]
	s_mov_b32 m0, s71
	v_lshl_add_u64 v[226:227], s[50:51], 0, v[132:133]
	global_load_lds_dwordx4 v[2:3], off
	v_lshl_add_u64 v[2:3], s[72:73], 0, v[138:139]
	s_add_i32 m0, s71, 0x2000
	v_lshl_add_u64 v[228:229], s[50:51], 0, v[136:137]
	global_load_lds_dwordx4 v[2:3], off
	s_mov_b32 m0, s56
	s_nop 0
	global_load_lds_dwordx4 v[226:227], off
	s_mov_b32 m0, s57
	s_nop 0
	global_load_lds_dwordx4 v[228:229], off
	s_waitcnt vmcnt(8)
	s_waitcnt lgkmcnt(0)
	s_setprio 1
	s_barrier
; #define PG8_STAGE(bufoff, gbase, voff) do { _Pragma("unroll") for (int _i = 0; _i < 2; ++_i) \
;         __builtin_amdgcn_global_load_lds((const unsigned*)((const char*)(gbase) + (voff)[_i]), (LAS unsigned*)(lds + (bufoff) + ldsw + _i * 8192), 16, 0, 0); } while (0)
; #define PG8_LDA(dst, b, h) do { _Pragma("unroll") for (int m = 0; m < 4; ++m) _Pragma("unroll") for (int k = 0; k < 2; ++k) dst[m][k] = *(const LAS bf16x8*)(lds + PG8_SA(b, h) + aoff + m * 2048 + k * 1024); } while (0)
; #define PG8_LDB(dst, b, h) do { _Pragma("unroll") for (int n = 0; n < 2; ++n) _Pragma("unroll") for (int k = 0; k < 2; ++k) dst[n][k] = *(const LAS bf16x8*)(lds + PG8_SB(b, h) + boff + n * 2048 + k * 1024); } while (0)
; #define PG8_MMA(ai, bj, At, Bt) do { __builtin_amdgcn_s_setprio(1); _Pragma("unroll") for (int m = 0; m < 4; ++m) _Pragma("unroll") for (int n = 0; n < 2; ++n) _Pragma("unroll") for (int k = 0; k < 2; ++k) \
;         acc[ai][bj][m][n] = __builtin_amdgcn_mfma_f32_16x16x32_bf16(Bt[n][k], At[m][k], acc[ai][bj][m][n], 0, 0, 0); __builtin_amdgcn_s_setprio(0); } while (0)
; #define PG8_WAIT_V(n) asm volatile("s_waitcnt vmcnt(" #n ")" ::: "memory")
; #define PG8_WAIT_L(n) asm volatile("s_waitcnt lgkmcnt(" #n ")" ::: "memory")
; #define PG8_BAR __builtin_amdgcn_s_barrier()
; #define PG8_SCHED __builtin_amdgcn_sched_barrier(0)
; template <class Epi>
; DI void gemm_phase(LAS unsigned char* lds, const Gemm g, const StaticOrder& S, const Epi& E) {
;     ...
;             PG8_WAIT_V(8); PG8_WAIT_L(0); PG8_BAR; PG8_MMA(1, 0, At, B0); PG8_MMA(1, 1, At, B1); PG8_BAR; PG8_SCHED;
;             PG8_LDB(B0, 1, 0); PG8_LDB(B1, 1, 1); PG8_SCHED; PG8_LDA(At, 1, 0); PG8_STAGE(PG8_SA(0, 1), a2 + hstepA, voffA);
;             PG8_WAIT_V(8); PG8_WAIT_L(0); PG8_BAR; PG8_MMA(0, 0, At, B0); PG8_MMA(0, 1, At, B1); PG8_BAR; PG8_SCHED;
	v_mfma_f32_16x16x32_bf16 v[64:67], v[148:151], v[194:197], v[64:67]
	v_mfma_f32_16x16x32_bf16 v[64:67], v[152:155], v[198:201], v[64:67]
	v_mfma_f32_16x16x32_bf16 v[56:59], v[148:151], v[202:205], v[56:59]
	v_mfma_f32_16x16x32_bf16 v[56:59], v[152:155], v[206:209], v[56:59]
	v_mfma_f32_16x16x32_bf16 v[48:51], v[148:151], v[210:213], v[48:51]
	v_mfma_f32_16x16x32_bf16 v[48:51], v[152:155], v[214:217], v[48:51]
	v_mfma_f32_16x16x32_bf16 v[40:43], v[148:151], v[218:221], v[40:43]
	v_mfma_f32_16x16x32_bf16 v[40:43], v[152:155], v[222:225], v[40:43]
	v_mfma_f32_16x16x32_bf16 v[36:39], v[166:169], v[218:221], v[36:39]
	v_mfma_f32_16x16x32_bf16 v[36:39], v[170:173], v[222:225], v[36:39]
	v_mfma_f32_16x16x32_bf16 v[44:47], v[166:169], v[210:213], v[44:47]
	v_mfma_f32_16x16x32_bf16 v[44:47], v[170:173], v[214:217], v[44:47]
	v_mfma_f32_16x16x32_bf16 v[52:55], v[166:169], v[202:205], v[52:55]
	v_mfma_f32_16x16x32_bf16 v[52:55], v[170:173], v[206:209], v[52:55]
	v_mfma_f32_16x16x32_bf16 v[60:63], v[166:169], v[194:197], v[60:63]
	v_mfma_f32_16x16x32_bf16 v[60:63], v[170:173], v[198:201], v[60:63]
	s_setprio 0
	s_setprio 1
	v_mfma_f32_16x16x32_bf16 v[32:35], v[174:177], v[194:197], v[32:35]
	v_mfma_f32_16x16x32_bf16 v[32:35], v[182:185], v[198:201], v[32:35]
	v_mfma_f32_16x16x32_bf16 v[24:27], v[174:177], v[202:205], v[24:27]
	v_mfma_f32_16x16x32_bf16 v[24:27], v[182:185], v[206:209], v[24:27]
	v_mfma_f32_16x16x32_bf16 v[16:19], v[174:177], v[210:213], v[16:19]
	v_mfma_f32_16x16x32_bf16 v[16:19], v[182:185], v[214:217], v[16:19]
	v_mfma_f32_16x16x32_bf16 v[8:11], v[174:177], v[218:221], v[8:11]
	v_mfma_f32_16x16x32_bf16 v[8:11], v[182:185], v[222:225], v[8:11]
	v_mfma_f32_16x16x32_bf16 v[2:5], v[186:189], v[218:221], v[4:7]
	v_mfma_f32_16x16x32_bf16 v[2:5], v[190:193], v[222:225], v[2:5]
	v_mfma_f32_16x16x32_bf16 v[12:15], v[186:189], v[210:213], v[12:15]
	v_mfma_f32_16x16x32_bf16 v[12:15], v[190:193], v[214:217], v[12:15]
	v_mfma_f32_16x16x32_bf16 v[20:23], v[186:189], v[202:205], v[20:23]
	v_mfma_f32_16x16x32_bf16 v[20:23], v[190:193], v[206:209], v[20:23]
	v_mfma_f32_16x16x32_bf16 v[28:31], v[186:189], v[194:197], v[28:31]
	v_mfma_f32_16x16x32_bf16 v[28:31], v[190:193], v[198:201], v[28:31]
	s_setprio 0
	s_barrier
	s_add_i32 s71, 0, 0x18000
	v_add_u32_e32 v1, s71, v160
	s_add_i32 s72, 0, 0x1c000
	ds_read_b128 v[148:151], v1
	ds_read_b128 v[152:155], v1 offset:1024
	ds_read_b128 v[166:169], v1 offset:2048
	ds_read_b128 v[170:173], v1 offset:3072
	v_add_u32_e32 v1, s72, v160
	ds_read_b128 v[174:177], v1
	ds_read_b128 v[182:185], v1 offset:1024
	ds_read_b128 v[186:189], v1 offset:2048
	ds_read_b128 v[190:193], v1 offset:3072
	s_add_u32 s50, s50, 0x100000
	s_addc_u32 s51, s51, 0
	s_mov_b32 m0, s58
	v_lshl_add_u64 v[6:7], s[50:51], 0, v[132:133]
	ds_read_b128 v[194:197], v162 offset:32768
	ds_read_b128 v[198:201], v162 offset:33792
	ds_read_b128 v[202:205], v162 offset:34816
	ds_read_b128 v[206:209], v162 offset:35840
	ds_read_b128 v[210:213], v162 offset:36864
	ds_read_b128 v[214:217], v162 offset:37888
	ds_read_b128 v[218:221], v162 offset:38912
	ds_read_b128 v[222:225], v162 offset:39936
	global_load_lds_dwordx4 v[6:7], off
	v_lshl_add_u64 v[6:7], s[50:51], 0, v[136:137]
	s_mov_b32 m0, s59
	s_nop 0
	global_load_lds_dwordx4 v[6:7], off
	s_waitcnt vmcnt(8)
	s_waitcnt lgkmcnt(0)
	s_setprio 1
	s_barrier
	v_mfma_f32_16x16x32_bf16 v[128:131], v[148:151], v[194:197], v[128:131]
	v_mfma_f32_16x16x32_bf16 v[128:131], v[152:155], v[198:201], v[128:131]
	v_mfma_f32_16x16x32_bf16 v[120:123], v[148:151], v[202:205], v[120:123]
	v_mfma_f32_16x16x32_bf16 v[120:123], v[152:155], v[206:209], v[120:123]
	v_mfma_f32_16x16x32_bf16 v[112:115], v[148:151], v[210:213], v[112:115]
	v_mfma_f32_16x16x32_bf16 v[112:115], v[152:155], v[214:217], v[112:115]
	v_mfma_f32_16x16x32_bf16 v[104:107], v[148:151], v[218:221], v[104:107]
	v_mfma_f32_16x16x32_bf16 v[104:107], v[152:155], v[222:225], v[104:107]
	v_mfma_f32_16x16x32_bf16 v[100:103], v[166:169], v[218:221], v[100:103]
	v_mfma_f32_16x16x32_bf16 v[100:103], v[170:173], v[222:225], v[100:103]
	v_mfma_f32_16x16x32_bf16 v[108:111], v[166:169], v[210:213], v[108:111]
	v_mfma_f32_16x16x32_bf16 v[108:111], v[170:173], v[214:217], v[108:111]
	v_mfma_f32_16x16x32_bf16 v[116:119], v[166:169], v[202:205], v[116:119]
	v_mfma_f32_16x16x32_bf16 v[116:119], v[170:173], v[206:209], v[116:119]
	v_mfma_f32_16x16x32_bf16 v[124:127], v[166:169], v[194:197], v[124:127]
	v_mfma_f32_16x16x32_bf16 v[124:127], v[170:173], v[198:201], v[124:127]
	s_setprio 0
	s_setprio 1
	v_mfma_f32_16x16x32_bf16 v[96:99], v[174:177], v[194:197], v[96:99]
	v_mfma_f32_16x16x32_bf16 v[96:99], v[182:185], v[198:201], v[96:99]
	v_mfma_f32_16x16x32_bf16 v[88:91], v[174:177], v[202:205], v[88:91]
	v_mfma_f32_16x16x32_bf16 v[88:91], v[182:185], v[206:209], v[88:91]
	v_mfma_f32_16x16x32_bf16 v[80:83], v[174:177], v[210:213], v[80:83]
	v_mfma_f32_16x16x32_bf16 v[80:83], v[182:185], v[214:217], v[80:83]
	v_mfma_f32_16x16x32_bf16 v[72:75], v[174:177], v[218:221], v[72:75]
	v_mfma_f32_16x16x32_bf16 v[72:75], v[182:185], v[222:225], v[72:75]
	v_mfma_f32_16x16x32_bf16 v[68:71], v[186:189], v[218:221], v[68:71]
	v_mfma_f32_16x16x32_bf16 v[68:71], v[190:193], v[222:225], v[68:71]
	v_mfma_f32_16x16x32_bf16 v[76:79], v[186:189], v[210:213], v[76:79]
	v_mfma_f32_16x16x32_bf16 v[76:79], v[190:193], v[214:217], v[76:79]
	v_mfma_f32_16x16x32_bf16 v[84:87], v[186:189], v[202:205], v[84:87]
	v_mfma_f32_16x16x32_bf16 v[84:87], v[190:193], v[206:209], v[84:87]
	v_mfma_f32_16x16x32_bf16 v[92:95], v[186:189], v[194:197], v[92:95]
	v_mfma_f32_16x16x32_bf16 v[92:95], v[190:193], v[198:201], v[92:95]
	s_setprio 0
	s_barrier
; #define PG8_STAGE(bufoff, gbase, voff) do { _Pragma("unroll") for (int _i = 0; _i < 2; ++_i) \
;         __builtin_amdgcn_global_load_lds((const unsigned*)((const char*)(gbase) + (voff)[_i]), (LAS unsigned*)(lds + (bufoff) + ldsw + _i * 8192), 16, 0, 0); } while (0)
; #define PG8_LDA(dst, b, h) do { _Pragma("unroll") for (int m = 0; m < 4; ++m) _Pragma("unroll") for (int k = 0; k < 2; ++k) dst[m][k] = *(const LAS bf16x8*)(lds + PG8_SA(b, h) + aoff + m * 2048 + k * 1024); } while (0)
; #define PG8_MMA(ai, bj, At, Bt) do { __builtin_amdgcn_s_setprio(1); _Pragma("unroll") for (int m = 0; m < 4; ++m) _Pragma("unroll") for (int n = 0; n < 2; ++n) _Pragma("unroll") for (int k = 0; k < 2; ++k) \
;         acc[ai][bj][m][n] = __builtin_amdgcn_mfma_f32_16x16x32_bf16(Bt[n][k], At[m][k], acc[ai][bj][m][n], 0, 0, 0); __builtin_amdgcn_s_setprio(0); } while (0)
; #define PG8_WAIT_V(n) asm volatile("s_waitcnt vmcnt(" #n ")" ::: "memory")
; #define PG8_WAIT_L(n) asm volatile("s_waitcnt lgkmcnt(" #n ")" ::: "memory")
; #define PG8_BAR __builtin_amdgcn_s_barrier()
; #define PG8_SCHED __builtin_amdgcn_sched_barrier(0)
; template <class Epi>
; DI void gemm_phase(LAS unsigned char* lds, const Gemm g, const StaticOrder& S, const Epi& E) {
;     ...
;             PG8_LDA(At, 1, 1); PG8_STAGE(PG8_SB(1, 0), b3, voffB); PG8_STAGE(PG8_SB(1, 1), b3 + hstepB, voffB); PG8_STAGE(PG8_SA(1, 0), a3, voffA);
;             PG8_WAIT_V(8); PG8_WAIT_L(0); PG8_BAR; PG8_MMA(1, 0, At, B0); PG8_MMA(1, 1, At, B1); PG8_BAR; PG8_SCHED;
;         }
	s_add_i32 s50, s71, s55
	v_lshl_add_u64 v[6:7], v[156:157], 0, s[26:27]
	s_mov_b32 m0, s50
	ds_read_b128 v[194:197], v162 offset:49152
	ds_read_b128 v[198:201], v162 offset:50176
	ds_read_b128 v[202:205], v162 offset:51200
	ds_read_b128 v[206:209], v162 offset:52224
	ds_read_b128 v[210:213], v162 offset:53248
	ds_read_b128 v[214:217], v162 offset:54272
	ds_read_b128 v[218:221], v162 offset:55296
	ds_read_b128 v[222:225], v162 offset:56320
	global_load_lds_dwordx4 v[6:7], off
	s_add_i32 m0, s50, 0x2000
	s_add_u32 s46, s46, 0x100080
	v_lshl_add_u64 v[6:7], v[178:179], 0, s[26:27]
	s_addc_u32 s47, s47, 0
	s_add_i32 s50, s72, s55
	global_load_lds_dwordx4 v[6:7], off
	v_lshl_add_u64 v[6:7], s[46:47], 0, v[134:135]
	s_mov_b32 m0, s50
	s_nop 0
	global_load_lds_dwordx4 v[6:7], off
	v_lshl_add_u64 v[6:7], s[46:47], 0, v[138:139]
	s_add_i32 m0, s50, 0x2000
	s_nop 0
	global_load_lds_dwordx4 v[6:7], off
	v_lshl_add_u64 v[6:7], v[226:227], 0, s[26:27]
	s_mov_b32 m0, s62
	s_nop 0
	global_load_lds_dwordx4 v[6:7], off
	v_lshl_add_u64 v[6:7], v[228:229], 0, s[26:27]
	s_mov_b32 m0, s63
	s_nop 0
	global_load_lds_dwordx4 v[6:7], off
	s_waitcnt vmcnt(8)
	s_waitcnt lgkmcnt(0)
	s_setprio 1
	s_barrier
	v_mfma_f32_16x16x32_bf16 v[64:67], v[148:151], v[194:197], v[64:67]
	v_mfma_f32_16x16x32_bf16 v[64:67], v[152:155], v[198:201], v[64:67]
	v_mfma_f32_16x16x32_bf16 v[56:59], v[148:151], v[202:205], v[56:59]
	v_mfma_f32_16x16x32_bf16 v[56:59], v[152:155], v[206:209], v[56:59]
	v_mfma_f32_16x16x32_bf16 v[48:51], v[148:151], v[210:213], v[48:51]
	v_mfma_f32_16x16x32_bf16 v[48:51], v[152:155], v[214:217], v[48:51]
	v_mfma_f32_16x16x32_bf16 v[40:43], v[148:151], v[218:221], v[40:43]
	v_mfma_f32_16x16x32_bf16 v[40:43], v[152:155], v[222:225], v[40:43]
	v_mfma_f32_16x16x32_bf16 v[36:39], v[166:169], v[218:221], v[36:39]
	v_mfma_f32_16x16x32_bf16 v[36:39], v[170:173], v[222:225], v[36:39]
	v_mfma_f32_16x16x32_bf16 v[44:47], v[166:169], v[210:213], v[44:47]
	v_mfma_f32_16x16x32_bf16 v[44:47], v[170:173], v[214:217], v[44:47]
	v_mfma_f32_16x16x32_bf16 v[52:55], v[166:169], v[202:205], v[52:55]
	v_mfma_f32_16x16x32_bf16 v[52:55], v[170:173], v[206:209], v[52:55]
	v_mfma_f32_16x16x32_bf16 v[60:63], v[166:169], v[194:197], v[60:63]
	v_mfma_f32_16x16x32_bf16 v[60:63], v[170:173], v[198:201], v[60:63]
	s_setprio 0
	s_setprio 1
	v_mfma_f32_16x16x32_bf16 v[32:35], v[174:177], v[194:197], v[32:35]
	v_mfma_f32_16x16x32_bf16 v[32:35], v[182:185], v[198:201], v[32:35]
	v_mfma_f32_16x16x32_bf16 v[28:31], v[186:189], v[194:197], v[28:31]
	v_mfma_f32_16x16x32_bf16 v[28:31], v[190:193], v[198:201], v[28:31]
	v_mfma_f32_16x16x32_bf16 v[24:27], v[174:177], v[202:205], v[24:27]
	v_mfma_f32_16x16x32_bf16 v[24:27], v[182:185], v[206:209], v[24:27]
	v_mfma_f32_16x16x32_bf16 v[20:23], v[186:189], v[202:205], v[20:23]
	v_mfma_f32_16x16x32_bf16 v[20:23], v[190:193], v[206:209], v[20:23]
	v_mfma_f32_16x16x32_bf16 v[16:19], v[174:177], v[210:213], v[16:19]
	v_mfma_f32_16x16x32_bf16 v[16:19], v[182:185], v[214:217], v[16:19]
	v_mfma_f32_16x16x32_bf16 v[12:15], v[186:189], v[210:213], v[12:15]
	v_mfma_f32_16x16x32_bf16 v[12:15], v[190:193], v[214:217], v[12:15]
	v_mfma_f32_16x16x32_bf16 v[6:9], v[174:177], v[218:221], v[8:11]
	v_mfma_f32_16x16x32_bf16 v[2:5], v[186:189], v[218:221], v[2:5]
	v_mfma_f32_16x16x32_bf16 v[8:11], v[182:185], v[222:225], v[6:9]
	v_mfma_f32_16x16x32_bf16 v[4:7], v[190:193], v[222:225], v[2:5]
	s_setprio 0
	s_barrier
	s_add_u32 s8, s8, 0x100
	s_addc_u32 s9, s9, 0
	s_add_u32 s13, s13, 0x100
	s_addc_u32 s35, s35, 0
	s_cmp_ge_i32 s39, s61
	s_mov_b32 s46, s39
	s_cbranch_scc0 .LBB0_548

; #define PG8_STAGE(bufoff, gbase, voff) do { _Pragma("unroll") for (int _i = 0; _i < 2; ++_i) \
;         __builtin_amdgcn_global_load_lds((const unsigned*)((const char*)(gbase) + (voff)[_i]), (LAS unsigned*)(lds + (bufoff) + ldsw + _i * 8192), 16, 0, 0); } while (0)
; #define PG8_LDA(dst, b, h) do { _Pragma("unroll") for (int m = 0; m < 4; ++m) _Pragma("unroll") for (int k = 0; k < 2; ++k) dst[m][k] = *(const LAS bf16x8*)(lds + PG8_SA(b, h) + aoff + m * 2048 + k * 1024); } while (0)
; #define PG8_LDB(dst, b, h) do { _Pragma("unroll") for (int n = 0; n < 2; ++n) _Pragma("unroll") for (int k = 0; k < 2; ++k) dst[n][k] = *(const LAS bf16x8*)(lds + PG8_SB(b, h) + boff + n * 2048 + k * 1024); } while (0)
; #define PG8_MMA(ai, bj, At, Bt) do { __builtin_amdgcn_s_setprio(1); _Pragma("unroll") for (int m = 0; m < 4; ++m) _Pragma("unroll") for (int n = 0; n < 2; ++n) _Pragma("unroll") for (int k = 0; k < 2; ++k) \
;         acc[ai][bj][m][n] = __builtin_amdgcn_mfma_f32_16x16x32_bf16(Bt[n][k], At[m][k], acc[ai][bj][m][n], 0, 0, 0); __builtin_amdgcn_s_setprio(0); } while (0)
; #define PG8_WAIT_V(n) asm volatile("s_waitcnt vmcnt(" #n ")" ::: "memory")
; #define PG8_WAIT_L(n) asm volatile("s_waitcnt lgkmcnt(" #n ")" ::: "memory")
; #define PG8_BAR __builtin_amdgcn_s_barrier()
; #define PG8_SCHED __builtin_amdgcn_sched_barrier(0)
; template <class Epi>
; DI void gemm_phase(LAS unsigned char* lds, const Gemm g, const StaticOrder& S, const Epi& E) {
;     ...
;             PG8_LDB(B0, 0, 0); PG8_LDB(B1, 0, 1); PG8_SCHED; PG8_LDA(At, 0, 0); PG8_STAGE(PG8_SA(1, 1), a1 + hstepA, voffA);
;             PG8_WAIT_V(8); PG8_WAIT_L(0); PG8_BAR; PG8_MMA(0, 0, At, B0); PG8_MMA(0, 1, At, B1); PG8_BAR; PG8_SCHED;
;             PG8_LDA(At, 0, 1); PG8_STAGE(PG8_SB(0, 0), b2, voffB); PG8_STAGE(PG8_SB(0, 1), b2 + hstepB, voffB); PG8_STAGE(PG8_SA(0, 0), a2, voffA);
;             PG8_WAIT_V(8); PG8_WAIT_L(0); PG8_BAR; PG8_MMA(1, 0, At, B0); PG8_MMA(1, 1, At, B1); PG8_BAR; PG8_SCHED;
.LBB0_705:
	ds_read_b128 v[150:153], v147
	ds_read_b128 v[154:157], v147 offset:1024
	ds_read_b128 v[158:161], v147 offset:2048
	ds_read_b128 v[162:165], v147 offset:3072
	ds_read_b128 v[166:169], v148
	ds_read_b128 v[170:173], v148 offset:1024
	ds_read_b128 v[174:177], v148 offset:2048
	ds_read_b128 v[182:185], v148 offset:3072
	s_add_i32 s63, s28, 2
	s_add_u32 s29, s26, 0xfff00080
	s_addc_u32 s30, s27, -1
	s_cmp_eq_u32 s54, s28
	s_cselect_b32 s28, s60, s61
	s_cselect_b32 s31, s17, s30
	s_cselect_b32 s30, s19, s29
	s_cselect_b32 s29, s59, s62
	v_lshl_add_u64 v[178:179], s[26:27], 0, v[136:137]
	s_add_i32 m0, s25, 0xc000
	ds_read_b128 v[186:189], v149
	ds_read_b128 v[190:193], v149 offset:1024
	ds_read_b128 v[194:197], v149 offset:2048
	ds_read_b128 v[198:201], v149 offset:3072
	ds_read_b128 v[202:205], v149 offset:4096
	ds_read_b128 v[206:209], v149 offset:5120
	ds_read_b128 v[210:213], v149 offset:6144
	ds_read_b128 v[214:217], v149 offset:7168
	global_load_lds_dwordx4 v[178:179], off
	v_lshl_add_u64 v[178:179], s[26:27], 0, v[138:139]
	s_add_i32 m0, s25, 0xe000
	s_nop 0
	global_load_lds_dwordx4 v[178:179], off
	s_waitcnt vmcnt(8)
	s_waitcnt lgkmcnt(0)
	s_setprio 1
	s_barrier
	v_mfma_f32_16x16x32_bf16 v[124:127], v[150:153], v[186:189], v[124:127]
	v_mfma_f32_16x16x32_bf16 v[124:127], v[154:157], v[190:193], v[124:127]
	v_mfma_f32_16x16x32_bf16 v[108:111], v[150:153], v[194:197], v[108:111]
	v_mfma_f32_16x16x32_bf16 v[108:111], v[154:157], v[198:201], v[108:111]
	v_mfma_f32_16x16x32_bf16 v[92:95], v[150:153], v[202:205], v[92:95]
	v_mfma_f32_16x16x32_bf16 v[92:95], v[154:157], v[206:209], v[92:95]
	v_mfma_f32_16x16x32_bf16 v[76:79], v[150:153], v[210:213], v[76:79]
	v_mfma_f32_16x16x32_bf16 v[76:79], v[154:157], v[214:217], v[76:79]
	v_mfma_f32_16x16x32_bf16 v[68:71], v[158:161], v[210:213], v[68:71]
	v_mfma_f32_16x16x32_bf16 v[68:71], v[162:165], v[214:217], v[68:71]
	v_mfma_f32_16x16x32_bf16 v[84:87], v[158:161], v[202:205], v[84:87]
	v_mfma_f32_16x16x32_bf16 v[84:87], v[162:165], v[206:209], v[84:87]
	v_mfma_f32_16x16x32_bf16 v[100:103], v[158:161], v[194:197], v[100:103]
	v_mfma_f32_16x16x32_bf16 v[100:103], v[162:165], v[198:201], v[100:103]
	v_mfma_f32_16x16x32_bf16 v[116:119], v[158:161], v[186:189], v[116:119]
	v_mfma_f32_16x16x32_bf16 v[116:119], v[162:165], v[190:193], v[116:119]
	s_setprio 0
	s_setprio 1
	v_mfma_f32_16x16x32_bf16 v[120:123], v[166:169], v[186:189], v[120:123]
	v_mfma_f32_16x16x32_bf16 v[120:123], v[170:173], v[190:193], v[120:123]
	v_mfma_f32_16x16x32_bf16 v[104:107], v[166:169], v[194:197], v[104:107]
	v_mfma_f32_16x16x32_bf16 v[104:107], v[170:173], v[198:201], v[104:107]
	v_mfma_f32_16x16x32_bf16 v[88:91], v[166:169], v[202:205], v[88:91]
	v_mfma_f32_16x16x32_bf16 v[88:91], v[170:173], v[206:209], v[88:91]
	v_mfma_f32_16x16x32_bf16 v[72:75], v[166:169], v[210:213], v[72:75]
	v_mfma_f32_16x16x32_bf16 v[72:75], v[170:173], v[214:217], v[72:75]
	v_mfma_f32_16x16x32_bf16 v[64:67], v[174:177], v[210:213], v[64:67]
	v_mfma_f32_16x16x32_bf16 v[64:67], v[182:185], v[214:217], v[64:67]
	v_mfma_f32_16x16x32_bf16 v[80:83], v[174:177], v[202:205], v[80:83]
	v_mfma_f32_16x16x32_bf16 v[80:83], v[182:185], v[206:209], v[80:83]
	v_mfma_f32_16x16x32_bf16 v[96:99], v[174:177], v[194:197], v[96:99]
	v_mfma_f32_16x16x32_bf16 v[96:99], v[182:185], v[198:201], v[96:99]
	v_mfma_f32_16x16x32_bf16 v[112:115], v[174:177], v[186:189], v[112:115]
	v_mfma_f32_16x16x32_bf16 v[112:115], v[182:185], v[190:193], v[112:115]
	s_setprio 0
	s_barrier
	s_add_i32 s64, s55, s39
	v_lshl_add_u64 v[178:179], s[28:29], 0, v[132:133]
	s_mov_b32 m0, s64
	ds_read_b128 v[186:189], v149 offset:16384
	ds_read_b128 v[190:193], v149 offset:17408
	ds_read_b128 v[194:197], v149 offset:18432
	ds_read_b128 v[198:201], v149 offset:19456
	ds_read_b128 v[202:205], v149 offset:20480
	ds_read_b128 v[206:209], v149 offset:21504
	ds_read_b128 v[210:213], v149 offset:22528
	ds_read_b128 v[214:217], v149 offset:23552
	global_load_lds_dwordx4 v[178:179], off
	s_add_i32 m0, s64, 0x2000
	s_add_u32 s64, s28, 0x100000
	v_lshl_add_u64 v[218:219], s[28:29], 0, v[128:129]
	s_addc_u32 s65, s29, 0
	s_add_i32 s66, s56, s39
	global_load_lds_dwordx4 v[218:219], off
	v_lshl_add_u64 v[220:221], s[64:65], 0, v[132:133]
	s_mov_b32 m0, s66
	v_lshl_add_u64 v[222:223], s[30:31], 0, v[130:131]
	global_load_lds_dwordx4 v[220:221], off
	v_lshl_add_u64 v[220:221], s[64:65], 0, v[128:129]
	s_add_i32 m0, s66, 0x2000
	s_nop 0
	global_load_lds_dwordx4 v[220:221], off
	v_lshl_add_u64 v[220:221], s[30:31], 0, v[134:135]
	s_mov_b32 m0, s25
	s_nop 0
	global_load_lds_dwordx4 v[220:221], off
	s_mov_b32 m0, s42
	s_nop 0
	global_load_lds_dwordx4 v[222:223], off
	s_waitcnt vmcnt(8)
	s_waitcnt lgkmcnt(0)
	s_setprio 1
	s_barrier
; #define PG8_STAGE(bufoff, gbase, voff) do { _Pragma("unroll") for (int _i = 0; _i < 2; ++_i) \
;         __builtin_amdgcn_global_load_lds((const unsigned*)((const char*)(gbase) + (voff)[_i]), (LAS unsigned*)(lds + (bufoff) + ldsw + _i * 8192), 16, 0, 0); } while (0)
; #define PG8_LDA(dst, b, h) do { _Pragma("unroll") for (int m = 0; m < 4; ++m) _Pragma("unroll") for (int k = 0; k < 2; ++k) dst[m][k] = *(const LAS bf16x8*)(lds + PG8_SA(b, h) + aoff + m * 2048 + k * 1024); } while (0)
; #define PG8_LDB(dst, b, h) do { _Pragma("unroll") for (int n = 0; n < 2; ++n) _Pragma("unroll") for (int k = 0; k < 2; ++k) dst[n][k] = *(const LAS bf16x8*)(lds + PG8_SB(b, h) + boff + n * 2048 + k * 1024); } while (0)
; #define PG8_MMA(ai, bj, At, Bt) do { __builtin_amdgcn_s_setprio(1); _Pragma("unroll") for (int m = 0; m < 4; ++m) _Pragma("unroll") for (int n = 0; n < 2; ++n) _Pragma("unroll") for (int k = 0; k < 2; ++k) \
;         acc[ai][bj][m][n] = __builtin_amdgcn_mfma_f32_16x16x32_bf16(Bt[n][k], At[m][k], acc[ai][bj][m][n], 0, 0, 0); __builtin_amdgcn_s_setprio(0); } while (0)
; #define PG8_WAIT_V(n) asm volatile("s_waitcnt vmcnt(" #n ")" ::: "memory")
; #define PG8_WAIT_L(n) asm volatile("s_waitcnt lgkmcnt(" #n ")" ::: "memory")
; #define PG8_BAR __builtin_amdgcn_s_barrier()
; #define PG8_SCHED __builtin_amdgcn_sched_barrier(0)
; template <class Epi>
; DI void gemm_phase(LAS unsigned char* lds, const Gemm g, const StaticOrder& S, const Epi& E) {
;     ...
;             PG8_WAIT_V(8); PG8_WAIT_L(0); PG8_BAR; PG8_MMA(1, 0, At, B0); PG8_MMA(1, 1, At, B1); PG8_BAR; PG8_SCHED;
;             PG8_LDB(B0, 1, 0); PG8_LDB(B1, 1, 1); PG8_SCHED; PG8_LDA(At, 1, 0); PG8_STAGE(PG8_SA(0, 1), a2 + hstepA, voffA);
;             PG8_WAIT_V(8); PG8_WAIT_L(0); PG8_BAR; PG8_MMA(0, 0, At, B0); PG8_MMA(0, 1, At, B1); PG8_BAR; PG8_SCHED;
	v_mfma_f32_16x16x32_bf16 v[60:63], v[150:153], v[186:189], v[60:63]
	v_mfma_f32_16x16x32_bf16 v[60:63], v[154:157], v[190:193], v[60:63]
	v_mfma_f32_16x16x32_bf16 v[44:47], v[150:153], v[194:197], v[44:47]
	v_mfma_f32_16x16x32_bf16 v[44:47], v[154:157], v[198:201], v[44:47]
	v_mfma_f32_16x16x32_bf16 v[28:31], v[150:153], v[202:205], v[28:31]
	v_mfma_f32_16x16x32_bf16 v[28:31], v[154:157], v[206:209], v[28:31]
	v_mfma_f32_16x16x32_bf16 v[12:15], v[150:153], v[210:213], v[12:15]
	v_mfma_f32_16x16x32_bf16 v[12:15], v[154:157], v[214:217], v[12:15]
	v_mfma_f32_16x16x32_bf16 v[4:7], v[158:161], v[210:213], v[4:7]
	v_mfma_f32_16x16x32_bf16 v[4:7], v[162:165], v[214:217], v[4:7]
	v_mfma_f32_16x16x32_bf16 v[20:23], v[158:161], v[202:205], v[20:23]
	v_mfma_f32_16x16x32_bf16 v[20:23], v[162:165], v[206:209], v[20:23]
	v_mfma_f32_16x16x32_bf16 v[36:39], v[158:161], v[194:197], v[36:39]
	v_mfma_f32_16x16x32_bf16 v[36:39], v[162:165], v[198:201], v[36:39]
	v_mfma_f32_16x16x32_bf16 v[52:55], v[158:161], v[186:189], v[52:55]
	v_mfma_f32_16x16x32_bf16 v[52:55], v[162:165], v[190:193], v[52:55]
	s_setprio 0
	s_setprio 1
	v_mfma_f32_16x16x32_bf16 v[56:59], v[166:169], v[186:189], v[56:59]
	v_mfma_f32_16x16x32_bf16 v[56:59], v[170:173], v[190:193], v[56:59]
	v_mfma_f32_16x16x32_bf16 v[40:43], v[166:169], v[194:197], v[40:43]
	v_mfma_f32_16x16x32_bf16 v[40:43], v[170:173], v[198:201], v[40:43]
	v_mfma_f32_16x16x32_bf16 v[24:27], v[166:169], v[202:205], v[24:27]
	v_mfma_f32_16x16x32_bf16 v[24:27], v[170:173], v[206:209], v[24:27]
	v_mfma_f32_16x16x32_bf16 v[8:11], v[166:169], v[210:213], v[8:11]
	v_mfma_f32_16x16x32_bf16 v[8:11], v[170:173], v[214:217], v[8:11]
	v_mfma_f32_16x16x32_bf16 v[0:3], v[174:177], v[210:213], v[0:3]
	v_mfma_f32_16x16x32_bf16 v[0:3], v[182:185], v[214:217], v[0:3]
	v_mfma_f32_16x16x32_bf16 v[16:19], v[174:177], v[202:205], v[16:19]
	v_mfma_f32_16x16x32_bf16 v[16:19], v[182:185], v[206:209], v[16:19]
	v_mfma_f32_16x16x32_bf16 v[32:35], v[174:177], v[194:197], v[32:35]
	v_mfma_f32_16x16x32_bf16 v[32:35], v[182:185], v[198:201], v[32:35]
	v_mfma_f32_16x16x32_bf16 v[48:51], v[174:177], v[186:189], v[48:51]
	v_mfma_f32_16x16x32_bf16 v[48:51], v[182:185], v[190:193], v[48:51]
	s_setprio 0
	s_barrier
	s_add_i32 s64, 0, 0x18000
	s_add_i32 s65, 0, 0x1c000
	v_add_u32_e32 v162, s64, v145
	v_add_u32_e32 v181, s65, v145
	ds_read_b128 v[150:153], v162
	ds_read_b128 v[154:157], v162 offset:1024
	ds_read_b128 v[158:161], v162 offset:2048
	ds_read_b128 v[162:165], v162 offset:3072
	ds_read_b128 v[166:169], v181
	ds_read_b128 v[170:173], v181 offset:1024
	ds_read_b128 v[174:177], v181 offset:2048
	ds_read_b128 v[182:185], v181 offset:3072
	s_add_u32 s30, s30, 0x100000
	s_addc_u32 s31, s31, 0
	s_mov_b32 m0, s43
	v_lshl_add_u64 v[224:225], s[30:31], 0, v[134:135]
	ds_read_b128 v[186:189], v149 offset:32768
	ds_read_b128 v[190:193], v149 offset:33792
	ds_read_b128 v[194:197], v149 offset:34816
	ds_read_b128 v[198:201], v149 offset:35840
	ds_read_b128 v[202:205], v149 offset:36864
	ds_read_b128 v[206:209], v149 offset:37888
	ds_read_b128 v[210:213], v149 offset:38912
	ds_read_b128 v[214:217], v149 offset:39936
	global_load_lds_dwordx4 v[224:225], off
	v_lshl_add_u64 v[224:225], s[30:31], 0, v[130:131]
	s_mov_b32 m0, s46
	s_nop 0
	global_load_lds_dwordx4 v[224:225], off
	s_waitcnt vmcnt(8)
	s_waitcnt lgkmcnt(0)
	s_setprio 1
	s_barrier
	v_mfma_f32_16x16x32_bf16 v[124:127], v[150:153], v[186:189], v[124:127]
	v_mfma_f32_16x16x32_bf16 v[124:127], v[154:157], v[190:193], v[124:127]
	v_mfma_f32_16x16x32_bf16 v[108:111], v[150:153], v[194:197], v[108:111]
	v_mfma_f32_16x16x32_bf16 v[108:111], v[154:157], v[198:201], v[108:111]
	v_mfma_f32_16x16x32_bf16 v[92:95], v[150:153], v[202:205], v[92:95]
	v_mfma_f32_16x16x32_bf16 v[92:95], v[154:157], v[206:209], v[92:95]
	v_mfma_f32_16x16x32_bf16 v[76:79], v[150:153], v[210:213], v[76:79]
	v_mfma_f32_16x16x32_bf16 v[76:79], v[154:157], v[214:217], v[76:79]
	v_mfma_f32_16x16x32_bf16 v[68:71], v[158:161], v[210:213], v[68:71]
	v_mfma_f32_16x16x32_bf16 v[68:71], v[162:165], v[214:217], v[68:71]
	v_mfma_f32_16x16x32_bf16 v[84:87], v[158:161], v[202:205], v[84:87]
	v_mfma_f32_16x16x32_bf16 v[84:87], v[162:165], v[206:209], v[84:87]
	v_mfma_f32_16x16x32_bf16 v[100:103], v[158:161], v[194:197], v[100:103]
	v_mfma_f32_16x16x32_bf16 v[100:103], v[162:165], v[198:201], v[100:103]
	v_mfma_f32_16x16x32_bf16 v[116:119], v[158:161], v[186:189], v[116:119]
	v_mfma_f32_16x16x32_bf16 v[116:119], v[162:165], v[190:193], v[116:119]
	s_setprio 0
	s_setprio 1
	v_mfma_f32_16x16x32_bf16 v[120:123], v[166:169], v[186:189], v[120:123]
	v_mfma_f32_16x16x32_bf16 v[120:123], v[170:173], v[190:193], v[120:123]
	v_mfma_f32_16x16x32_bf16 v[104:107], v[166:169], v[194:197], v[104:107]
	v_mfma_f32_16x16x32_bf16 v[104:107], v[170:173], v[198:201], v[104:107]
	v_mfma_f32_16x16x32_bf16 v[88:91], v[166:169], v[202:205], v[88:91]
	v_mfma_f32_16x16x32_bf16 v[88:91], v[170:173], v[206:209], v[88:91]
	v_mfma_f32_16x16x32_bf16 v[72:75], v[166:169], v[210:213], v[72:75]
	v_mfma_f32_16x16x32_bf16 v[72:75], v[170:173], v[214:217], v[72:75]
	v_mfma_f32_16x16x32_bf16 v[64:67], v[174:177], v[210:213], v[64:67]
	v_mfma_f32_16x16x32_bf16 v[64:67], v[182:185], v[214:217], v[64:67]
	v_mfma_f32_16x16x32_bf16 v[80:83], v[174:177], v[202:205], v[80:83]
	v_mfma_f32_16x16x32_bf16 v[80:83], v[182:185], v[206:209], v[80:83]
	v_mfma_f32_16x16x32_bf16 v[96:99], v[174:177], v[194:197], v[96:99]
	v_mfma_f32_16x16x32_bf16 v[96:99], v[182:185], v[198:201], v[96:99]
	v_mfma_f32_16x16x32_bf16 v[112:115], v[174:177], v[186:189], v[112:115]
	v_mfma_f32_16x16x32_bf16 v[112:115], v[182:185], v[190:193], v[112:115]
	s_setprio 0
	s_barrier
; #define PG8_STAGE(bufoff, gbase, voff) do { _Pragma("unroll") for (int _i = 0; _i < 2; ++_i) \
;         __builtin_amdgcn_global_load_lds((const unsigned*)((const char*)(gbase) + (voff)[_i]), (LAS unsigned*)(lds + (bufoff) + ldsw + _i * 8192), 16, 0, 0); } while (0)
; #define PG8_LDA(dst, b, h) do { _Pragma("unroll") for (int m = 0; m < 4; ++m) _Pragma("unroll") for (int k = 0; k < 2; ++k) dst[m][k] = *(const LAS bf16x8*)(lds + PG8_SA(b, h) + aoff + m * 2048 + k * 1024); } while (0)
; #define PG8_MMA(ai, bj, At, Bt) do { __builtin_amdgcn_s_setprio(1); _Pragma("unroll") for (int m = 0; m < 4; ++m) _Pragma("unroll") for (int n = 0; n < 2; ++n) _Pragma("unroll") for (int k = 0; k < 2; ++k) \
;         acc[ai][bj][m][n] = __builtin_amdgcn_mfma_f32_16x16x32_bf16(Bt[n][k], At[m][k], acc[ai][bj][m][n], 0, 0, 0); __builtin_amdgcn_s_setprio(0); } while (0)
; #define PG8_WAIT_V(n) asm volatile("s_waitcnt vmcnt(" #n ")" ::: "memory")
; #define PG8_WAIT_L(n) asm volatile("s_waitcnt lgkmcnt(" #n ")" ::: "memory")
; #define PG8_BAR __builtin_amdgcn_s_barrier()
; #define PG8_SCHED __builtin_amdgcn_sched_barrier(0)
; template <class Epi>
; DI void gemm_phase(LAS unsigned char* lds, const Gemm g, const StaticOrder& S, const Epi& E) {
;     ...
;             PG8_LDA(At, 1, 1); PG8_STAGE(PG8_SB(1, 0), b3, voffB); PG8_STAGE(PG8_SB(1, 1), b3 + hstepB, voffB); PG8_STAGE(PG8_SA(1, 0), a3, voffA);
;             PG8_WAIT_V(8); PG8_WAIT_L(0); PG8_BAR; PG8_MMA(1, 0, At, B0); PG8_MMA(1, 1, At, B1); PG8_BAR; PG8_SCHED;
;         }
	s_add_i32 s30, s64, s39
	v_lshl_add_u64 v[178:179], v[178:179], 0, s[12:13]
	s_mov_b32 m0, s30
	ds_read_b128 v[186:189], v149 offset:49152
	ds_read_b128 v[190:193], v149 offset:50176
	ds_read_b128 v[194:197], v149 offset:51200
	ds_read_b128 v[198:201], v149 offset:52224
	ds_read_b128 v[202:205], v149 offset:53248
	ds_read_b128 v[206:209], v149 offset:54272
	ds_read_b128 v[210:213], v149 offset:55296
	ds_read_b128 v[214:217], v149 offset:56320
	global_load_lds_dwordx4 v[178:179], off
	s_add_i32 m0, s30, 0x2000
	s_add_u32 s28, s28, 0x100080
	v_lshl_add_u64 v[178:179], v[218:219], 0, s[12:13]
	s_addc_u32 s29, s29, 0
	s_add_i32 s30, s65, s39
	global_load_lds_dwordx4 v[178:179], off
	v_lshl_add_u64 v[178:179], s[28:29], 0, v[132:133]
	s_mov_b32 m0, s30
	s_nop 0
	global_load_lds_dwordx4 v[178:179], off
	v_lshl_add_u64 v[178:179], s[28:29], 0, v[128:129]
	s_add_i32 m0, s30, 0x2000
	s_nop 0
	global_load_lds_dwordx4 v[178:179], off
	v_lshl_add_u64 v[178:179], v[220:221], 0, s[12:13]
	s_mov_b32 m0, s52
	s_nop 0
	global_load_lds_dwordx4 v[178:179], off
	v_lshl_add_u64 v[178:179], v[222:223], 0, s[12:13]
	s_mov_b32 m0, s53
	s_nop 0
	global_load_lds_dwordx4 v[178:179], off
	s_waitcnt vmcnt(8)
	s_waitcnt lgkmcnt(0)
	s_setprio 1
	s_barrier
	v_mfma_f32_16x16x32_bf16 v[60:63], v[150:153], v[186:189], v[60:63]
	v_mfma_f32_16x16x32_bf16 v[60:63], v[154:157], v[190:193], v[60:63]
	v_mfma_f32_16x16x32_bf16 v[44:47], v[150:153], v[194:197], v[44:47]
	v_mfma_f32_16x16x32_bf16 v[44:47], v[154:157], v[198:201], v[44:47]
	v_mfma_f32_16x16x32_bf16 v[28:31], v[150:153], v[202:205], v[28:31]
	v_mfma_f32_16x16x32_bf16 v[28:31], v[154:157], v[206:209], v[28:31]
	v_mfma_f32_16x16x32_bf16 v[12:15], v[150:153], v[210:213], v[12:15]
	v_mfma_f32_16x16x32_bf16 v[12:15], v[154:157], v[214:217], v[12:15]
	v_mfma_f32_16x16x32_bf16 v[4:7], v[158:161], v[210:213], v[4:7]
	v_mfma_f32_16x16x32_bf16 v[4:7], v[162:165], v[214:217], v[4:7]
	v_mfma_f32_16x16x32_bf16 v[20:23], v[158:161], v[202:205], v[20:23]
	v_mfma_f32_16x16x32_bf16 v[20:23], v[162:165], v[206:209], v[20:23]
	v_mfma_f32_16x16x32_bf16 v[36:39], v[158:161], v[194:197], v[36:39]
	v_mfma_f32_16x16x32_bf16 v[36:39], v[162:165], v[198:201], v[36:39]
	v_mfma_f32_16x16x32_bf16 v[52:55], v[158:161], v[186:189], v[52:55]
	v_mfma_f32_16x16x32_bf16 v[52:55], v[162:165], v[190:193], v[52:55]
	s_setprio 0
	s_setprio 1
	v_mfma_f32_16x16x32_bf16 v[56:59], v[166:169], v[186:189], v[56:59]
	v_mfma_f32_16x16x32_bf16 v[56:59], v[170:173], v[190:193], v[56:59]
	v_mfma_f32_16x16x32_bf16 v[40:43], v[166:169], v[194:197], v[40:43]
	v_mfma_f32_16x16x32_bf16 v[40:43], v[170:173], v[198:201], v[40:43]
	v_mfma_f32_16x16x32_bf16 v[24:27], v[166:169], v[202:205], v[24:27]
	v_mfma_f32_16x16x32_bf16 v[24:27], v[170:173], v[206:209], v[24:27]
	v_mfma_f32_16x16x32_bf16 v[8:11], v[166:169], v[210:213], v[8:11]
	v_mfma_f32_16x16x32_bf16 v[8:11], v[170:173], v[214:217], v[8:11]
	v_mfma_f32_16x16x32_bf16 v[0:3], v[174:177], v[210:213], v[0:3]
	v_mfma_f32_16x16x32_bf16 v[0:3], v[182:185], v[214:217], v[0:3]
	v_mfma_f32_16x16x32_bf16 v[16:19], v[174:177], v[202:205], v[16:19]
	v_mfma_f32_16x16x32_bf16 v[16:19], v[182:185], v[206:209], v[16:19]
	v_mfma_f32_16x16x32_bf16 v[32:35], v[174:177], v[194:197], v[32:35]
	v_mfma_f32_16x16x32_bf16 v[32:35], v[182:185], v[198:201], v[32:35]
	v_mfma_f32_16x16x32_bf16 v[48:51], v[174:177], v[186:189], v[48:51]
	v_mfma_f32_16x16x32_bf16 v[48:51], v[182:185], v[190:193], v[48:51]
	s_setprio 0
	s_barrier
	s_add_u32 s26, s26, 0x100
	s_addc_u32 s27, s27, 0
	s_add_u32 s61, s61, 0x100
	s_addc_u32 s62, s62, 0
	s_cmp_ge_i32 s63, s51
	s_mov_b32 s28, s63
	s_cbranch_scc0 .LBB0_705

; #define PG8_STAGE(bufoff, gbase, voff) do { _Pragma("unroll") for (int _i = 0; _i < 2; ++_i) \
;         __builtin_amdgcn_global_load_lds((const unsigned*)((const char*)(gbase) + (voff)[_i]), (LAS unsigned*)(lds + (bufoff) + ldsw + _i * 8192), 16, 0, 0); } while (0)
; #define PG8_LDA(dst, b, h) do { _Pragma("unroll") for (int m = 0; m < 4; ++m) _Pragma("unroll") for (int k = 0; k < 2; ++k) dst[m][k] = *(const LAS bf16x8*)(lds + PG8_SA(b, h) + aoff + m * 2048 + k * 1024); } while (0)
; #define PG8_LDB(dst, b, h) do { _Pragma("unroll") for (int n = 0; n < 2; ++n) _Pragma("unroll") for (int k = 0; k < 2; ++k) dst[n][k] = *(const LAS bf16x8*)(lds + PG8_SB(b, h) + boff + n * 2048 + k * 1024); } while (0)
; #define PG8_MMA(ai, bj, At, Bt) do { __builtin_amdgcn_s_setprio(1); _Pragma("unroll") for (int m = 0; m < 4; ++m) _Pragma("unroll") for (int n = 0; n < 2; ++n) _Pragma("unroll") for (int k = 0; k < 2; ++k) \
;         acc[ai][bj][m][n] = __builtin_amdgcn_mfma_f32_16x16x32_bf16(Bt[n][k], At[m][k], acc[ai][bj][m][n], 0, 0, 0); __builtin_amdgcn_s_setprio(0); } while (0)
; #define PG8_WAIT_V(n) asm volatile("s_waitcnt vmcnt(" #n ")" ::: "memory")
; #define PG8_WAIT_L(n) asm volatile("s_waitcnt lgkmcnt(" #n ")" ::: "memory")
; #define PG8_BAR __builtin_amdgcn_s_barrier()
; #define PG8_SCHED __builtin_amdgcn_sched_barrier(0)
; template <class Epi>
; DI void gemm_phase(LAS unsigned char* lds, const Gemm g, const StaticOrder& S, const Epi& E) {
;     ...
;             PG8_LDB(B0, 0, 0); PG8_LDB(B1, 0, 1); PG8_SCHED; PG8_LDA(At, 0, 0); PG8_STAGE(PG8_SA(1, 1), a1 + hstepA, voffA);
;             PG8_WAIT_V(8); PG8_WAIT_L(0); PG8_BAR; PG8_MMA(0, 0, At, B0); PG8_MMA(0, 1, At, B1); PG8_BAR; PG8_SCHED;
;             PG8_LDA(At, 0, 1); PG8_STAGE(PG8_SB(0, 0), b2, voffB); PG8_STAGE(PG8_SB(0, 1), b2 + hstepB, voffB); PG8_STAGE(PG8_SA(0, 0), a2, voffA);
;             PG8_WAIT_V(8); PG8_WAIT_L(0); PG8_BAR; PG8_MMA(1, 0, At, B0); PG8_MMA(1, 1, At, B1); PG8_BAR; PG8_SCHED;
.LBB0_727:
	ds_read_b128 v[150:153], v147
	ds_read_b128 v[154:157], v147 offset:1024
	ds_read_b128 v[158:161], v147 offset:2048
	ds_read_b128 v[162:165], v147 offset:3072
	ds_read_b128 v[166:169], v148
	ds_read_b128 v[170:173], v148 offset:1024
	ds_read_b128 v[174:177], v148 offset:2048
	ds_read_b128 v[182:185], v148 offset:3072
	s_add_i32 s74, s38, 2
	s_add_u32 s39, s34, 0xffff0080
	s_addc_u32 s40, s35, -1
	s_cmp_eq_u32 s60, s38
	s_cselect_b32 s38, s71, s72
	s_cselect_b32 s41, s25, s40
	s_cselect_b32 s40, s27, s39
	s_cselect_b32 s39, s70, s73
	v_lshl_add_u64 v[178:179], s[34:35], 0, v[136:137]
	s_add_i32 m0, s51, 0xc000
	ds_read_b128 v[186:189], v149
	ds_read_b128 v[190:193], v149 offset:1024
	ds_read_b128 v[194:197], v149 offset:2048
	ds_read_b128 v[198:201], v149 offset:3072
	ds_read_b128 v[202:205], v149 offset:4096
	ds_read_b128 v[206:209], v149 offset:5120
	ds_read_b128 v[210:213], v149 offset:6144
	ds_read_b128 v[214:217], v149 offset:7168
	global_load_lds_dwordx4 v[178:179], off
	v_lshl_add_u64 v[178:179], s[34:35], 0, v[138:139]
	s_add_i32 m0, s51, 0xe000
	s_nop 0
	global_load_lds_dwordx4 v[178:179], off
	s_waitcnt vmcnt(8)
	s_waitcnt lgkmcnt(0)
	s_setprio 1
	s_barrier
	v_mfma_f32_16x16x32_bf16 v[120:123], v[150:153], v[186:189], v[120:123]
	v_mfma_f32_16x16x32_bf16 v[120:123], v[154:157], v[190:193], v[120:123]
	v_mfma_f32_16x16x32_bf16 v[108:111], v[150:153], v[194:197], v[108:111]
	v_mfma_f32_16x16x32_bf16 v[108:111], v[154:157], v[198:201], v[108:111]
	v_mfma_f32_16x16x32_bf16 v[92:95], v[150:153], v[202:205], v[92:95]
	v_mfma_f32_16x16x32_bf16 v[92:95], v[154:157], v[206:209], v[92:95]
	v_mfma_f32_16x16x32_bf16 v[76:79], v[150:153], v[210:213], v[76:79]
	v_mfma_f32_16x16x32_bf16 v[76:79], v[154:157], v[214:217], v[76:79]
	v_mfma_f32_16x16x32_bf16 v[72:75], v[158:161], v[210:213], v[72:75]
	v_mfma_f32_16x16x32_bf16 v[72:75], v[162:165], v[214:217], v[72:75]
	v_mfma_f32_16x16x32_bf16 v[88:91], v[158:161], v[202:205], v[88:91]
	v_mfma_f32_16x16x32_bf16 v[88:91], v[162:165], v[206:209], v[88:91]
	v_mfma_f32_16x16x32_bf16 v[104:107], v[158:161], v[194:197], v[104:107]
	v_mfma_f32_16x16x32_bf16 v[104:107], v[162:165], v[198:201], v[104:107]
	v_mfma_f32_16x16x32_bf16 v[124:127], v[158:161], v[186:189], v[124:127]
	v_mfma_f32_16x16x32_bf16 v[124:127], v[162:165], v[190:193], v[124:127]
	s_setprio 0
	s_setprio 1
	v_mfma_f32_16x16x32_bf16 v[116:119], v[166:169], v[186:189], v[116:119]
	v_mfma_f32_16x16x32_bf16 v[116:119], v[170:173], v[190:193], v[116:119]
	v_mfma_f32_16x16x32_bf16 v[100:103], v[166:169], v[194:197], v[100:103]
	v_mfma_f32_16x16x32_bf16 v[100:103], v[170:173], v[198:201], v[100:103]
	v_mfma_f32_16x16x32_bf16 v[84:87], v[166:169], v[202:205], v[84:87]
	v_mfma_f32_16x16x32_bf16 v[84:87], v[170:173], v[206:209], v[84:87]
	v_mfma_f32_16x16x32_bf16 v[68:71], v[166:169], v[210:213], v[68:71]
	v_mfma_f32_16x16x32_bf16 v[68:71], v[170:173], v[214:217], v[68:71]
	v_mfma_f32_16x16x32_bf16 v[64:67], v[174:177], v[210:213], v[64:67]
	v_mfma_f32_16x16x32_bf16 v[64:67], v[182:185], v[214:217], v[64:67]
	v_mfma_f32_16x16x32_bf16 v[80:83], v[174:177], v[202:205], v[80:83]
	v_mfma_f32_16x16x32_bf16 v[80:83], v[182:185], v[206:209], v[80:83]
	v_mfma_f32_16x16x32_bf16 v[96:99], v[174:177], v[194:197], v[96:99]
	v_mfma_f32_16x16x32_bf16 v[96:99], v[182:185], v[198:201], v[96:99]
	v_mfma_f32_16x16x32_bf16 v[112:115], v[174:177], v[186:189], v[112:115]
	v_mfma_f32_16x16x32_bf16 v[112:115], v[182:185], v[190:193], v[112:115]
	s_setprio 0
	s_barrier
	s_add_i32 s75, s62, s50
	v_lshl_add_u64 v[178:179], s[38:39], 0, v[132:133]
	s_mov_b32 m0, s75
	ds_read_b128 v[186:189], v149 offset:16384
	ds_read_b128 v[190:193], v149 offset:17408
	ds_read_b128 v[194:197], v149 offset:18432
	ds_read_b128 v[198:201], v149 offset:19456
	ds_read_b128 v[202:205], v149 offset:20480
	ds_read_b128 v[206:209], v149 offset:21504
	ds_read_b128 v[210:213], v149 offset:22528
	ds_read_b128 v[214:217], v149 offset:23552
	global_load_lds_dwordx4 v[178:179], off
	s_add_i32 m0, s75, 0x2000
	s_add_u32 s76, s38, 0x10000
	v_lshl_add_u64 v[218:219], s[38:39], 0, v[128:129]
	s_addc_u32 s77, s39, 0
	s_add_i32 s75, s63, s50
	global_load_lds_dwordx4 v[218:219], off
	v_lshl_add_u64 v[220:221], s[76:77], 0, v[132:133]
	s_mov_b32 m0, s75
	v_lshl_add_u64 v[222:223], s[40:41], 0, v[130:131]
	global_load_lds_dwordx4 v[220:221], off
	v_lshl_add_u64 v[220:221], s[76:77], 0, v[128:129]
	s_add_i32 m0, s75, 0x2000
	s_nop 0
	global_load_lds_dwordx4 v[220:221], off
	v_lshl_add_u64 v[220:221], s[40:41], 0, v[134:135]
	s_mov_b32 m0, s51
	s_nop 0
	global_load_lds_dwordx4 v[220:221], off
	s_mov_b32 m0, s52
	s_nop 0
	global_load_lds_dwordx4 v[222:223], off
	s_waitcnt vmcnt(8)
	s_waitcnt lgkmcnt(0)
	s_setprio 1
	s_barrier
; #define PG8_STAGE(bufoff, gbase, voff) do { _Pragma("unroll") for (int _i = 0; _i < 2; ++_i) \
;         __builtin_amdgcn_global_load_lds((const unsigned*)((const char*)(gbase) + (voff)[_i]), (LAS unsigned*)(lds + (bufoff) + ldsw + _i * 8192), 16, 0, 0); } while (0)
; #define PG8_LDA(dst, b, h) do { _Pragma("unroll") for (int m = 0; m < 4; ++m) _Pragma("unroll") for (int k = 0; k < 2; ++k) dst[m][k] = *(const LAS bf16x8*)(lds + PG8_SA(b, h) + aoff + m * 2048 + k * 1024); } while (0)
; #define PG8_LDB(dst, b, h) do { _Pragma("unroll") for (int n = 0; n < 2; ++n) _Pragma("unroll") for (int k = 0; k < 2; ++k) dst[n][k] = *(const LAS bf16x8*)(lds + PG8_SB(b, h) + boff + n * 2048 + k * 1024); } while (0)
; #define PG8_MMA(ai, bj, At, Bt) do { __builtin_amdgcn_s_setprio(1); _Pragma("unroll") for (int m = 0; m < 4; ++m) _Pragma("unroll") for (int n = 0; n < 2; ++n) _Pragma("unroll") for (int k = 0; k < 2; ++k) \
;         acc[ai][bj][m][n] = __builtin_amdgcn_mfma_f32_16x16x32_bf16(Bt[n][k], At[m][k], acc[ai][bj][m][n], 0, 0, 0); __builtin_amdgcn_s_setprio(0); } while (0)
; #define PG8_WAIT_V(n) asm volatile("s_waitcnt vmcnt(" #n ")" ::: "memory")
; #define PG8_WAIT_L(n) asm volatile("s_waitcnt lgkmcnt(" #n ")" ::: "memory")
; #define PG8_BAR __builtin_amdgcn_s_barrier()
; #define PG8_SCHED __builtin_amdgcn_sched_barrier(0)
; template <class Epi>
; DI void gemm_phase(LAS unsigned char* lds, const Gemm g, const StaticOrder& S, const Epi& E) {
;     ...
;             PG8_WAIT_V(8); PG8_WAIT_L(0); PG8_BAR; PG8_MMA(1, 0, At, B0); PG8_MMA(1, 1, At, B1); PG8_BAR; PG8_SCHED;
;             PG8_LDB(B0, 1, 0); PG8_LDB(B1, 1, 1); PG8_SCHED; PG8_LDA(At, 1, 0); PG8_STAGE(PG8_SA(0, 1), a2 + hstepA, voffA);
;             PG8_WAIT_V(8); PG8_WAIT_L(0); PG8_BAR; PG8_MMA(0, 0, At, B0); PG8_MMA(0, 1, At, B1); PG8_BAR; PG8_SCHED;
	v_mfma_f32_16x16x32_bf16 v[60:63], v[150:153], v[186:189], v[60:63]
	v_mfma_f32_16x16x32_bf16 v[60:63], v[154:157], v[190:193], v[60:63]
	v_mfma_f32_16x16x32_bf16 v[44:47], v[150:153], v[194:197], v[44:47]
	v_mfma_f32_16x16x32_bf16 v[44:47], v[154:157], v[198:201], v[44:47]
	v_mfma_f32_16x16x32_bf16 v[28:31], v[150:153], v[202:205], v[28:31]
	v_mfma_f32_16x16x32_bf16 v[28:31], v[154:157], v[206:209], v[28:31]
	v_mfma_f32_16x16x32_bf16 v[12:15], v[150:153], v[210:213], v[12:15]
	v_mfma_f32_16x16x32_bf16 v[12:15], v[154:157], v[214:217], v[12:15]
	v_mfma_f32_16x16x32_bf16 v[8:11], v[158:161], v[210:213], v[8:11]
	v_mfma_f32_16x16x32_bf16 v[8:11], v[162:165], v[214:217], v[8:11]
	v_mfma_f32_16x16x32_bf16 v[24:27], v[158:161], v[202:205], v[24:27]
	v_mfma_f32_16x16x32_bf16 v[24:27], v[162:165], v[206:209], v[24:27]
	v_mfma_f32_16x16x32_bf16 v[40:43], v[158:161], v[194:197], v[40:43]
	v_mfma_f32_16x16x32_bf16 v[40:43], v[162:165], v[198:201], v[40:43]
	v_mfma_f32_16x16x32_bf16 v[56:59], v[158:161], v[186:189], v[56:59]
	v_mfma_f32_16x16x32_bf16 v[56:59], v[162:165], v[190:193], v[56:59]
	s_setprio 0
	s_setprio 1
	v_mfma_f32_16x16x32_bf16 v[52:55], v[166:169], v[186:189], v[52:55]
	v_mfma_f32_16x16x32_bf16 v[52:55], v[170:173], v[190:193], v[52:55]
	v_mfma_f32_16x16x32_bf16 v[36:39], v[166:169], v[194:197], v[36:39]
	v_mfma_f32_16x16x32_bf16 v[36:39], v[170:173], v[198:201], v[36:39]
	v_mfma_f32_16x16x32_bf16 v[20:23], v[166:169], v[202:205], v[20:23]
	v_mfma_f32_16x16x32_bf16 v[20:23], v[170:173], v[206:209], v[20:23]
	v_mfma_f32_16x16x32_bf16 v[4:7], v[166:169], v[210:213], v[4:7]
	v_mfma_f32_16x16x32_bf16 v[4:7], v[170:173], v[214:217], v[4:7]
	v_mfma_f32_16x16x32_bf16 v[0:3], v[174:177], v[210:213], v[0:3]
	v_mfma_f32_16x16x32_bf16 v[0:3], v[182:185], v[214:217], v[0:3]
	v_mfma_f32_16x16x32_bf16 v[16:19], v[174:177], v[202:205], v[16:19]
	v_mfma_f32_16x16x32_bf16 v[16:19], v[182:185], v[206:209], v[16:19]
	v_mfma_f32_16x16x32_bf16 v[32:35], v[174:177], v[194:197], v[32:35]
	v_mfma_f32_16x16x32_bf16 v[32:35], v[182:185], v[198:201], v[32:35]
	v_mfma_f32_16x16x32_bf16 v[48:51], v[174:177], v[186:189], v[48:51]
	v_mfma_f32_16x16x32_bf16 v[48:51], v[182:185], v[190:193], v[48:51]
	s_setprio 0
	s_barrier
	s_add_i32 s75, 0, 0x18000
	s_add_i32 s76, 0, 0x1c000
	v_add_u32_e32 v162, s75, v145
	v_add_u32_e32 v181, s76, v145
	ds_read_b128 v[150:153], v162
	ds_read_b128 v[154:157], v162 offset:1024
	ds_read_b128 v[158:161], v162 offset:2048
	ds_read_b128 v[162:165], v162 offset:3072
	ds_read_b128 v[166:169], v181
	ds_read_b128 v[170:173], v181 offset:1024
	ds_read_b128 v[174:177], v181 offset:2048
	ds_read_b128 v[182:185], v181 offset:3072
	s_add_u32 s40, s40, 0x10000
	s_addc_u32 s41, s41, 0
	s_mov_b32 m0, s53
	v_lshl_add_u64 v[224:225], s[40:41], 0, v[134:135]
	ds_read_b128 v[186:189], v149 offset:32768
	ds_read_b128 v[190:193], v149 offset:33792
	ds_read_b128 v[194:197], v149 offset:34816
	ds_read_b128 v[198:201], v149 offset:35840
	ds_read_b128 v[202:205], v149 offset:36864
	ds_read_b128 v[206:209], v149 offset:37888
	ds_read_b128 v[210:213], v149 offset:38912
	ds_read_b128 v[214:217], v149 offset:39936
	global_load_lds_dwordx4 v[224:225], off
	v_lshl_add_u64 v[224:225], s[40:41], 0, v[130:131]
	s_mov_b32 m0, s54
	s_nop 0
	global_load_lds_dwordx4 v[224:225], off
	s_waitcnt vmcnt(8)
	s_waitcnt lgkmcnt(0)
	s_setprio 1
	s_barrier
	v_mfma_f32_16x16x32_bf16 v[120:123], v[150:153], v[186:189], v[120:123]
	v_mfma_f32_16x16x32_bf16 v[120:123], v[154:157], v[190:193], v[120:123]
	v_mfma_f32_16x16x32_bf16 v[108:111], v[150:153], v[194:197], v[108:111]
	v_mfma_f32_16x16x32_bf16 v[108:111], v[154:157], v[198:201], v[108:111]
	v_mfma_f32_16x16x32_bf16 v[92:95], v[150:153], v[202:205], v[92:95]
	v_mfma_f32_16x16x32_bf16 v[92:95], v[154:157], v[206:209], v[92:95]
	v_mfma_f32_16x16x32_bf16 v[76:79], v[150:153], v[210:213], v[76:79]
	v_mfma_f32_16x16x32_bf16 v[76:79], v[154:157], v[214:217], v[76:79]
	v_mfma_f32_16x16x32_bf16 v[72:75], v[158:161], v[210:213], v[72:75]
	v_mfma_f32_16x16x32_bf16 v[72:75], v[162:165], v[214:217], v[72:75]
	v_mfma_f32_16x16x32_bf16 v[88:91], v[158:161], v[202:205], v[88:91]
	v_mfma_f32_16x16x32_bf16 v[88:91], v[162:165], v[206:209], v[88:91]
	v_mfma_f32_16x16x32_bf16 v[104:107], v[158:161], v[194:197], v[104:107]
	v_mfma_f32_16x16x32_bf16 v[104:107], v[162:165], v[198:201], v[104:107]
	v_mfma_f32_16x16x32_bf16 v[124:127], v[158:161], v[186:189], v[124:127]
	v_mfma_f32_16x16x32_bf16 v[124:127], v[162:165], v[190:193], v[124:127]
	s_setprio 0
	s_setprio 1
	v_mfma_f32_16x16x32_bf16 v[116:119], v[166:169], v[186:189], v[116:119]
	v_mfma_f32_16x16x32_bf16 v[116:119], v[170:173], v[190:193], v[116:119]
	v_mfma_f32_16x16x32_bf16 v[100:103], v[166:169], v[194:197], v[100:103]
	v_mfma_f32_16x16x32_bf16 v[100:103], v[170:173], v[198:201], v[100:103]
	v_mfma_f32_16x16x32_bf16 v[84:87], v[166:169], v[202:205], v[84:87]
	v_mfma_f32_16x16x32_bf16 v[84:87], v[170:173], v[206:209], v[84:87]
	v_mfma_f32_16x16x32_bf16 v[68:71], v[166:169], v[210:213], v[68:71]
	v_mfma_f32_16x16x32_bf16 v[68:71], v[170:173], v[214:217], v[68:71]
	v_mfma_f32_16x16x32_bf16 v[64:67], v[174:177], v[210:213], v[64:67]
	v_mfma_f32_16x16x32_bf16 v[64:67], v[182:185], v[214:217], v[64:67]
	v_mfma_f32_16x16x32_bf16 v[80:83], v[174:177], v[202:205], v[80:83]
	v_mfma_f32_16x16x32_bf16 v[80:83], v[182:185], v[206:209], v[80:83]
	v_mfma_f32_16x16x32_bf16 v[96:99], v[174:177], v[194:197], v[96:99]
	v_mfma_f32_16x16x32_bf16 v[96:99], v[182:185], v[198:201], v[96:99]
	v_mfma_f32_16x16x32_bf16 v[112:115], v[174:177], v[186:189], v[112:115]
	v_mfma_f32_16x16x32_bf16 v[112:115], v[182:185], v[190:193], v[112:115]
	s_setprio 0
	s_barrier
; #define PG8_STAGE(bufoff, gbase, voff) do { _Pragma("unroll") for (int _i = 0; _i < 2; ++_i) \
;         __builtin_amdgcn_global_load_lds((const unsigned*)((const char*)(gbase) + (voff)[_i]), (LAS unsigned*)(lds + (bufoff) + ldsw + _i * 8192), 16, 0, 0); } while (0)
; #define PG8_LDA(dst, b, h) do { _Pragma("unroll") for (int m = 0; m < 4; ++m) _Pragma("unroll") for (int k = 0; k < 2; ++k) dst[m][k] = *(const LAS bf16x8*)(lds + PG8_SA(b, h) + aoff + m * 2048 + k * 1024); } while (0)
; #define PG8_MMA(ai, bj, At, Bt) do { __builtin_amdgcn_s_setprio(1); _Pragma("unroll") for (int m = 0; m < 4; ++m) _Pragma("unroll") for (int n = 0; n < 2; ++n) _Pragma("unroll") for (int k = 0; k < 2; ++k) \
;         acc[ai][bj][m][n] = __builtin_amdgcn_mfma_f32_16x16x32_bf16(Bt[n][k], At[m][k], acc[ai][bj][m][n], 0, 0, 0); __builtin_amdgcn_s_setprio(0); } while (0)
; #define PG8_WAIT_V(n) asm volatile("s_waitcnt vmcnt(" #n ")" ::: "memory")
; #define PG8_WAIT_L(n) asm volatile("s_waitcnt lgkmcnt(" #n ")" ::: "memory")
; #define PG8_BAR __builtin_amdgcn_s_barrier()
; #define PG8_SCHED __builtin_amdgcn_sched_barrier(0)
; template <class Epi>
; DI void gemm_phase(LAS unsigned char* lds, const Gemm g, const StaticOrder& S, const Epi& E) {
;     ...
;             PG8_LDA(At, 1, 1); PG8_STAGE(PG8_SB(1, 0), b3, voffB); PG8_STAGE(PG8_SB(1, 1), b3 + hstepB, voffB); PG8_STAGE(PG8_SA(1, 0), a3, voffA);
;             PG8_WAIT_V(8); PG8_WAIT_L(0); PG8_BAR; PG8_MMA(1, 0, At, B0); PG8_MMA(1, 1, At, B1); PG8_BAR; PG8_SCHED;
;         }
	s_add_i32 s40, s75, s50
	v_lshl_add_u64 v[178:179], v[178:179], 0, s[10:11]
	s_mov_b32 m0, s40
	ds_read_b128 v[186:189], v149 offset:49152
	ds_read_b128 v[190:193], v149 offset:50176
	ds_read_b128 v[194:197], v149 offset:51200
	ds_read_b128 v[198:201], v149 offset:52224
	ds_read_b128 v[202:205], v149 offset:53248
	ds_read_b128 v[206:209], v149 offset:54272
	ds_read_b128 v[210:213], v149 offset:55296
	ds_read_b128 v[214:217], v149 offset:56320
	global_load_lds_dwordx4 v[178:179], off
	s_add_i32 m0, s40, 0x2000
	s_add_u32 s38, s38, 0x10080
	v_lshl_add_u64 v[178:179], v[218:219], 0, s[10:11]
	s_addc_u32 s39, s39, 0
	s_add_i32 s40, s76, s50
	global_load_lds_dwordx4 v[178:179], off
	v_lshl_add_u64 v[178:179], s[38:39], 0, v[132:133]
	s_mov_b32 m0, s40
	s_nop 0
	global_load_lds_dwordx4 v[178:179], off
	v_lshl_add_u64 v[178:179], s[38:39], 0, v[128:129]
	s_add_i32 m0, s40, 0x2000
	s_nop 0
	global_load_lds_dwordx4 v[178:179], off
	v_lshl_add_u64 v[178:179], v[220:221], 0, s[10:11]
	s_mov_b32 m0, s58
	s_nop 0
	global_load_lds_dwordx4 v[178:179], off
	v_lshl_add_u64 v[178:179], v[222:223], 0, s[10:11]
	s_mov_b32 m0, s59
	s_nop 0
	global_load_lds_dwordx4 v[178:179], off
	s_waitcnt vmcnt(8)
	s_waitcnt lgkmcnt(0)
	s_setprio 1
	s_barrier
	v_mfma_f32_16x16x32_bf16 v[60:63], v[150:153], v[186:189], v[60:63]
	v_mfma_f32_16x16x32_bf16 v[60:63], v[154:157], v[190:193], v[60:63]
	v_mfma_f32_16x16x32_bf16 v[44:47], v[150:153], v[194:197], v[44:47]
	v_mfma_f32_16x16x32_bf16 v[44:47], v[154:157], v[198:201], v[44:47]
	v_mfma_f32_16x16x32_bf16 v[28:31], v[150:153], v[202:205], v[28:31]
	v_mfma_f32_16x16x32_bf16 v[28:31], v[154:157], v[206:209], v[28:31]
	v_mfma_f32_16x16x32_bf16 v[12:15], v[150:153], v[210:213], v[12:15]
	v_mfma_f32_16x16x32_bf16 v[12:15], v[154:157], v[214:217], v[12:15]
	v_mfma_f32_16x16x32_bf16 v[8:11], v[158:161], v[210:213], v[8:11]
	v_mfma_f32_16x16x32_bf16 v[8:11], v[162:165], v[214:217], v[8:11]
	v_mfma_f32_16x16x32_bf16 v[24:27], v[158:161], v[202:205], v[24:27]
	v_mfma_f32_16x16x32_bf16 v[24:27], v[162:165], v[206:209], v[24:27]
	v_mfma_f32_16x16x32_bf16 v[40:43], v[158:161], v[194:197], v[40:43]
	v_mfma_f32_16x16x32_bf16 v[40:43], v[162:165], v[198:201], v[40:43]
	v_mfma_f32_16x16x32_bf16 v[56:59], v[158:161], v[186:189], v[56:59]
	v_mfma_f32_16x16x32_bf16 v[56:59], v[162:165], v[190:193], v[56:59]
	s_setprio 0
	s_setprio 1
	v_mfma_f32_16x16x32_bf16 v[52:55], v[166:169], v[186:189], v[52:55]
	v_mfma_f32_16x16x32_bf16 v[52:55], v[170:173], v[190:193], v[52:55]
	v_mfma_f32_16x16x32_bf16 v[36:39], v[166:169], v[194:197], v[36:39]
	v_mfma_f32_16x16x32_bf16 v[36:39], v[170:173], v[198:201], v[36:39]
	v_mfma_f32_16x16x32_bf16 v[20:23], v[166:169], v[202:205], v[20:23]
	v_mfma_f32_16x16x32_bf16 v[20:23], v[170:173], v[206:209], v[20:23]
	v_mfma_f32_16x16x32_bf16 v[4:7], v[166:169], v[210:213], v[4:7]
	v_mfma_f32_16x16x32_bf16 v[4:7], v[170:173], v[214:217], v[4:7]
	v_mfma_f32_16x16x32_bf16 v[0:3], v[174:177], v[210:213], v[0:3]
	v_mfma_f32_16x16x32_bf16 v[0:3], v[182:185], v[214:217], v[0:3]
	v_mfma_f32_16x16x32_bf16 v[16:19], v[174:177], v[202:205], v[16:19]
	v_mfma_f32_16x16x32_bf16 v[16:19], v[182:185], v[206:209], v[16:19]
	v_mfma_f32_16x16x32_bf16 v[32:35], v[174:177], v[194:197], v[32:35]
	v_mfma_f32_16x16x32_bf16 v[32:35], v[182:185], v[198:201], v[32:35]
	v_mfma_f32_16x16x32_bf16 v[48:51], v[174:177], v[186:189], v[48:51]
	v_mfma_f32_16x16x32_bf16 v[48:51], v[182:185], v[190:193], v[48:51]
	s_setprio 0
	s_barrier
	s_add_u32 s34, s34, 0x100
	s_addc_u32 s35, s35, 0
	s_add_u32 s72, s72, 0x100
	s_addc_u32 s73, s73, 0
	s_cmp_ge_i32 s74, s57
	s_mov_b32 s38, s74
	s_cbranch_scc0 .LBB0_727

; #define PG8_STAGE(bufoff, gbase, voff) do { _Pragma("unroll") for (int _i = 0; _i < 2; ++_i) \
;         __builtin_amdgcn_global_load_lds((const unsigned*)((const char*)(gbase) + (voff)[_i]), (LAS unsigned*)(lds + (bufoff) + ldsw + _i * 8192), 16, 0, 0); } while (0)
; #define PG8_LDA(dst, b, h) do { _Pragma("unroll") for (int m = 0; m < 4; ++m) _Pragma("unroll") for (int k = 0; k < 2; ++k) dst[m][k] = *(const LAS bf16x8*)(lds + PG8_SA(b, h) + aoff + m * 2048 + k * 1024); } while (0)
; #define PG8_LDB(dst, b, h) do { _Pragma("unroll") for (int n = 0; n < 2; ++n) _Pragma("unroll") for (int k = 0; k < 2; ++k) dst[n][k] = *(const LAS bf16x8*)(lds + PG8_SB(b, h) + boff + n * 2048 + k * 1024); } while (0)
; #define PG8_MMA(ai, bj, At, Bt) do { __builtin_amdgcn_s_setprio(1); _Pragma("unroll") for (int m = 0; m < 4; ++m) _Pragma("unroll") for (int n = 0; n < 2; ++n) _Pragma("unroll") for (int k = 0; k < 2; ++k) \
;         acc[ai][bj][m][n] = __builtin_amdgcn_mfma_f32_16x16x32_bf16(Bt[n][k], At[m][k], acc[ai][bj][m][n], 0, 0, 0); __builtin_amdgcn_s_setprio(0); } while (0)
; #define PG8_WAIT_V(n) asm volatile("s_waitcnt vmcnt(" #n ")" ::: "memory")
; #define PG8_WAIT_L(n) asm volatile("s_waitcnt lgkmcnt(" #n ")" ::: "memory")
; #define PG8_BAR __builtin_amdgcn_s_barrier()
; #define PG8_SCHED __builtin_amdgcn_sched_barrier(0)
; template <class Epi>
; DI void gemm_phase(LAS unsigned char* lds, const Gemm g, const StaticOrder& S, const Epi& E) {
;     ...
;             PG8_LDB(B0, 0, 0); PG8_LDB(B1, 0, 1); PG8_SCHED; PG8_LDA(At, 0, 0); PG8_STAGE(PG8_SA(1, 1), a1 + hstepA, voffA);
;             PG8_WAIT_V(8); PG8_WAIT_L(0); PG8_BAR; PG8_MMA(0, 0, At, B0); PG8_MMA(0, 1, At, B1); PG8_BAR; PG8_SCHED;
;             PG8_LDA(At, 0, 1); PG8_STAGE(PG8_SB(0, 0), b2, voffB); PG8_STAGE(PG8_SB(0, 1), b2 + hstepB, voffB); PG8_STAGE(PG8_SA(0, 0), a2, voffA);
;             PG8_WAIT_V(8); PG8_WAIT_L(0); PG8_BAR; PG8_MMA(1, 0, At, B0); PG8_MMA(1, 1, At, B1); PG8_BAR; PG8_SCHED;
.LBB0_813:
	ds_read_b128 v[144:147], v151
	ds_read_b128 v[156:159], v151 offset:1024
	ds_read_b128 v[160:163], v151 offset:2048
	ds_read_b128 v[164:167], v151 offset:3072
	ds_read_b128 v[168:171], v152
	ds_read_b128 v[172:175], v152 offset:1024
	ds_read_b128 v[176:179], v152 offset:2048
	ds_read_b128 v[182:185], v152 offset:3072
	s_add_i32 s63, s28, 2
	s_add_u32 s26, s24, 0x100
	s_addc_u32 s27, s25, 0
	s_cmp_eq_u32 s54, s28
	s_cselect_b32 s28, s22, s61
	s_cselect_b32 s31, s9, s27
	s_cselect_b32 s30, s8, s26
	s_cselect_b32 s29, s23, s62
	v_lshl_add_u64 v[218:219], s[24:25], 0, v[136:137]
	s_add_i32 m0, s40, 0xc000
	ds_read_b128 v[186:189], v153
	ds_read_b128 v[190:193], v153 offset:1024
	ds_read_b128 v[194:197], v153 offset:2048
	ds_read_b128 v[198:201], v153 offset:3072
	ds_read_b128 v[202:205], v153 offset:4096
	ds_read_b128 v[206:209], v153 offset:5120
	ds_read_b128 v[210:213], v153 offset:6144
	ds_read_b128 v[214:217], v153 offset:7168
	global_load_lds_dwordx4 v[218:219], off
	v_lshl_add_u64 v[218:219], s[24:25], 0, v[138:139]
	s_add_i32 m0, s40, 0xe000
	s_nop 0
	global_load_lds_dwordx4 v[218:219], off
	s_waitcnt vmcnt(8)
	s_waitcnt lgkmcnt(0)
	s_setprio 1
	s_barrier
	v_mfma_f32_16x16x32_bf16 v[124:127], v[144:147], v[186:189], v[124:127]
	v_mfma_f32_16x16x32_bf16 v[124:127], v[156:159], v[190:193], v[124:127]
	v_mfma_f32_16x16x32_bf16 v[108:111], v[144:147], v[194:197], v[108:111]
	v_mfma_f32_16x16x32_bf16 v[108:111], v[156:159], v[198:201], v[108:111]
	v_mfma_f32_16x16x32_bf16 v[92:95], v[144:147], v[202:205], v[92:95]
	v_mfma_f32_16x16x32_bf16 v[92:95], v[156:159], v[206:209], v[92:95]
	v_mfma_f32_16x16x32_bf16 v[76:79], v[144:147], v[210:213], v[76:79]
	v_mfma_f32_16x16x32_bf16 v[76:79], v[156:159], v[214:217], v[76:79]
	v_mfma_f32_16x16x32_bf16 v[72:75], v[160:163], v[210:213], v[72:75]
	v_mfma_f32_16x16x32_bf16 v[72:75], v[164:167], v[214:217], v[72:75]
	v_mfma_f32_16x16x32_bf16 v[88:91], v[160:163], v[202:205], v[88:91]
	v_mfma_f32_16x16x32_bf16 v[88:91], v[164:167], v[206:209], v[88:91]
	v_mfma_f32_16x16x32_bf16 v[104:107], v[160:163], v[194:197], v[104:107]
	v_mfma_f32_16x16x32_bf16 v[104:107], v[164:167], v[198:201], v[104:107]
	v_mfma_f32_16x16x32_bf16 v[120:123], v[160:163], v[186:189], v[120:123]
	v_mfma_f32_16x16x32_bf16 v[120:123], v[164:167], v[190:193], v[120:123]
	s_setprio 0
	s_setprio 1
	v_mfma_f32_16x16x32_bf16 v[116:119], v[168:171], v[186:189], v[116:119]
	v_mfma_f32_16x16x32_bf16 v[116:119], v[172:175], v[190:193], v[116:119]
	v_mfma_f32_16x16x32_bf16 v[100:103], v[168:171], v[194:197], v[100:103]
	v_mfma_f32_16x16x32_bf16 v[100:103], v[172:175], v[198:201], v[100:103]
	v_mfma_f32_16x16x32_bf16 v[84:87], v[168:171], v[202:205], v[84:87]
	v_mfma_f32_16x16x32_bf16 v[84:87], v[172:175], v[206:209], v[84:87]
	v_mfma_f32_16x16x32_bf16 v[68:71], v[168:171], v[210:213], v[68:71]
	v_mfma_f32_16x16x32_bf16 v[68:71], v[172:175], v[214:217], v[68:71]
	v_mfma_f32_16x16x32_bf16 v[64:67], v[176:179], v[210:213], v[64:67]
	v_mfma_f32_16x16x32_bf16 v[64:67], v[182:185], v[214:217], v[64:67]
	v_mfma_f32_16x16x32_bf16 v[80:83], v[176:179], v[202:205], v[80:83]
	v_mfma_f32_16x16x32_bf16 v[80:83], v[182:185], v[206:209], v[80:83]
	v_mfma_f32_16x16x32_bf16 v[96:99], v[176:179], v[194:197], v[96:99]
	v_mfma_f32_16x16x32_bf16 v[96:99], v[182:185], v[198:201], v[96:99]
	v_mfma_f32_16x16x32_bf16 v[112:115], v[176:179], v[186:189], v[112:115]
	v_mfma_f32_16x16x32_bf16 v[112:115], v[182:185], v[190:193], v[112:115]
	s_setprio 0
	s_barrier
	s_add_i32 s24, s55, s39
	v_lshl_add_u64 v[218:219], s[28:29], 0, v[130:131]
	s_mov_b32 m0, s24
	ds_read_b128 v[186:189], v153 offset:16384
	ds_read_b128 v[190:193], v153 offset:17408
	ds_read_b128 v[194:197], v153 offset:18432
	ds_read_b128 v[198:201], v153 offset:19456
	ds_read_b128 v[202:205], v153 offset:20480
	ds_read_b128 v[206:209], v153 offset:21504
	ds_read_b128 v[210:213], v153 offset:22528
	ds_read_b128 v[214:217], v153 offset:23552
	global_load_lds_dwordx4 v[218:219], off
	s_add_i32 m0, s24, 0x2000
	s_add_u32 s24, s28, 0x2b0000
	v_lshl_add_u64 v[220:221], s[28:29], 0, v[134:135]
	s_addc_u32 s25, s29, 0
	s_add_i32 s64, s56, s39
	global_load_lds_dwordx4 v[220:221], off
	v_lshl_add_u64 v[222:223], s[24:25], 0, v[130:131]
	s_mov_b32 m0, s64
	v_lshl_add_u64 v[224:225], s[30:31], 0, v[132:133]
	global_load_lds_dwordx4 v[222:223], off
	v_lshl_add_u64 v[222:223], s[24:25], 0, v[134:135]
	s_add_i32 m0, s64, 0x2000
	s_nop 0
	global_load_lds_dwordx4 v[222:223], off
	v_lshl_add_u64 v[222:223], s[30:31], 0, v[128:129]
	s_mov_b32 m0, s40
	s_nop 0
	global_load_lds_dwordx4 v[222:223], off
	s_mov_b32 m0, s41
	s_nop 0
	global_load_lds_dwordx4 v[224:225], off
	s_waitcnt vmcnt(8)
	s_waitcnt lgkmcnt(0)
	s_setprio 1
	s_barrier
; #define PG8_STAGE(bufoff, gbase, voff) do { _Pragma("unroll") for (int _i = 0; _i < 2; ++_i) \
;         __builtin_amdgcn_global_load_lds((const unsigned*)((const char*)(gbase) + (voff)[_i]), (LAS unsigned*)(lds + (bufoff) + ldsw + _i * 8192), 16, 0, 0); } while (0)
; #define PG8_LDA(dst, b, h) do { _Pragma("unroll") for (int m = 0; m < 4; ++m) _Pragma("unroll") for (int k = 0; k < 2; ++k) dst[m][k] = *(const LAS bf16x8*)(lds + PG8_SA(b, h) + aoff + m * 2048 + k * 1024); } while (0)
; #define PG8_LDB(dst, b, h) do { _Pragma("unroll") for (int n = 0; n < 2; ++n) _Pragma("unroll") for (int k = 0; k < 2; ++k) dst[n][k] = *(const LAS bf16x8*)(lds + PG8_SB(b, h) + boff + n * 2048 + k * 1024); } while (0)
; #define PG8_MMA(ai, bj, At, Bt) do { __builtin_amdgcn_s_setprio(1); _Pragma("unroll") for (int m = 0; m < 4; ++m) _Pragma("unroll") for (int n = 0; n < 2; ++n) _Pragma("unroll") for (int k = 0; k < 2; ++k) \
;         acc[ai][bj][m][n] = __builtin_amdgcn_mfma_f32_16x16x32_bf16(Bt[n][k], At[m][k], acc[ai][bj][m][n], 0, 0, 0); __builtin_amdgcn_s_setprio(0); } while (0)
; #define PG8_WAIT_V(n) asm volatile("s_waitcnt vmcnt(" #n ")" ::: "memory")
; #define PG8_WAIT_L(n) asm volatile("s_waitcnt lgkmcnt(" #n ")" ::: "memory")
; #define PG8_BAR __builtin_amdgcn_s_barrier()
; #define PG8_SCHED __builtin_amdgcn_sched_barrier(0)
; template <class Epi>
; DI void gemm_phase(LAS unsigned char* lds, const Gemm g, const StaticOrder& S, const Epi& E) {
;     ...
;             PG8_WAIT_V(8); PG8_WAIT_L(0); PG8_BAR; PG8_MMA(1, 0, At, B0); PG8_MMA(1, 1, At, B1); PG8_BAR; PG8_SCHED;
;             PG8_LDB(B0, 1, 0); PG8_LDB(B1, 1, 1); PG8_SCHED; PG8_LDA(At, 1, 0); PG8_STAGE(PG8_SA(0, 1), a2 + hstepA, voffA);
;             PG8_WAIT_V(8); PG8_WAIT_L(0); PG8_BAR; PG8_MMA(0, 0, At, B0); PG8_MMA(0, 1, At, B1); PG8_BAR; PG8_SCHED;
	v_mfma_f32_16x16x32_bf16 v[60:63], v[144:147], v[186:189], v[60:63]
	v_mfma_f32_16x16x32_bf16 v[60:63], v[156:159], v[190:193], v[60:63]
	v_mfma_f32_16x16x32_bf16 v[44:47], v[144:147], v[194:197], v[44:47]
	v_mfma_f32_16x16x32_bf16 v[44:47], v[156:159], v[198:201], v[44:47]
	v_mfma_f32_16x16x32_bf16 v[28:31], v[144:147], v[202:205], v[28:31]
	v_mfma_f32_16x16x32_bf16 v[28:31], v[156:159], v[206:209], v[28:31]
	v_mfma_f32_16x16x32_bf16 v[12:15], v[144:147], v[210:213], v[12:15]
	v_mfma_f32_16x16x32_bf16 v[12:15], v[156:159], v[214:217], v[12:15]
	v_mfma_f32_16x16x32_bf16 v[8:11], v[160:163], v[210:213], v[8:11]
	v_mfma_f32_16x16x32_bf16 v[8:11], v[164:167], v[214:217], v[8:11]
	v_mfma_f32_16x16x32_bf16 v[24:27], v[160:163], v[202:205], v[24:27]
	v_mfma_f32_16x16x32_bf16 v[24:27], v[164:167], v[206:209], v[24:27]
	v_mfma_f32_16x16x32_bf16 v[40:43], v[160:163], v[194:197], v[40:43]
	v_mfma_f32_16x16x32_bf16 v[40:43], v[164:167], v[198:201], v[40:43]
	v_mfma_f32_16x16x32_bf16 v[56:59], v[160:163], v[186:189], v[56:59]
	v_mfma_f32_16x16x32_bf16 v[56:59], v[164:167], v[190:193], v[56:59]
	s_setprio 0
	s_setprio 1
	v_mfma_f32_16x16x32_bf16 v[52:55], v[168:171], v[186:189], v[52:55]
	v_mfma_f32_16x16x32_bf16 v[52:55], v[172:175], v[190:193], v[52:55]
	v_mfma_f32_16x16x32_bf16 v[36:39], v[168:171], v[194:197], v[36:39]
	v_mfma_f32_16x16x32_bf16 v[36:39], v[172:175], v[198:201], v[36:39]
	v_mfma_f32_16x16x32_bf16 v[20:23], v[168:171], v[202:205], v[20:23]
	v_mfma_f32_16x16x32_bf16 v[20:23], v[172:175], v[206:209], v[20:23]
	v_mfma_f32_16x16x32_bf16 v[4:7], v[168:171], v[210:213], v[4:7]
	v_mfma_f32_16x16x32_bf16 v[4:7], v[172:175], v[214:217], v[4:7]
	v_mfma_f32_16x16x32_bf16 v[0:3], v[176:179], v[210:213], v[0:3]
	v_mfma_f32_16x16x32_bf16 v[0:3], v[182:185], v[214:217], v[0:3]
	v_mfma_f32_16x16x32_bf16 v[16:19], v[176:179], v[202:205], v[16:19]
	v_mfma_f32_16x16x32_bf16 v[16:19], v[182:185], v[206:209], v[16:19]
	v_mfma_f32_16x16x32_bf16 v[32:35], v[176:179], v[194:197], v[32:35]
	v_mfma_f32_16x16x32_bf16 v[32:35], v[182:185], v[198:201], v[32:35]
	v_mfma_f32_16x16x32_bf16 v[48:51], v[176:179], v[186:189], v[48:51]
	v_mfma_f32_16x16x32_bf16 v[48:51], v[182:185], v[190:193], v[48:51]
	s_setprio 0
	s_barrier
	s_add_i32 s64, 0, 0x18000
	v_add_u32_e32 v155, s64, v149
	s_add_i32 s65, 0, 0x1c000
	ds_read_b128 v[144:147], v155
	ds_read_b128 v[156:159], v155 offset:1024
	ds_read_b128 v[160:163], v155 offset:2048
	ds_read_b128 v[164:167], v155 offset:3072
	v_add_u32_e32 v155, s65, v149
	ds_read_b128 v[168:171], v155
	ds_read_b128 v[172:175], v155 offset:1024
	ds_read_b128 v[176:179], v155 offset:2048
	ds_read_b128 v[182:185], v155 offset:3072
	s_add_u32 s24, s30, 0x2b0000
	s_addc_u32 s25, s31, 0
	s_mov_b32 m0, s42
	v_lshl_add_u64 v[226:227], s[24:25], 0, v[128:129]
	ds_read_b128 v[186:189], v153 offset:32768
	ds_read_b128 v[190:193], v153 offset:33792
	ds_read_b128 v[194:197], v153 offset:34816
	ds_read_b128 v[198:201], v153 offset:35840
	ds_read_b128 v[202:205], v153 offset:36864
	ds_read_b128 v[206:209], v153 offset:37888
	ds_read_b128 v[210:213], v153 offset:38912
	ds_read_b128 v[214:217], v153 offset:39936
	global_load_lds_dwordx4 v[226:227], off
	v_lshl_add_u64 v[226:227], s[24:25], 0, v[132:133]
	s_mov_b32 m0, s43
	s_nop 0
	global_load_lds_dwordx4 v[226:227], off
	s_waitcnt vmcnt(8)
	s_waitcnt lgkmcnt(0)
	s_setprio 1
	s_barrier
	v_mfma_f32_16x16x32_bf16 v[124:127], v[144:147], v[186:189], v[124:127]
	v_mfma_f32_16x16x32_bf16 v[124:127], v[156:159], v[190:193], v[124:127]
	v_mfma_f32_16x16x32_bf16 v[108:111], v[144:147], v[194:197], v[108:111]
	v_mfma_f32_16x16x32_bf16 v[108:111], v[156:159], v[198:201], v[108:111]
	v_mfma_f32_16x16x32_bf16 v[92:95], v[144:147], v[202:205], v[92:95]
	v_mfma_f32_16x16x32_bf16 v[92:95], v[156:159], v[206:209], v[92:95]
	v_mfma_f32_16x16x32_bf16 v[76:79], v[144:147], v[210:213], v[76:79]
	v_mfma_f32_16x16x32_bf16 v[76:79], v[156:159], v[214:217], v[76:79]
	v_mfma_f32_16x16x32_bf16 v[72:75], v[160:163], v[210:213], v[72:75]
	v_mfma_f32_16x16x32_bf16 v[72:75], v[164:167], v[214:217], v[72:75]
	v_mfma_f32_16x16x32_bf16 v[88:91], v[160:163], v[202:205], v[88:91]
	v_mfma_f32_16x16x32_bf16 v[88:91], v[164:167], v[206:209], v[88:91]
	v_mfma_f32_16x16x32_bf16 v[104:107], v[160:163], v[194:197], v[104:107]
	v_mfma_f32_16x16x32_bf16 v[104:107], v[164:167], v[198:201], v[104:107]
	v_mfma_f32_16x16x32_bf16 v[120:123], v[160:163], v[186:189], v[120:123]
	v_mfma_f32_16x16x32_bf16 v[120:123], v[164:167], v[190:193], v[120:123]
	s_setprio 0
	s_setprio 1
	v_mfma_f32_16x16x32_bf16 v[116:119], v[168:171], v[186:189], v[116:119]
	v_mfma_f32_16x16x32_bf16 v[116:119], v[172:175], v[190:193], v[116:119]
	v_mfma_f32_16x16x32_bf16 v[100:103], v[168:171], v[194:197], v[100:103]
	v_mfma_f32_16x16x32_bf16 v[100:103], v[172:175], v[198:201], v[100:103]
	v_mfma_f32_16x16x32_bf16 v[84:87], v[168:171], v[202:205], v[84:87]
	v_mfma_f32_16x16x32_bf16 v[84:87], v[172:175], v[206:209], v[84:87]
	v_mfma_f32_16x16x32_bf16 v[68:71], v[168:171], v[210:213], v[68:71]
	v_mfma_f32_16x16x32_bf16 v[68:71], v[172:175], v[214:217], v[68:71]
	v_mfma_f32_16x16x32_bf16 v[64:67], v[176:179], v[210:213], v[64:67]
	v_mfma_f32_16x16x32_bf16 v[64:67], v[182:185], v[214:217], v[64:67]
	v_mfma_f32_16x16x32_bf16 v[80:83], v[176:179], v[202:205], v[80:83]
	v_mfma_f32_16x16x32_bf16 v[80:83], v[182:185], v[206:209], v[80:83]
	v_mfma_f32_16x16x32_bf16 v[96:99], v[176:179], v[194:197], v[96:99]
	v_mfma_f32_16x16x32_bf16 v[96:99], v[182:185], v[198:201], v[96:99]
	v_mfma_f32_16x16x32_bf16 v[112:115], v[176:179], v[186:189], v[112:115]
	v_mfma_f32_16x16x32_bf16 v[112:115], v[182:185], v[190:193], v[112:115]
	s_setprio 0
	s_barrier
; #define PG8_STAGE(bufoff, gbase, voff) do { _Pragma("unroll") for (int _i = 0; _i < 2; ++_i) \
;         __builtin_amdgcn_global_load_lds((const unsigned*)((const char*)(gbase) + (voff)[_i]), (LAS unsigned*)(lds + (bufoff) + ldsw + _i * 8192), 16, 0, 0); } while (0)
; #define PG8_LDA(dst, b, h) do { _Pragma("unroll") for (int m = 0; m < 4; ++m) _Pragma("unroll") for (int k = 0; k < 2; ++k) dst[m][k] = *(const LAS bf16x8*)(lds + PG8_SA(b, h) + aoff + m * 2048 + k * 1024); } while (0)
; #define PG8_MMA(ai, bj, At, Bt) do { __builtin_amdgcn_s_setprio(1); _Pragma("unroll") for (int m = 0; m < 4; ++m) _Pragma("unroll") for (int n = 0; n < 2; ++n) _Pragma("unroll") for (int k = 0; k < 2; ++k) \
;         acc[ai][bj][m][n] = __builtin_amdgcn_mfma_f32_16x16x32_bf16(Bt[n][k], At[m][k], acc[ai][bj][m][n], 0, 0, 0); __builtin_amdgcn_s_setprio(0); } while (0)
; #define PG8_WAIT_V(n) asm volatile("s_waitcnt vmcnt(" #n ")" ::: "memory")
; #define PG8_WAIT_L(n) asm volatile("s_waitcnt lgkmcnt(" #n ")" ::: "memory")
; #define PG8_BAR __builtin_amdgcn_s_barrier()
; #define PG8_SCHED __builtin_amdgcn_sched_barrier(0)
; template <class Epi>
; DI void gemm_phase(LAS unsigned char* lds, const Gemm g, const StaticOrder& S, const Epi& E) {
;     ...
;             PG8_LDA(At, 1, 1); PG8_STAGE(PG8_SB(1, 0), b3, voffB); PG8_STAGE(PG8_SB(1, 1), b3 + hstepB, voffB); PG8_STAGE(PG8_SA(1, 0), a3, voffA);
;             PG8_WAIT_V(8); PG8_WAIT_L(0); PG8_BAR; PG8_MMA(1, 0, At, B0); PG8_MMA(1, 1, At, B1); PG8_BAR; PG8_SCHED;
;         }
	s_add_i32 s24, s64, s39
	v_lshl_add_u64 v[218:219], v[218:219], 0, s[16:17]
	s_mov_b32 m0, s24
	ds_read_b128 v[186:189], v153 offset:49152
	ds_read_b128 v[190:193], v153 offset:50176
	ds_read_b128 v[194:197], v153 offset:51200
	ds_read_b128 v[198:201], v153 offset:52224
	ds_read_b128 v[202:205], v153 offset:53248
	ds_read_b128 v[206:209], v153 offset:54272
	ds_read_b128 v[210:213], v153 offset:55296
	ds_read_b128 v[214:217], v153 offset:56320
	global_load_lds_dwordx4 v[218:219], off
	s_add_i32 m0, s24, 0x2000
	s_add_u32 s24, s28, 0x2b0080
	v_lshl_add_u64 v[218:219], v[220:221], 0, s[16:17]
	s_addc_u32 s25, s29, 0
	s_add_i32 s28, s65, s39
	global_load_lds_dwordx4 v[218:219], off
	v_lshl_add_u64 v[218:219], s[24:25], 0, v[130:131]
	s_mov_b32 m0, s28
	s_nop 0
	global_load_lds_dwordx4 v[218:219], off
	v_lshl_add_u64 v[218:219], s[24:25], 0, v[134:135]
	s_add_i32 m0, s28, 0x2000
	s_nop 0
	global_load_lds_dwordx4 v[218:219], off
	v_lshl_add_u64 v[218:219], v[222:223], 0, s[16:17]
	s_mov_b32 m0, s52
	s_nop 0
	global_load_lds_dwordx4 v[218:219], off
	v_lshl_add_u64 v[218:219], v[224:225], 0, s[16:17]
	s_mov_b32 m0, s53
	s_nop 0
	global_load_lds_dwordx4 v[218:219], off
	s_waitcnt vmcnt(8)
	s_waitcnt lgkmcnt(0)
	s_setprio 1
	s_barrier
	v_mfma_f32_16x16x32_bf16 v[60:63], v[144:147], v[186:189], v[60:63]
	v_mfma_f32_16x16x32_bf16 v[60:63], v[156:159], v[190:193], v[60:63]
	v_mfma_f32_16x16x32_bf16 v[44:47], v[144:147], v[194:197], v[44:47]
	v_mfma_f32_16x16x32_bf16 v[44:47], v[156:159], v[198:201], v[44:47]
	v_mfma_f32_16x16x32_bf16 v[28:31], v[144:147], v[202:205], v[28:31]
	v_mfma_f32_16x16x32_bf16 v[28:31], v[156:159], v[206:209], v[28:31]
	v_mfma_f32_16x16x32_bf16 v[12:15], v[144:147], v[210:213], v[12:15]
	v_mfma_f32_16x16x32_bf16 v[12:15], v[156:159], v[214:217], v[12:15]
	v_mfma_f32_16x16x32_bf16 v[8:11], v[160:163], v[210:213], v[8:11]
	v_mfma_f32_16x16x32_bf16 v[8:11], v[164:167], v[214:217], v[8:11]
	v_mfma_f32_16x16x32_bf16 v[24:27], v[160:163], v[202:205], v[24:27]
	v_mfma_f32_16x16x32_bf16 v[24:27], v[164:167], v[206:209], v[24:27]
	v_mfma_f32_16x16x32_bf16 v[40:43], v[160:163], v[194:197], v[40:43]
	v_mfma_f32_16x16x32_bf16 v[40:43], v[164:167], v[198:201], v[40:43]
	v_mfma_f32_16x16x32_bf16 v[56:59], v[160:163], v[186:189], v[56:59]
	v_mfma_f32_16x16x32_bf16 v[56:59], v[164:167], v[190:193], v[56:59]
	s_setprio 0
	s_setprio 1
	v_mfma_f32_16x16x32_bf16 v[52:55], v[168:171], v[186:189], v[52:55]
	v_mfma_f32_16x16x32_bf16 v[52:55], v[172:175], v[190:193], v[52:55]
	v_mfma_f32_16x16x32_bf16 v[36:39], v[168:171], v[194:197], v[36:39]
	v_mfma_f32_16x16x32_bf16 v[36:39], v[172:175], v[198:201], v[36:39]
	v_mfma_f32_16x16x32_bf16 v[20:23], v[168:171], v[202:205], v[20:23]
	v_mfma_f32_16x16x32_bf16 v[20:23], v[172:175], v[206:209], v[20:23]
	v_mfma_f32_16x16x32_bf16 v[4:7], v[168:171], v[210:213], v[4:7]
	v_mfma_f32_16x16x32_bf16 v[4:7], v[172:175], v[214:217], v[4:7]
	v_mfma_f32_16x16x32_bf16 v[0:3], v[176:179], v[210:213], v[0:3]
	v_mfma_f32_16x16x32_bf16 v[0:3], v[182:185], v[214:217], v[0:3]
	v_mfma_f32_16x16x32_bf16 v[16:19], v[176:179], v[202:205], v[16:19]
	v_mfma_f32_16x16x32_bf16 v[16:19], v[182:185], v[206:209], v[16:19]
	v_mfma_f32_16x16x32_bf16 v[32:35], v[176:179], v[194:197], v[32:35]
	v_mfma_f32_16x16x32_bf16 v[32:35], v[182:185], v[198:201], v[32:35]
	v_mfma_f32_16x16x32_bf16 v[48:51], v[176:179], v[186:189], v[48:51]
	v_mfma_f32_16x16x32_bf16 v[48:51], v[182:185], v[190:193], v[48:51]
	s_setprio 0
	s_barrier
	s_add_u32 s61, s61, 0x100
	s_addc_u32 s62, s62, 0
	s_cmp_ge_i32 s63, s51
	s_mov_b64 s[24:25], s[26:27]
	s_mov_b32 s28, s63
	s_cbranch_scc0 .LBB0_813

; #define PG8_STAGE(bufoff, gbase, voff) do { _Pragma("unroll") for (int _i = 0; _i < 2; ++_i) \
;         __builtin_amdgcn_global_load_lds((const unsigned*)((const char*)(gbase) + (voff)[_i]), (LAS unsigned*)(lds + (bufoff) + ldsw + _i * 8192), 16, 0, 0); } while (0)
; #define PG8_LDA(dst, b, h) do { _Pragma("unroll") for (int m = 0; m < 4; ++m) _Pragma("unroll") for (int k = 0; k < 2; ++k) dst[m][k] = *(const LAS bf16x8*)(lds + PG8_SA(b, h) + aoff + m * 2048 + k * 1024); } while (0)
; #define PG8_LDB(dst, b, h) do { _Pragma("unroll") for (int n = 0; n < 2; ++n) _Pragma("unroll") for (int k = 0; k < 2; ++k) dst[n][k] = *(const LAS bf16x8*)(lds + PG8_SB(b, h) + boff + n * 2048 + k * 1024); } while (0)
; #define PG8_MMA(ai, bj, At, Bt) do { __builtin_amdgcn_s_setprio(1); _Pragma("unroll") for (int m = 0; m < 4; ++m) _Pragma("unroll") for (int n = 0; n < 2; ++n) _Pragma("unroll") for (int k = 0; k < 2; ++k) \
;         acc[ai][bj][m][n] = __builtin_amdgcn_mfma_f32_16x16x32_bf16(Bt[n][k], At[m][k], acc[ai][bj][m][n], 0, 0, 0); __builtin_amdgcn_s_setprio(0); } while (0)
; #define PG8_WAIT_V(n) asm volatile("s_waitcnt vmcnt(" #n ")" ::: "memory")
; #define PG8_WAIT_L(n) asm volatile("s_waitcnt lgkmcnt(" #n ")" ::: "memory")
; #define PG8_BAR __builtin_amdgcn_s_barrier()
; #define PG8_SCHED __builtin_amdgcn_sched_barrier(0)
; template <class Epi>
; DI void gemm_phase(LAS unsigned char* lds, const Gemm g, const StaticOrder& S, const Epi& E) {
;     ...
;             PG8_LDB(B0, 0, 0); PG8_LDB(B1, 0, 1); PG8_SCHED; PG8_LDA(At, 0, 0); PG8_STAGE(PG8_SA(1, 1), a1 + hstepA, voffA);
;             PG8_WAIT_V(8); PG8_WAIT_L(0); PG8_BAR; PG8_MMA(0, 0, At, B0); PG8_MMA(0, 1, At, B1); PG8_BAR; PG8_SCHED;
;             PG8_LDA(At, 0, 1); PG8_STAGE(PG8_SB(0, 0), b2, voffB); PG8_STAGE(PG8_SB(0, 1), b2 + hstepB, voffB); PG8_STAGE(PG8_SA(0, 0), a2, voffA);
;             PG8_WAIT_V(8); PG8_WAIT_L(0); PG8_BAR; PG8_MMA(1, 0, At, B0); PG8_MMA(1, 1, At, B1); PG8_BAR; PG8_SCHED;
.LBB0_972:
	ds_read_b128 v[128:131], v201
	ds_read_b128 v[132:135], v201 offset:1024
	ds_read_b128 v[136:139], v201 offset:2048
	ds_read_b128 v[140:143], v201 offset:3072
	ds_read_b128 v[144:147], v202
	ds_read_b128 v[148:151], v202 offset:1024
	ds_read_b128 v[152:155], v202 offset:2048
	ds_read_b128 v[156:159], v202 offset:3072
	s_add_i32 s55, s30, 2
	s_add_u32 s31, s28, 0xfff00080
	s_addc_u32 s34, s29, -1
	s_cmp_eq_u32 s46, s30
	s_cselect_b32 s30, s52, s53
	s_cselect_b32 s35, s19, s34
	s_cselect_b32 s34, s21, s31
	s_cselect_b32 s31, s51, s54
	v_lshl_add_u64 v[196:197], s[28:29], 0, v[180:181]
	s_add_i32 m0, s27, 0xc000
	ds_read_b128 v[160:163], v203
	ds_read_b128 v[164:167], v203 offset:1024
	ds_read_b128 v[168:171], v203 offset:2048
	ds_read_b128 v[188:191], v203 offset:3072
	ds_read_b128 v[192:195], v203 offset:4096
	ds_read_b128 v[204:207], v203 offset:5120
	ds_read_b128 v[208:211], v203 offset:6144
	ds_read_b128 v[212:215], v203 offset:7168
	global_load_lds_dwordx4 v[196:197], off
	v_lshl_add_u64 v[196:197], s[28:29], 0, v[182:183]
	s_add_i32 m0, s27, 0xe000
	s_nop 0
	global_load_lds_dwordx4 v[196:197], off
	s_waitcnt vmcnt(8)
	s_waitcnt lgkmcnt(0)
	s_setprio 1
	s_barrier
	v_mfma_f32_16x16x32_bf16 v[124:127], v[128:131], v[160:163], v[124:127]
	v_mfma_f32_16x16x32_bf16 v[124:127], v[132:135], v[164:167], v[124:127]
	v_mfma_f32_16x16x32_bf16 v[108:111], v[128:131], v[168:171], v[108:111]
	v_mfma_f32_16x16x32_bf16 v[108:111], v[132:135], v[188:191], v[108:111]
	v_mfma_f32_16x16x32_bf16 v[92:95], v[128:131], v[192:195], v[92:95]
	v_mfma_f32_16x16x32_bf16 v[92:95], v[132:135], v[204:207], v[92:95]
	v_mfma_f32_16x16x32_bf16 v[76:79], v[128:131], v[208:211], v[76:79]
	v_mfma_f32_16x16x32_bf16 v[76:79], v[132:135], v[212:215], v[76:79]
	v_mfma_f32_16x16x32_bf16 v[72:75], v[136:139], v[208:211], v[72:75]
	v_mfma_f32_16x16x32_bf16 v[72:75], v[140:143], v[212:215], v[72:75]
	v_mfma_f32_16x16x32_bf16 v[88:91], v[136:139], v[192:195], v[88:91]
	v_mfma_f32_16x16x32_bf16 v[88:91], v[140:143], v[204:207], v[88:91]
	v_mfma_f32_16x16x32_bf16 v[104:107], v[136:139], v[168:171], v[104:107]
	v_mfma_f32_16x16x32_bf16 v[104:107], v[140:143], v[188:191], v[104:107]
	v_mfma_f32_16x16x32_bf16 v[120:123], v[136:139], v[160:163], v[120:123]
	v_mfma_f32_16x16x32_bf16 v[120:123], v[140:143], v[164:167], v[120:123]
	s_setprio 0
	s_setprio 1
	v_mfma_f32_16x16x32_bf16 v[116:119], v[144:147], v[160:163], v[116:119]
	v_mfma_f32_16x16x32_bf16 v[116:119], v[148:151], v[164:167], v[116:119]
	v_mfma_f32_16x16x32_bf16 v[100:103], v[144:147], v[168:171], v[100:103]
	v_mfma_f32_16x16x32_bf16 v[100:103], v[148:151], v[188:191], v[100:103]
	v_mfma_f32_16x16x32_bf16 v[84:87], v[144:147], v[192:195], v[84:87]
	v_mfma_f32_16x16x32_bf16 v[84:87], v[148:151], v[204:207], v[84:87]
	v_mfma_f32_16x16x32_bf16 v[68:71], v[144:147], v[208:211], v[68:71]
	v_mfma_f32_16x16x32_bf16 v[68:71], v[148:151], v[212:215], v[68:71]
	v_mfma_f32_16x16x32_bf16 v[64:67], v[152:155], v[208:211], v[64:67]
	v_mfma_f32_16x16x32_bf16 v[64:67], v[156:159], v[212:215], v[64:67]
	v_mfma_f32_16x16x32_bf16 v[80:83], v[152:155], v[192:195], v[80:83]
	v_mfma_f32_16x16x32_bf16 v[80:83], v[156:159], v[204:207], v[80:83]
	v_mfma_f32_16x16x32_bf16 v[96:99], v[152:155], v[168:171], v[96:99]
	v_mfma_f32_16x16x32_bf16 v[96:99], v[156:159], v[188:191], v[96:99]
	v_mfma_f32_16x16x32_bf16 v[112:115], v[152:155], v[160:163], v[112:115]
	v_mfma_f32_16x16x32_bf16 v[112:115], v[156:159], v[164:167], v[112:115]
	s_setprio 0
	s_barrier
	s_add_i32 s56, s48, s38
	v_lshl_add_u64 v[196:197], s[30:31], 0, v[174:175]
	s_mov_b32 m0, s56
	ds_read_b128 v[160:163], v203 offset:16384
	ds_read_b128 v[164:167], v203 offset:17408
	ds_read_b128 v[168:171], v203 offset:18432
	ds_read_b128 v[188:191], v203 offset:19456
	ds_read_b128 v[192:195], v203 offset:20480
	ds_read_b128 v[204:207], v203 offset:21504
	ds_read_b128 v[208:211], v203 offset:22528
	ds_read_b128 v[212:215], v203 offset:23552
	global_load_lds_dwordx4 v[196:197], off
	s_add_i32 m0, s56, 0x2000
	s_add_u32 s56, s30, 0x100000
	v_lshl_add_u64 v[216:217], s[30:31], 0, v[178:179]
	s_addc_u32 s57, s31, 0
	s_add_i32 s58, s49, s38
	global_load_lds_dwordx4 v[216:217], off
	v_lshl_add_u64 v[218:219], s[56:57], 0, v[174:175]
	s_mov_b32 m0, s58
	v_lshl_add_u64 v[220:221], s[34:35], 0, v[176:177]
	global_load_lds_dwordx4 v[218:219], off
	v_lshl_add_u64 v[218:219], s[56:57], 0, v[178:179]
	s_add_i32 m0, s58, 0x2000
	s_nop 0
	global_load_lds_dwordx4 v[218:219], off
	v_lshl_add_u64 v[218:219], s[34:35], 0, v[172:173]
	s_mov_b32 m0, s27
	s_nop 0
	global_load_lds_dwordx4 v[218:219], off
	s_mov_b32 m0, s39
	s_nop 0
	global_load_lds_dwordx4 v[220:221], off
	s_waitcnt vmcnt(8)
	s_waitcnt lgkmcnt(0)
	s_setprio 1
	s_barrier
; #define PG8_STAGE(bufoff, gbase, voff) do { _Pragma("unroll") for (int _i = 0; _i < 2; ++_i) \
;         __builtin_amdgcn_global_load_lds((const unsigned*)((const char*)(gbase) + (voff)[_i]), (LAS unsigned*)(lds + (bufoff) + ldsw + _i * 8192), 16, 0, 0); } while (0)
; #define PG8_LDA(dst, b, h) do { _Pragma("unroll") for (int m = 0; m < 4; ++m) _Pragma("unroll") for (int k = 0; k < 2; ++k) dst[m][k] = *(const LAS bf16x8*)(lds + PG8_SA(b, h) + aoff + m * 2048 + k * 1024); } while (0)
; #define PG8_LDB(dst, b, h) do { _Pragma("unroll") for (int n = 0; n < 2; ++n) _Pragma("unroll") for (int k = 0; k < 2; ++k) dst[n][k] = *(const LAS bf16x8*)(lds + PG8_SB(b, h) + boff + n * 2048 + k * 1024); } while (0)
; #define PG8_MMA(ai, bj, At, Bt) do { __builtin_amdgcn_s_setprio(1); _Pragma("unroll") for (int m = 0; m < 4; ++m) _Pragma("unroll") for (int n = 0; n < 2; ++n) _Pragma("unroll") for (int k = 0; k < 2; ++k) \
;         acc[ai][bj][m][n] = __builtin_amdgcn_mfma_f32_16x16x32_bf16(Bt[n][k], At[m][k], acc[ai][bj][m][n], 0, 0, 0); __builtin_amdgcn_s_setprio(0); } while (0)
; #define PG8_WAIT_V(n) asm volatile("s_waitcnt vmcnt(" #n ")" ::: "memory")
; #define PG8_WAIT_L(n) asm volatile("s_waitcnt lgkmcnt(" #n ")" ::: "memory")
; #define PG8_BAR __builtin_amdgcn_s_barrier()
; #define PG8_SCHED __builtin_amdgcn_sched_barrier(0)
; template <class Epi>
; DI void gemm_phase(LAS unsigned char* lds, const Gemm g, const StaticOrder& S, const Epi& E) {
;     ...
;             PG8_WAIT_V(8); PG8_WAIT_L(0); PG8_BAR; PG8_MMA(1, 0, At, B0); PG8_MMA(1, 1, At, B1); PG8_BAR; PG8_SCHED;
;             PG8_LDB(B0, 1, 0); PG8_LDB(B1, 1, 1); PG8_SCHED; PG8_LDA(At, 1, 0); PG8_STAGE(PG8_SA(0, 1), a2 + hstepA, voffA);
;             PG8_WAIT_V(8); PG8_WAIT_L(0); PG8_BAR; PG8_MMA(0, 0, At, B0); PG8_MMA(0, 1, At, B1); PG8_BAR; PG8_SCHED;
	v_mfma_f32_16x16x32_bf16 v[60:63], v[128:131], v[160:163], v[60:63]
	v_mfma_f32_16x16x32_bf16 v[60:63], v[132:135], v[164:167], v[60:63]
	v_mfma_f32_16x16x32_bf16 v[44:47], v[128:131], v[168:171], v[44:47]
	v_mfma_f32_16x16x32_bf16 v[44:47], v[132:135], v[188:191], v[44:47]
	v_mfma_f32_16x16x32_bf16 v[28:31], v[128:131], v[192:195], v[28:31]
	v_mfma_f32_16x16x32_bf16 v[28:31], v[132:135], v[204:207], v[28:31]
	v_mfma_f32_16x16x32_bf16 v[12:15], v[128:131], v[208:211], v[12:15]
	v_mfma_f32_16x16x32_bf16 v[12:15], v[132:135], v[212:215], v[12:15]
	v_mfma_f32_16x16x32_bf16 v[8:11], v[136:139], v[208:211], v[8:11]
	v_mfma_f32_16x16x32_bf16 v[8:11], v[140:143], v[212:215], v[8:11]
	v_mfma_f32_16x16x32_bf16 v[24:27], v[136:139], v[192:195], v[24:27]
	v_mfma_f32_16x16x32_bf16 v[24:27], v[140:143], v[204:207], v[24:27]
	v_mfma_f32_16x16x32_bf16 v[40:43], v[136:139], v[168:171], v[40:43]
	v_mfma_f32_16x16x32_bf16 v[40:43], v[140:143], v[188:191], v[40:43]
	v_mfma_f32_16x16x32_bf16 v[56:59], v[136:139], v[160:163], v[56:59]
	v_mfma_f32_16x16x32_bf16 v[56:59], v[140:143], v[164:167], v[56:59]
	s_setprio 0
	s_setprio 1
	v_mfma_f32_16x16x32_bf16 v[52:55], v[144:147], v[160:163], v[52:55]
	v_mfma_f32_16x16x32_bf16 v[52:55], v[148:151], v[164:167], v[52:55]
	v_mfma_f32_16x16x32_bf16 v[36:39], v[144:147], v[168:171], v[36:39]
	v_mfma_f32_16x16x32_bf16 v[36:39], v[148:151], v[188:191], v[36:39]
	v_mfma_f32_16x16x32_bf16 v[20:23], v[144:147], v[192:195], v[20:23]
	v_mfma_f32_16x16x32_bf16 v[20:23], v[148:151], v[204:207], v[20:23]
	v_mfma_f32_16x16x32_bf16 v[4:7], v[144:147], v[208:211], v[4:7]
	v_mfma_f32_16x16x32_bf16 v[4:7], v[148:151], v[212:215], v[4:7]
	v_mfma_f32_16x16x32_bf16 v[0:3], v[152:155], v[208:211], v[0:3]
	v_mfma_f32_16x16x32_bf16 v[0:3], v[156:159], v[212:215], v[0:3]
	v_mfma_f32_16x16x32_bf16 v[16:19], v[152:155], v[192:195], v[16:19]
	v_mfma_f32_16x16x32_bf16 v[16:19], v[156:159], v[204:207], v[16:19]
	v_mfma_f32_16x16x32_bf16 v[32:35], v[152:155], v[168:171], v[32:35]
	v_mfma_f32_16x16x32_bf16 v[32:35], v[156:159], v[188:191], v[32:35]
	v_mfma_f32_16x16x32_bf16 v[48:51], v[152:155], v[160:163], v[48:51]
	v_mfma_f32_16x16x32_bf16 v[48:51], v[156:159], v[164:167], v[48:51]
	s_setprio 0
	s_barrier
	s_add_i32 s56, 0, 0x18000
	s_add_i32 s57, 0, 0x1c000
	v_add_u32_e32 v140, s56, v199
	v_add_u32_e32 v156, s57, v199
	ds_read_b128 v[128:131], v140
	ds_read_b128 v[132:135], v140 offset:1024
	ds_read_b128 v[136:139], v140 offset:2048
	ds_read_b128 v[140:143], v140 offset:3072
	ds_read_b128 v[144:147], v156
	ds_read_b128 v[148:151], v156 offset:1024
	ds_read_b128 v[152:155], v156 offset:2048
	ds_read_b128 v[156:159], v156 offset:3072
	s_add_u32 s34, s34, 0x100000
	s_addc_u32 s35, s35, 0
	s_mov_b32 m0, s40
	v_lshl_add_u64 v[222:223], s[34:35], 0, v[172:173]
	ds_read_b128 v[160:163], v203 offset:32768
	ds_read_b128 v[164:167], v203 offset:33792
	ds_read_b128 v[168:171], v203 offset:34816
	ds_read_b128 v[188:191], v203 offset:35840
	ds_read_b128 v[192:195], v203 offset:36864
	ds_read_b128 v[204:207], v203 offset:37888
	ds_read_b128 v[208:211], v203 offset:38912
	ds_read_b128 v[212:215], v203 offset:39936
	global_load_lds_dwordx4 v[222:223], off
	v_lshl_add_u64 v[222:223], s[34:35], 0, v[176:177]
	s_mov_b32 m0, s41
	s_nop 0
	global_load_lds_dwordx4 v[222:223], off
	s_waitcnt vmcnt(8)
	s_waitcnt lgkmcnt(0)
	s_setprio 1
	s_barrier
	v_mfma_f32_16x16x32_bf16 v[124:127], v[128:131], v[160:163], v[124:127]
	v_mfma_f32_16x16x32_bf16 v[124:127], v[132:135], v[164:167], v[124:127]
	v_mfma_f32_16x16x32_bf16 v[108:111], v[128:131], v[168:171], v[108:111]
	v_mfma_f32_16x16x32_bf16 v[108:111], v[132:135], v[188:191], v[108:111]
	v_mfma_f32_16x16x32_bf16 v[92:95], v[128:131], v[192:195], v[92:95]
	v_mfma_f32_16x16x32_bf16 v[92:95], v[132:135], v[204:207], v[92:95]
	v_mfma_f32_16x16x32_bf16 v[76:79], v[128:131], v[208:211], v[76:79]
	v_mfma_f32_16x16x32_bf16 v[76:79], v[132:135], v[212:215], v[76:79]
	v_mfma_f32_16x16x32_bf16 v[72:75], v[136:139], v[208:211], v[72:75]
	v_mfma_f32_16x16x32_bf16 v[72:75], v[140:143], v[212:215], v[72:75]
	v_mfma_f32_16x16x32_bf16 v[88:91], v[136:139], v[192:195], v[88:91]
	v_mfma_f32_16x16x32_bf16 v[88:91], v[140:143], v[204:207], v[88:91]
	v_mfma_f32_16x16x32_bf16 v[104:107], v[136:139], v[168:171], v[104:107]
	v_mfma_f32_16x16x32_bf16 v[104:107], v[140:143], v[188:191], v[104:107]
	v_mfma_f32_16x16x32_bf16 v[120:123], v[136:139], v[160:163], v[120:123]
	v_mfma_f32_16x16x32_bf16 v[120:123], v[140:143], v[164:167], v[120:123]
	s_setprio 0
	s_setprio 1
	v_mfma_f32_16x16x32_bf16 v[116:119], v[144:147], v[160:163], v[116:119]
	v_mfma_f32_16x16x32_bf16 v[116:119], v[148:151], v[164:167], v[116:119]
	v_mfma_f32_16x16x32_bf16 v[100:103], v[144:147], v[168:171], v[100:103]
	v_mfma_f32_16x16x32_bf16 v[100:103], v[148:151], v[188:191], v[100:103]
	v_mfma_f32_16x16x32_bf16 v[84:87], v[144:147], v[192:195], v[84:87]
	v_mfma_f32_16x16x32_bf16 v[84:87], v[148:151], v[204:207], v[84:87]
	v_mfma_f32_16x16x32_bf16 v[68:71], v[144:147], v[208:211], v[68:71]
	v_mfma_f32_16x16x32_bf16 v[68:71], v[148:151], v[212:215], v[68:71]
	v_mfma_f32_16x16x32_bf16 v[64:67], v[152:155], v[208:211], v[64:67]
	v_mfma_f32_16x16x32_bf16 v[64:67], v[156:159], v[212:215], v[64:67]
	v_mfma_f32_16x16x32_bf16 v[80:83], v[152:155], v[192:195], v[80:83]
	v_mfma_f32_16x16x32_bf16 v[80:83], v[156:159], v[204:207], v[80:83]
	v_mfma_f32_16x16x32_bf16 v[96:99], v[152:155], v[168:171], v[96:99]
	v_mfma_f32_16x16x32_bf16 v[96:99], v[156:159], v[188:191], v[96:99]
	v_mfma_f32_16x16x32_bf16 v[112:115], v[152:155], v[160:163], v[112:115]
	v_mfma_f32_16x16x32_bf16 v[112:115], v[156:159], v[164:167], v[112:115]
	s_setprio 0
	s_barrier
; #define PG8_STAGE(bufoff, gbase, voff) do { _Pragma("unroll") for (int _i = 0; _i < 2; ++_i) \
;         __builtin_amdgcn_global_load_lds((const unsigned*)((const char*)(gbase) + (voff)[_i]), (LAS unsigned*)(lds + (bufoff) + ldsw + _i * 8192), 16, 0, 0); } while (0)
; #define PG8_LDA(dst, b, h) do { _Pragma("unroll") for (int m = 0; m < 4; ++m) _Pragma("unroll") for (int k = 0; k < 2; ++k) dst[m][k] = *(const LAS bf16x8*)(lds + PG8_SA(b, h) + aoff + m * 2048 + k * 1024); } while (0)
; #define PG8_MMA(ai, bj, At, Bt) do { __builtin_amdgcn_s_setprio(1); _Pragma("unroll") for (int m = 0; m < 4; ++m) _Pragma("unroll") for (int n = 0; n < 2; ++n) _Pragma("unroll") for (int k = 0; k < 2; ++k) \
;         acc[ai][bj][m][n] = __builtin_amdgcn_mfma_f32_16x16x32_bf16(Bt[n][k], At[m][k], acc[ai][bj][m][n], 0, 0, 0); __builtin_amdgcn_s_setprio(0); } while (0)
; #define PG8_WAIT_V(n) asm volatile("s_waitcnt vmcnt(" #n ")" ::: "memory")
; #define PG8_WAIT_L(n) asm volatile("s_waitcnt lgkmcnt(" #n ")" ::: "memory")
; #define PG8_BAR __builtin_amdgcn_s_barrier()
; #define PG8_SCHED __builtin_amdgcn_sched_barrier(0)
; template <class Epi>
; DI void gemm_phase(LAS unsigned char* lds, const Gemm g, const StaticOrder& S, const Epi& E) {
;     ...
;             PG8_LDA(At, 1, 1); PG8_STAGE(PG8_SB(1, 0), b3, voffB); PG8_STAGE(PG8_SB(1, 1), b3 + hstepB, voffB); PG8_STAGE(PG8_SA(1, 0), a3, voffA);
;             PG8_WAIT_V(8); PG8_WAIT_L(0); PG8_BAR; PG8_MMA(1, 0, At, B0); PG8_MMA(1, 1, At, B1); PG8_BAR; PG8_SCHED;
;         }
	s_add_i32 s34, s56, s38
	v_lshl_add_u64 v[196:197], v[196:197], 0, s[12:13]
	s_mov_b32 m0, s34
	ds_read_b128 v[160:163], v203 offset:49152
	ds_read_b128 v[164:167], v203 offset:50176
	ds_read_b128 v[168:171], v203 offset:51200
	ds_read_b128 v[188:191], v203 offset:52224
	ds_read_b128 v[192:195], v203 offset:53248
	ds_read_b128 v[204:207], v203 offset:54272
	ds_read_b128 v[208:211], v203 offset:55296
	ds_read_b128 v[212:215], v203 offset:56320
	global_load_lds_dwordx4 v[196:197], off
	s_add_i32 m0, s34, 0x2000
	s_add_u32 s30, s30, 0x100080
	v_lshl_add_u64 v[196:197], v[216:217], 0, s[12:13]
	s_addc_u32 s31, s31, 0
	s_add_i32 s34, s57, s38
	global_load_lds_dwordx4 v[196:197], off
	v_lshl_add_u64 v[196:197], s[30:31], 0, v[174:175]
	s_mov_b32 m0, s34
	s_nop 0
	global_load_lds_dwordx4 v[196:197], off
	v_lshl_add_u64 v[196:197], s[30:31], 0, v[178:179]
	s_add_i32 m0, s34, 0x2000
	s_nop 0
	global_load_lds_dwordx4 v[196:197], off
	v_lshl_add_u64 v[196:197], v[218:219], 0, s[12:13]
	s_mov_b32 m0, s44
	s_nop 0
	global_load_lds_dwordx4 v[196:197], off
	v_lshl_add_u64 v[196:197], v[220:221], 0, s[12:13]
	s_mov_b32 m0, s45
	s_nop 0
	global_load_lds_dwordx4 v[196:197], off
	s_waitcnt vmcnt(8)
	s_waitcnt lgkmcnt(0)
	s_setprio 1
	s_barrier
	v_mfma_f32_16x16x32_bf16 v[60:63], v[128:131], v[160:163], v[60:63]
	v_mfma_f32_16x16x32_bf16 v[60:63], v[132:135], v[164:167], v[60:63]
	v_mfma_f32_16x16x32_bf16 v[44:47], v[128:131], v[168:171], v[44:47]
	v_mfma_f32_16x16x32_bf16 v[44:47], v[132:135], v[188:191], v[44:47]
	v_mfma_f32_16x16x32_bf16 v[28:31], v[128:131], v[192:195], v[28:31]
	v_mfma_f32_16x16x32_bf16 v[28:31], v[132:135], v[204:207], v[28:31]
	v_mfma_f32_16x16x32_bf16 v[12:15], v[128:131], v[208:211], v[12:15]
	v_mfma_f32_16x16x32_bf16 v[12:15], v[132:135], v[212:215], v[12:15]
	v_mfma_f32_16x16x32_bf16 v[8:11], v[136:139], v[208:211], v[8:11]
	v_mfma_f32_16x16x32_bf16 v[8:11], v[140:143], v[212:215], v[8:11]
	v_mfma_f32_16x16x32_bf16 v[24:27], v[136:139], v[192:195], v[24:27]
	v_mfma_f32_16x16x32_bf16 v[24:27], v[140:143], v[204:207], v[24:27]
	v_mfma_f32_16x16x32_bf16 v[40:43], v[136:139], v[168:171], v[40:43]
	v_mfma_f32_16x16x32_bf16 v[40:43], v[140:143], v[188:191], v[40:43]
	v_mfma_f32_16x16x32_bf16 v[56:59], v[136:139], v[160:163], v[56:59]
	v_mfma_f32_16x16x32_bf16 v[56:59], v[140:143], v[164:167], v[56:59]
	s_setprio 0
	s_setprio 1
	v_mfma_f32_16x16x32_bf16 v[52:55], v[144:147], v[160:163], v[52:55]
	v_mfma_f32_16x16x32_bf16 v[52:55], v[148:151], v[164:167], v[52:55]
	v_mfma_f32_16x16x32_bf16 v[36:39], v[144:147], v[168:171], v[36:39]
	v_mfma_f32_16x16x32_bf16 v[36:39], v[148:151], v[188:191], v[36:39]
	v_mfma_f32_16x16x32_bf16 v[20:23], v[144:147], v[192:195], v[20:23]
	v_mfma_f32_16x16x32_bf16 v[20:23], v[148:151], v[204:207], v[20:23]
	v_mfma_f32_16x16x32_bf16 v[4:7], v[144:147], v[208:211], v[4:7]
	v_mfma_f32_16x16x32_bf16 v[4:7], v[148:151], v[212:215], v[4:7]
	v_mfma_f32_16x16x32_bf16 v[0:3], v[152:155], v[208:211], v[0:3]
	v_mfma_f32_16x16x32_bf16 v[0:3], v[156:159], v[212:215], v[0:3]
	v_mfma_f32_16x16x32_bf16 v[16:19], v[152:155], v[192:195], v[16:19]
	v_mfma_f32_16x16x32_bf16 v[16:19], v[156:159], v[204:207], v[16:19]
	v_mfma_f32_16x16x32_bf16 v[32:35], v[152:155], v[168:171], v[32:35]
	v_mfma_f32_16x16x32_bf16 v[32:35], v[156:159], v[188:191], v[32:35]
	v_mfma_f32_16x16x32_bf16 v[48:51], v[152:155], v[160:163], v[48:51]
	v_mfma_f32_16x16x32_bf16 v[48:51], v[156:159], v[164:167], v[48:51]
	s_setprio 0
	s_barrier
	s_add_u32 s28, s28, 0x100
	s_addc_u32 s29, s29, 0
	s_add_u32 s53, s53, 0x100
	s_addc_u32 s54, s54, 0
	s_cmp_ge_i32 s55, s43
	s_mov_b32 s30, s55
	s_cbranch_scc0 .LBB0_972
